# A/B: deleted hipcc per-phase s_setprio 1/0 flips in the 14 eight-phase GEMM K loops, on top of v48
# speedup vs baseline: 1.0024x; 1.0024x over previous
; #define PG8_STAGE(bufoff, gbase, voff) do { _Pragma("unroll") for (int _i = 0; _i < 2; ++_i) \
;         __builtin_amdgcn_global_load_lds((const unsigned*)((const char*)(gbase) + (voff)[_i]), (LAS unsigned*)(lds + (bufoff) + ldsw + _i * 8192), 16, 0, 0); } while (0)
; #define PG8_LDA(dst, b, h) do { _Pragma("unroll") for (int m = 0; m < 4; ++m) _Pragma("unroll") for (int k = 0; k < 2; ++k) dst[m][k] = *(const LAS bf16x8*)(lds + PG8_SA(b, h) + aoff + m * 2048 + k * 1024); } while (0)
; #define PG8_LDB(dst, b, h) do { _Pragma("unroll") for (int n = 0; n < 2; ++n) _Pragma("unroll") for (int k = 0; k < 2; ++k) dst[n][k] = *(const LAS bf16x8*)(lds + PG8_SB(b, h) + boff + n * 2048 + k * 1024); } while (0)
; #define PG8_MMA(ai, bj, At, Bt) do { __builtin_amdgcn_s_setprio(1); _Pragma("unroll") for (int m = 0; m < 4; ++m) _Pragma("unroll") for (int n = 0; n < 2; ++n) _Pragma("unroll") for (int k = 0; k < 2; ++k) \
;         acc[ai][bj][m][n] = __builtin_amdgcn_mfma_f32_16x16x32_bf16(Bt[n][k], At[m][k], acc[ai][bj][m][n], 0, 0, 0); __builtin_amdgcn_s_setprio(0); } while (0)
; #define PG8_WAIT_V(n) asm volatile("s_waitcnt vmcnt(" #n ")" ::: "memory")
; #define PG8_WAIT_L(n) asm volatile("s_waitcnt lgkmcnt(" #n ")" ::: "memory")
; #define PG8_BAR __builtin_amdgcn_s_barrier()
; #define PG8_SCHED __builtin_amdgcn_sched_barrier(0)
; template <class Epi>
; DI void gemm_phase(int wv, LAS unsigned char* lds, LAS unsigned char* scr, const Sched& S, const Epi& E) {
;     ...
;         for (int t = 0; t < nt; t += 2) {
;             const bool last = (t == nt - 2);
;             const char* a1 = cA + (size_t)(t + 1) * kstep;
;             const char* a2 = last ? nA : cA + (size_t)(t + 2) * kstep; const char* b2 = last ? nB : cB + (size_t)(t + 2) * kstep;
;             const char* a3 = a2 + kstep; const char* b3 = b2 + kstep;
;             PG8_LDB(B0, 0, 0); PG8_LDB(B1, 0, 1); PG8_SCHED; PG8_LDA(At, 0, 0); PG8_STAGE(PG8_SA(1, 1), a1 + hstepA, voffA);
;             PG8_WAIT_V(8); PG8_WAIT_L(0); PG8_BAR; PG8_MMA(0, 0, At, B0); PG8_MMA(0, 1, At, B1); PG8_BAR; PG8_SCHED;
;             PG8_LDA(At, 0, 1); PG8_STAGE(PG8_SB(0, 0), b2, voffB); PG8_STAGE(PG8_SB(0, 1), b2 + hstepB, voffB); PG8_STAGE(PG8_SA(0, 0), a2, voffA);
;             PG8_WAIT_V(8); PG8_WAIT_L(0); PG8_BAR; PG8_MMA(1, 0, At, B0); PG8_MMA(1, 1, At, B1); PG8_BAR; PG8_SCHED;
.LBB0_43:
	s_add_u32 s22, s20, 0xfffc0080
	s_addc_u32 s23, s21, -1
	s_add_i32 s56, 0, 0x10000
	s_cmp_eq_u32 s53, 12
	s_cselect_b32 s25, s7, s23
	s_cselect_b32 s24, s9, s22
	s_cselect_b32 s23, s13, s52
	s_cselect_b32 s22, s15, s49
	s_add_i32 s58, 0, 0x14000
	v_add_u32_e32 v156, s56, v142
	v_add_u32_e32 v172, s58, v142
	ds_read_b128 v[144:147], v156
	ds_read_b128 v[148:151], v156 offset:1024
	ds_read_b128 v[152:155], v156 offset:2048
	ds_read_b128 v[156:159], v156 offset:3072
	ds_read_b128 v[160:163], v172
	ds_read_b128 v[164:167], v172 offset:1024
	ds_read_b128 v[168:171], v172 offset:2048
	ds_read_b128 v[172:175], v172 offset:3072
	v_lshl_add_u64 v[210:211], s[20:21], 0, v[140:141]
	s_add_i32 m0, s38, 0xc000
	ds_read_b128 v[176:179], v143
	ds_read_b128 v[180:183], v143 offset:1024
	ds_read_b128 v[184:187], v143 offset:2048
	ds_read_b128 v[188:191], v143 offset:3072
	ds_read_b128 v[194:197], v143 offset:4096
	ds_read_b128 v[198:201], v143 offset:5120
	ds_read_b128 v[202:205], v143 offset:6144
	ds_read_b128 v[206:209], v143 offset:7168
	global_load_lds_dwordx4 v[210:211], off
	v_lshl_add_u64 v[210:211], s[20:21], 0, v[138:139]
	s_add_i32 m0, s38, 0xe000
	s_nop 0
	global_load_lds_dwordx4 v[210:211], off
	s_waitcnt vmcnt(8)
	s_waitcnt lgkmcnt(0)
	s_barrier
	s_waitcnt lgkmcnt(0)
	v_mfma_f32_16x16x32_bf16 v[124:127], v[144:147], v[176:179], v[124:127]
	v_mfma_f32_16x16x32_bf16 v[120:123], v[152:155], v[176:179], v[120:123]
	v_mfma_f32_16x16x32_bf16 v[116:119], v[144:147], v[184:187], v[116:119]
	v_mfma_f32_16x16x32_bf16 v[112:115], v[152:155], v[184:187], v[112:115]
	v_mfma_f32_16x16x32_bf16 v[100:103], v[144:147], v[194:197], v[100:103]
	v_mfma_f32_16x16x32_bf16 v[96:99], v[152:155], v[194:197], v[96:99]
	v_mfma_f32_16x16x32_bf16 v[84:87], v[144:147], v[202:205], v[84:87]
	v_mfma_f32_16x16x32_bf16 v[80:83], v[152:155], v[202:205], v[80:83]
	v_mfma_f32_16x16x32_bf16 v[124:127], v[148:151], v[180:183], v[124:127]
	v_mfma_f32_16x16x32_bf16 v[120:123], v[156:159], v[180:183], v[120:123]
	v_mfma_f32_16x16x32_bf16 v[116:119], v[148:151], v[188:191], v[116:119]
	v_mfma_f32_16x16x32_bf16 v[112:115], v[156:159], v[188:191], v[112:115]
	v_mfma_f32_16x16x32_bf16 v[100:103], v[148:151], v[198:201], v[100:103]
	v_mfma_f32_16x16x32_bf16 v[96:99], v[156:159], v[198:201], v[96:99]
	v_mfma_f32_16x16x32_bf16 v[84:87], v[148:151], v[206:209], v[84:87]
	v_mfma_f32_16x16x32_bf16 v[80:83], v[156:159], v[206:209], v[80:83]
	v_mfma_f32_16x16x32_bf16 v[108:111], v[160:163], v[176:179], v[108:111]
	v_mfma_f32_16x16x32_bf16 v[104:107], v[168:171], v[176:179], v[104:107]
	v_mfma_f32_16x16x32_bf16 v[92:95], v[160:163], v[184:187], v[92:95]
	v_mfma_f32_16x16x32_bf16 v[88:91], v[168:171], v[184:187], v[88:91]
	v_mfma_f32_16x16x32_bf16 v[76:79], v[160:163], v[194:197], v[76:79]
	v_mfma_f32_16x16x32_bf16 v[72:75], v[168:171], v[194:197], v[72:75]
	v_mfma_f32_16x16x32_bf16 v[68:71], v[160:163], v[202:205], v[68:71]
	v_mfma_f32_16x16x32_bf16 v[64:67], v[168:171], v[202:205], v[64:67]
	v_mfma_f32_16x16x32_bf16 v[108:111], v[164:167], v[180:183], v[108:111]
	v_mfma_f32_16x16x32_bf16 v[104:107], v[172:175], v[180:183], v[104:107]
	v_mfma_f32_16x16x32_bf16 v[92:95], v[164:167], v[188:191], v[92:95]
	v_mfma_f32_16x16x32_bf16 v[88:91], v[172:175], v[188:191], v[88:91]
	v_mfma_f32_16x16x32_bf16 v[76:79], v[164:167], v[198:201], v[76:79]
	v_mfma_f32_16x16x32_bf16 v[72:75], v[172:175], v[198:201], v[72:75]
	v_mfma_f32_16x16x32_bf16 v[68:71], v[164:167], v[206:209], v[68:71]
	v_mfma_f32_16x16x32_bf16 v[64:67], v[172:175], v[206:209], v[64:67]
	s_barrier
	s_add_i32 s56, s56, s37
	v_lshl_add_u64 v[210:211], s[22:23], 0, v[130:131]
	s_mov_b32 m0, s56
	ds_read_b128 v[176:179], v143 offset:16384
	ds_read_b128 v[180:183], v143 offset:17408
	ds_read_b128 v[184:187], v143 offset:18432
	ds_read_b128 v[188:191], v143 offset:19456
	ds_read_b128 v[194:197], v143 offset:20480
	ds_read_b128 v[198:201], v143 offset:21504
	ds_read_b128 v[202:205], v143 offset:22528
	ds_read_b128 v[206:209], v143 offset:23552
	global_load_lds_dwordx4 v[210:211], off
	s_add_i32 m0, s56, 0x2000
	s_add_u32 s56, s22, 0x40000
	v_lshl_add_u64 v[212:213], s[22:23], 0, v[134:135]
	s_addc_u32 s57, s23, 0
	s_add_i32 s58, s58, s37
	global_load_lds_dwordx4 v[212:213], off
	v_lshl_add_u64 v[214:215], s[56:57], 0, v[130:131]
	s_mov_b32 m0, s58
	v_lshl_add_u64 v[216:217], s[24:25], 0, v[132:133]
	global_load_lds_dwordx4 v[214:215], off
	v_lshl_add_u64 v[214:215], s[56:57], 0, v[134:135]
	s_add_i32 m0, s58, 0x2000
	s_nop 0
	global_load_lds_dwordx4 v[214:215], off
	v_lshl_add_u64 v[214:215], s[24:25], 0, v[128:129]
	s_mov_b32 m0, s38
	s_nop 0
	global_load_lds_dwordx4 v[214:215], off
	s_mov_b32 m0, s39
	s_nop 0
	global_load_lds_dwordx4 v[216:217], off
	s_waitcnt vmcnt(8)
	s_waitcnt lgkmcnt(0)
	s_barrier
; #define PG8_STAGE(bufoff, gbase, voff) do { _Pragma("unroll") for (int _i = 0; _i < 2; ++_i) \
;         __builtin_amdgcn_global_load_lds((const unsigned*)((const char*)(gbase) + (voff)[_i]), (LAS unsigned*)(lds + (bufoff) + ldsw + _i * 8192), 16, 0, 0); } while (0)
; #define PG8_LDA(dst, b, h) do { _Pragma("unroll") for (int m = 0; m < 4; ++m) _Pragma("unroll") for (int k = 0; k < 2; ++k) dst[m][k] = *(const LAS bf16x8*)(lds + PG8_SA(b, h) + aoff + m * 2048 + k * 1024); } while (0)
; #define PG8_LDB(dst, b, h) do { _Pragma("unroll") for (int n = 0; n < 2; ++n) _Pragma("unroll") for (int k = 0; k < 2; ++k) dst[n][k] = *(const LAS bf16x8*)(lds + PG8_SB(b, h) + boff + n * 2048 + k * 1024); } while (0)
; #define PG8_MMA(ai, bj, At, Bt) do { __builtin_amdgcn_s_setprio(1); _Pragma("unroll") for (int m = 0; m < 4; ++m) _Pragma("unroll") for (int n = 0; n < 2; ++n) _Pragma("unroll") for (int k = 0; k < 2; ++k) \
;         acc[ai][bj][m][n] = __builtin_amdgcn_mfma_f32_16x16x32_bf16(Bt[n][k], At[m][k], acc[ai][bj][m][n], 0, 0, 0); __builtin_amdgcn_s_setprio(0); } while (0)
; #define PG8_WAIT_V(n) asm volatile("s_waitcnt vmcnt(" #n ")" ::: "memory")
; #define PG8_WAIT_L(n) asm volatile("s_waitcnt lgkmcnt(" #n ")" ::: "memory")
; #define PG8_BAR __builtin_amdgcn_s_barrier()
; #define PG8_SCHED __builtin_amdgcn_sched_barrier(0)
; template <class Epi>
; DI void gemm_phase(int wv, LAS unsigned char* lds, LAS unsigned char* scr, const Sched& S, const Epi& E) {
;     ...
;             PG8_WAIT_V(8); PG8_WAIT_L(0); PG8_BAR; PG8_MMA(0, 0, At, B0); PG8_MMA(0, 1, At, B1); PG8_BAR; PG8_SCHED;
;             PG8_LDA(At, 0, 1); PG8_STAGE(PG8_SB(0, 0), b2, voffB); PG8_STAGE(PG8_SB(0, 1), b2 + hstepB, voffB); PG8_STAGE(PG8_SA(0, 0), a2, voffA);
;             PG8_WAIT_V(8); PG8_WAIT_L(0); PG8_BAR; PG8_MMA(1, 0, At, B0); PG8_MMA(1, 1, At, B1); PG8_BAR; PG8_SCHED;
;             PG8_LDB(B0, 1, 0); PG8_LDB(B1, 1, 1); PG8_SCHED; PG8_LDA(At, 1, 0); PG8_STAGE(PG8_SA(0, 1), a2 + hstepA, voffA);
;             PG8_WAIT_V(8); PG8_WAIT_L(0); PG8_BAR; PG8_MMA(0, 0, At, B0); PG8_MMA(0, 1, At, B1); PG8_BAR; PG8_SCHED;
	s_waitcnt lgkmcnt(0)
	v_mfma_f32_16x16x32_bf16 v[60:63], v[144:147], v[176:179], v[60:63]
	v_mfma_f32_16x16x32_bf16 v[56:59], v[152:155], v[176:179], v[56:59]
	v_mfma_f32_16x16x32_bf16 v[52:55], v[144:147], v[184:187], v[52:55]
	v_mfma_f32_16x16x32_bf16 v[48:51], v[152:155], v[184:187], v[48:51]
	v_mfma_f32_16x16x32_bf16 v[36:39], v[144:147], v[194:197], v[36:39]
	v_mfma_f32_16x16x32_bf16 v[32:35], v[152:155], v[194:197], v[32:35]
	v_mfma_f32_16x16x32_bf16 v[20:23], v[144:147], v[202:205], v[20:23]
	v_mfma_f32_16x16x32_bf16 v[16:19], v[152:155], v[202:205], v[16:19]
	v_mfma_f32_16x16x32_bf16 v[60:63], v[148:151], v[180:183], v[60:63]
	v_mfma_f32_16x16x32_bf16 v[56:59], v[156:159], v[180:183], v[56:59]
	v_mfma_f32_16x16x32_bf16 v[52:55], v[148:151], v[188:191], v[52:55]
	v_mfma_f32_16x16x32_bf16 v[48:51], v[156:159], v[188:191], v[48:51]
	v_mfma_f32_16x16x32_bf16 v[36:39], v[148:151], v[198:201], v[36:39]
	v_mfma_f32_16x16x32_bf16 v[32:35], v[156:159], v[198:201], v[32:35]
	v_mfma_f32_16x16x32_bf16 v[20:23], v[148:151], v[206:209], v[20:23]
	v_mfma_f32_16x16x32_bf16 v[16:19], v[156:159], v[206:209], v[16:19]
	v_mfma_f32_16x16x32_bf16 v[44:47], v[160:163], v[176:179], v[44:47]
	v_mfma_f32_16x16x32_bf16 v[40:43], v[168:171], v[176:179], v[40:43]
	v_mfma_f32_16x16x32_bf16 v[28:31], v[160:163], v[184:187], v[28:31]
	v_mfma_f32_16x16x32_bf16 v[24:27], v[168:171], v[184:187], v[24:27]
	v_mfma_f32_16x16x32_bf16 v[12:15], v[160:163], v[194:197], v[12:15]
	v_mfma_f32_16x16x32_bf16 v[8:11], v[168:171], v[194:197], v[8:11]
	v_mfma_f32_16x16x32_bf16 v[4:7], v[160:163], v[202:205], v[4:7]
	v_mfma_f32_16x16x32_bf16 v[0:3], v[168:171], v[202:205], v[0:3]
	v_mfma_f32_16x16x32_bf16 v[44:47], v[164:167], v[180:183], v[44:47]
	v_mfma_f32_16x16x32_bf16 v[40:43], v[172:175], v[180:183], v[40:43]
	v_mfma_f32_16x16x32_bf16 v[28:31], v[164:167], v[188:191], v[28:31]
	v_mfma_f32_16x16x32_bf16 v[24:27], v[172:175], v[188:191], v[24:27]
	v_mfma_f32_16x16x32_bf16 v[12:15], v[164:167], v[198:201], v[12:15]
	v_mfma_f32_16x16x32_bf16 v[8:11], v[172:175], v[198:201], v[8:11]
	v_mfma_f32_16x16x32_bf16 v[4:7], v[164:167], v[206:209], v[4:7]
	v_mfma_f32_16x16x32_bf16 v[0:3], v[172:175], v[206:209], v[0:3]
	s_barrier
	s_add_i32 s56, 0, 0x18000
	s_add_i32 s57, 0, 0x1c000
	v_add_u32_e32 v156, s56, v142
	v_add_u32_e32 v172, s57, v142
	ds_read_b128 v[144:147], v156
	ds_read_b128 v[148:151], v156 offset:1024
	ds_read_b128 v[152:155], v156 offset:2048
	ds_read_b128 v[156:159], v156 offset:3072
	ds_read_b128 v[160:163], v172
	ds_read_b128 v[164:167], v172 offset:1024
	ds_read_b128 v[168:171], v172 offset:2048
	ds_read_b128 v[172:175], v172 offset:3072
	s_add_u32 s24, s24, 0x40000
	s_addc_u32 s25, s25, 0
	s_mov_b32 m0, s42
	v_lshl_add_u64 v[218:219], s[24:25], 0, v[128:129]
	ds_read_b128 v[176:179], v143 offset:32768
	ds_read_b128 v[180:183], v143 offset:33792
	ds_read_b128 v[184:187], v143 offset:34816
	ds_read_b128 v[188:191], v143 offset:35840
	ds_read_b128 v[194:197], v143 offset:36864
	ds_read_b128 v[198:201], v143 offset:37888
	ds_read_b128 v[202:205], v143 offset:38912
	ds_read_b128 v[206:209], v143 offset:39936
	global_load_lds_dwordx4 v[218:219], off
	v_lshl_add_u64 v[218:219], s[24:25], 0, v[132:133]
	s_mov_b32 m0, s43
	s_nop 0
	global_load_lds_dwordx4 v[218:219], off
	s_waitcnt vmcnt(8)
	s_waitcnt lgkmcnt(0)
	s_barrier
	s_waitcnt lgkmcnt(0)
	v_mfma_f32_16x16x32_bf16 v[124:127], v[144:147], v[176:179], v[124:127]
	v_mfma_f32_16x16x32_bf16 v[120:123], v[152:155], v[176:179], v[120:123]
	v_mfma_f32_16x16x32_bf16 v[116:119], v[144:147], v[184:187], v[116:119]
	v_mfma_f32_16x16x32_bf16 v[112:115], v[152:155], v[184:187], v[112:115]
	v_mfma_f32_16x16x32_bf16 v[100:103], v[144:147], v[194:197], v[100:103]
	v_mfma_f32_16x16x32_bf16 v[96:99], v[152:155], v[194:197], v[96:99]
	v_mfma_f32_16x16x32_bf16 v[84:87], v[144:147], v[202:205], v[84:87]
	v_mfma_f32_16x16x32_bf16 v[80:83], v[152:155], v[202:205], v[80:83]
	v_mfma_f32_16x16x32_bf16 v[124:127], v[148:151], v[180:183], v[124:127]
	v_mfma_f32_16x16x32_bf16 v[120:123], v[156:159], v[180:183], v[120:123]
	v_mfma_f32_16x16x32_bf16 v[116:119], v[148:151], v[188:191], v[116:119]
	v_mfma_f32_16x16x32_bf16 v[112:115], v[156:159], v[188:191], v[112:115]
	v_mfma_f32_16x16x32_bf16 v[100:103], v[148:151], v[198:201], v[100:103]
	v_mfma_f32_16x16x32_bf16 v[96:99], v[156:159], v[198:201], v[96:99]
	v_mfma_f32_16x16x32_bf16 v[84:87], v[148:151], v[206:209], v[84:87]
	v_mfma_f32_16x16x32_bf16 v[80:83], v[156:159], v[206:209], v[80:83]
	v_mfma_f32_16x16x32_bf16 v[108:111], v[160:163], v[176:179], v[108:111]
	v_mfma_f32_16x16x32_bf16 v[104:107], v[168:171], v[176:179], v[104:107]
	v_mfma_f32_16x16x32_bf16 v[92:95], v[160:163], v[184:187], v[92:95]
	v_mfma_f32_16x16x32_bf16 v[88:91], v[168:171], v[184:187], v[88:91]
	v_mfma_f32_16x16x32_bf16 v[76:79], v[160:163], v[194:197], v[76:79]
	v_mfma_f32_16x16x32_bf16 v[72:75], v[168:171], v[194:197], v[72:75]
	v_mfma_f32_16x16x32_bf16 v[68:71], v[160:163], v[202:205], v[68:71]
	v_mfma_f32_16x16x32_bf16 v[64:67], v[168:171], v[202:205], v[64:67]
	v_mfma_f32_16x16x32_bf16 v[108:111], v[164:167], v[180:183], v[108:111]
	v_mfma_f32_16x16x32_bf16 v[104:107], v[172:175], v[180:183], v[104:107]
	v_mfma_f32_16x16x32_bf16 v[92:95], v[164:167], v[188:191], v[92:95]
	v_mfma_f32_16x16x32_bf16 v[88:91], v[172:175], v[188:191], v[88:91]
	v_mfma_f32_16x16x32_bf16 v[76:79], v[164:167], v[198:201], v[76:79]
	v_mfma_f32_16x16x32_bf16 v[72:75], v[172:175], v[198:201], v[72:75]
	v_mfma_f32_16x16x32_bf16 v[68:71], v[164:167], v[206:209], v[68:71]
	v_mfma_f32_16x16x32_bf16 v[64:67], v[172:175], v[206:209], v[64:67]
	s_barrier
; #define PG8_STAGE(bufoff, gbase, voff) do { _Pragma("unroll") for (int _i = 0; _i < 2; ++_i) \
;         __builtin_amdgcn_global_load_lds((const unsigned*)((const char*)(gbase) + (voff)[_i]), (LAS unsigned*)(lds + (bufoff) + ldsw + _i * 8192), 16, 0, 0); } while (0)
; #define PG8_LDA(dst, b, h) do { _Pragma("unroll") for (int m = 0; m < 4; ++m) _Pragma("unroll") for (int k = 0; k < 2; ++k) dst[m][k] = *(const LAS bf16x8*)(lds + PG8_SA(b, h) + aoff + m * 2048 + k * 1024); } while (0)
; #define PG8_MMA(ai, bj, At, Bt) do { __builtin_amdgcn_s_setprio(1); _Pragma("unroll") for (int m = 0; m < 4; ++m) _Pragma("unroll") for (int n = 0; n < 2; ++n) _Pragma("unroll") for (int k = 0; k < 2; ++k) \
;         acc[ai][bj][m][n] = __builtin_amdgcn_mfma_f32_16x16x32_bf16(Bt[n][k], At[m][k], acc[ai][bj][m][n], 0, 0, 0); __builtin_amdgcn_s_setprio(0); } while (0)
; #define PG8_WAIT_V(n) asm volatile("s_waitcnt vmcnt(" #n ")" ::: "memory")
; #define PG8_WAIT_L(n) asm volatile("s_waitcnt lgkmcnt(" #n ")" ::: "memory")
; #define PG8_BAR __builtin_amdgcn_s_barrier()
; #define PG8_SCHED __builtin_amdgcn_sched_barrier(0)
; template <class Epi>
; DI void gemm_phase(int wv, LAS unsigned char* lds, LAS unsigned char* scr, const Sched& S, const Epi& E) {
;     ...
;             PG8_LDA(At, 1, 1); PG8_STAGE(PG8_SB(1, 0), b3, voffB); PG8_STAGE(PG8_SB(1, 1), b3 + hstepB, voffB); PG8_STAGE(PG8_SA(1, 0), a3, voffA);
;             PG8_WAIT_V(8); PG8_WAIT_L(0); PG8_BAR; PG8_MMA(1, 0, At, B0); PG8_MMA(1, 1, At, B1); PG8_BAR; PG8_SCHED;
;         }
;         if (wr == 0) PG8_BAR;
	s_add_i32 s24, s56, s37
	v_lshl_add_u64 v[210:211], v[210:211], 0, s[2:3]
	s_mov_b32 m0, s24
	ds_read_b128 v[176:179], v143 offset:49152
	ds_read_b128 v[180:183], v143 offset:50176
	ds_read_b128 v[184:187], v143 offset:51200
	ds_read_b128 v[188:191], v143 offset:52224
	ds_read_b128 v[194:197], v143 offset:53248
	ds_read_b128 v[198:201], v143 offset:54272
	ds_read_b128 v[202:205], v143 offset:55296
	ds_read_b128 v[206:209], v143 offset:56320
	global_load_lds_dwordx4 v[210:211], off
	s_add_i32 m0, s24, 0x2000
	s_add_u32 s22, s22, 0x40080
	v_lshl_add_u64 v[210:211], v[212:213], 0, s[2:3]
	s_addc_u32 s23, s23, 0
	s_add_i32 s24, s57, s37
	global_load_lds_dwordx4 v[210:211], off
	v_lshl_add_u64 v[210:211], s[22:23], 0, v[130:131]
	s_mov_b32 m0, s24
	s_nop 0
	global_load_lds_dwordx4 v[210:211], off
	v_lshl_add_u64 v[210:211], s[22:23], 0, v[134:135]
	s_add_i32 m0, s24, 0x2000
	s_nop 0
	global_load_lds_dwordx4 v[210:211], off
	v_lshl_add_u64 v[210:211], v[214:215], 0, s[2:3]
	s_mov_b32 m0, s46
	s_nop 0
	global_load_lds_dwordx4 v[210:211], off
	v_lshl_add_u64 v[210:211], v[216:217], 0, s[2:3]
	s_mov_b32 m0, s47
	s_nop 0
	global_load_lds_dwordx4 v[210:211], off
	s_waitcnt vmcnt(8)
	s_waitcnt lgkmcnt(0)
	s_barrier
	s_waitcnt lgkmcnt(0)
	v_mfma_f32_16x16x32_bf16 v[60:63], v[144:147], v[176:179], v[60:63]
	v_mfma_f32_16x16x32_bf16 v[56:59], v[152:155], v[176:179], v[56:59]
	v_mfma_f32_16x16x32_bf16 v[52:55], v[144:147], v[184:187], v[52:55]
	v_mfma_f32_16x16x32_bf16 v[48:51], v[152:155], v[184:187], v[48:51]
	v_mfma_f32_16x16x32_bf16 v[36:39], v[144:147], v[194:197], v[36:39]
	v_mfma_f32_16x16x32_bf16 v[32:35], v[152:155], v[194:197], v[32:35]
	v_mfma_f32_16x16x32_bf16 v[20:23], v[144:147], v[202:205], v[20:23]
	v_mfma_f32_16x16x32_bf16 v[16:19], v[152:155], v[202:205], v[16:19]
	v_mfma_f32_16x16x32_bf16 v[60:63], v[148:151], v[180:183], v[60:63]
	v_mfma_f32_16x16x32_bf16 v[56:59], v[156:159], v[180:183], v[56:59]
	v_mfma_f32_16x16x32_bf16 v[52:55], v[148:151], v[188:191], v[52:55]
	v_mfma_f32_16x16x32_bf16 v[48:51], v[156:159], v[188:191], v[48:51]
	v_mfma_f32_16x16x32_bf16 v[36:39], v[148:151], v[198:201], v[36:39]
	v_mfma_f32_16x16x32_bf16 v[32:35], v[156:159], v[198:201], v[32:35]
	v_mfma_f32_16x16x32_bf16 v[20:23], v[148:151], v[206:209], v[20:23]
	v_mfma_f32_16x16x32_bf16 v[16:19], v[156:159], v[206:209], v[16:19]
	v_mfma_f32_16x16x32_bf16 v[44:47], v[160:163], v[176:179], v[44:47]
	v_mfma_f32_16x16x32_bf16 v[40:43], v[168:171], v[176:179], v[40:43]
	v_mfma_f32_16x16x32_bf16 v[28:31], v[160:163], v[184:187], v[28:31]
	v_mfma_f32_16x16x32_bf16 v[24:27], v[168:171], v[184:187], v[24:27]
	v_mfma_f32_16x16x32_bf16 v[12:15], v[160:163], v[194:197], v[12:15]
	v_mfma_f32_16x16x32_bf16 v[8:11], v[168:171], v[194:197], v[8:11]
	v_mfma_f32_16x16x32_bf16 v[4:7], v[160:163], v[202:205], v[4:7]
	v_mfma_f32_16x16x32_bf16 v[0:3], v[168:171], v[202:205], v[0:3]
	v_mfma_f32_16x16x32_bf16 v[44:47], v[164:167], v[180:183], v[44:47]
	v_mfma_f32_16x16x32_bf16 v[40:43], v[172:175], v[180:183], v[40:43]
	v_mfma_f32_16x16x32_bf16 v[28:31], v[164:167], v[188:191], v[28:31]
	v_mfma_f32_16x16x32_bf16 v[24:27], v[172:175], v[188:191], v[24:27]
	v_mfma_f32_16x16x32_bf16 v[12:15], v[164:167], v[198:201], v[12:15]
	v_mfma_f32_16x16x32_bf16 v[8:11], v[172:175], v[198:201], v[8:11]
	v_mfma_f32_16x16x32_bf16 v[4:7], v[164:167], v[206:209], v[4:7]
	v_mfma_f32_16x16x32_bf16 v[0:3], v[172:175], v[206:209], v[0:3]
	s_barrier
	s_add_i32 s53, s53, 2
	s_add_u32 s49, s49, 0x100
	s_addc_u32 s52, s52, 0
	s_add_u32 s20, s20, 0x100
	s_addc_u32 s21, s21, 0
	s_cmp_gt_u32 s53, 13
	s_cbranch_scc0 .LBB0_43
	s_and_b64 vcc, exec, s[4:5]
	s_cbranch_vccz .LBB0_46
	s_barrier

; #define PG8_STAGE(bufoff, gbase, voff) do { _Pragma("unroll") for (int _i = 0; _i < 2; ++_i) \
;         __builtin_amdgcn_global_load_lds((const unsigned*)((const char*)(gbase) + (voff)[_i]), (LAS unsigned*)(lds + (bufoff) + ldsw + _i * 8192), 16, 0, 0); } while (0)
; #define PG8_LDA(dst, b, h) do { _Pragma("unroll") for (int m = 0; m < 4; ++m) _Pragma("unroll") for (int k = 0; k < 2; ++k) dst[m][k] = *(const LAS bf16x8*)(lds + PG8_SA(b, h) + aoff + m * 2048 + k * 1024); } while (0)
; #define PG8_LDB(dst, b, h) do { _Pragma("unroll") for (int n = 0; n < 2; ++n) _Pragma("unroll") for (int k = 0; k < 2; ++k) dst[n][k] = *(const LAS bf16x8*)(lds + PG8_SB(b, h) + boff + n * 2048 + k * 1024); } while (0)
; #define PG8_MMA(ai, bj, At, Bt) do { __builtin_amdgcn_s_setprio(1); _Pragma("unroll") for (int m = 0; m < 4; ++m) _Pragma("unroll") for (int n = 0; n < 2; ++n) _Pragma("unroll") for (int k = 0; k < 2; ++k) \
;         acc[ai][bj][m][n] = __builtin_amdgcn_mfma_f32_16x16x32_bf16(Bt[n][k], At[m][k], acc[ai][bj][m][n], 0, 0, 0); __builtin_amdgcn_s_setprio(0); } while (0)
; #define PG8_WAIT_V(n) asm volatile("s_waitcnt vmcnt(" #n ")" ::: "memory")
; #define PG8_WAIT_L(n) asm volatile("s_waitcnt lgkmcnt(" #n ")" ::: "memory")
; #define PG8_BAR __builtin_amdgcn_s_barrier()
; #define PG8_SCHED __builtin_amdgcn_sched_barrier(0)
; template <class Epi>
; DI void gemm_phase(int wv, LAS unsigned char* lds, LAS unsigned char* scr, const Sched& S, const Epi& E) {
;     ...
;         for (int t = 0; t < nt; t += 2) {
;             const bool last = (t == nt - 2);
;             const char* a1 = cA + (size_t)(t + 1) * kstep;
;             const char* a2 = last ? nA : cA + (size_t)(t + 2) * kstep; const char* b2 = last ? nB : cB + (size_t)(t + 2) * kstep;
;             const char* a3 = a2 + kstep; const char* b3 = b2 + kstep;
;             PG8_LDB(B0, 0, 0); PG8_LDB(B1, 0, 1); PG8_SCHED; PG8_LDA(At, 0, 0); PG8_STAGE(PG8_SA(1, 1), a1 + hstepA, voffA);
;             PG8_WAIT_V(8); PG8_WAIT_L(0); PG8_BAR; PG8_MMA(0, 0, At, B0); PG8_MMA(0, 1, At, B1); PG8_BAR; PG8_SCHED;
;             PG8_LDA(At, 0, 1); PG8_STAGE(PG8_SB(0, 0), b2, voffB); PG8_STAGE(PG8_SB(0, 1), b2 + hstepB, voffB); PG8_STAGE(PG8_SA(0, 0), a2, voffA);
;             PG8_WAIT_V(8); PG8_WAIT_L(0); PG8_BAR; PG8_MMA(1, 0, At, B0); PG8_MMA(1, 1, At, B1); PG8_BAR; PG8_SCHED;
.LBB0_89:
	s_add_u32 s24, s22, 0xfffc0080
	s_addc_u32 s25, s23, -1
	s_add_i32 s58, 0, 0x10000
	s_cmp_eq_u32 s57, 12
	s_cselect_b32 s27, s15, s25
	s_cselect_b32 s26, s33, s24
	v_add_u32_e32 v145, s58, v150
	s_cselect_b32 s25, s13, s49
	s_cselect_b32 s24, s47, s48
	s_add_i32 s62, 0, 0x14000
	ds_read_b128 v[152:155], v145
	ds_read_b128 v[156:159], v145 offset:1024
	ds_read_b128 v[160:163], v145 offset:2048
	ds_read_b128 v[164:167], v145 offset:3072
	v_add_u32_e32 v145, s62, v150
	ds_read_b128 v[168:171], v145
	ds_read_b128 v[172:175], v145 offset:1024
	ds_read_b128 v[176:179], v145 offset:2048
	ds_read_b128 v[180:183], v145 offset:3072
	v_lshl_add_u64 v[148:149], s[22:23], 0, v[142:143]
	s_add_i32 m0, s36, 0xc000
	ds_read_b128 v[184:187], v151
	ds_read_b128 v[188:191], v151 offset:1024
	ds_read_b128 v[194:197], v151 offset:2048
	ds_read_b128 v[198:201], v151 offset:3072
	ds_read_b128 v[202:205], v151 offset:4096
	ds_read_b128 v[206:209], v151 offset:5120
	ds_read_b128 v[210:213], v151 offset:6144
	ds_read_b128 v[214:217], v151 offset:7168
	global_load_lds_dwordx4 v[148:149], off
	v_lshl_add_u64 v[148:149], s[22:23], 0, v[140:141]
	s_add_i32 m0, s36, 0xe000
	s_nop 0
	global_load_lds_dwordx4 v[148:149], off
	s_waitcnt vmcnt(8)
	s_waitcnt lgkmcnt(0)
	s_barrier
	s_waitcnt lgkmcnt(0)
	v_mfma_f32_16x16x32_bf16 v[124:127], v[152:155], v[184:187], v[124:127]
	v_mfma_f32_16x16x32_bf16 v[120:123], v[160:163], v[184:187], v[120:123]
	v_mfma_f32_16x16x32_bf16 v[108:111], v[152:155], v[194:197], v[108:111]
	v_mfma_f32_16x16x32_bf16 v[104:107], v[160:163], v[194:197], v[104:107]
	v_mfma_f32_16x16x32_bf16 v[92:95], v[152:155], v[202:205], v[92:95]
	v_mfma_f32_16x16x32_bf16 v[88:91], v[160:163], v[202:205], v[88:91]
	v_mfma_f32_16x16x32_bf16 v[76:79], v[152:155], v[210:213], v[76:79]
	v_mfma_f32_16x16x32_bf16 v[72:75], v[160:163], v[210:213], v[72:75]
	v_mfma_f32_16x16x32_bf16 v[124:127], v[156:159], v[188:191], v[124:127]
	v_mfma_f32_16x16x32_bf16 v[120:123], v[164:167], v[188:191], v[120:123]
	v_mfma_f32_16x16x32_bf16 v[108:111], v[156:159], v[198:201], v[108:111]
	v_mfma_f32_16x16x32_bf16 v[104:107], v[164:167], v[198:201], v[104:107]
	v_mfma_f32_16x16x32_bf16 v[92:95], v[156:159], v[206:209], v[92:95]
	v_mfma_f32_16x16x32_bf16 v[88:91], v[164:167], v[206:209], v[88:91]
	v_mfma_f32_16x16x32_bf16 v[76:79], v[156:159], v[214:217], v[76:79]
	v_mfma_f32_16x16x32_bf16 v[72:75], v[164:167], v[214:217], v[72:75]
	v_mfma_f32_16x16x32_bf16 v[116:119], v[168:171], v[184:187], v[116:119]
	v_mfma_f32_16x16x32_bf16 v[112:115], v[176:179], v[184:187], v[112:115]
	v_mfma_f32_16x16x32_bf16 v[100:103], v[168:171], v[194:197], v[100:103]
	v_mfma_f32_16x16x32_bf16 v[96:99], v[176:179], v[194:197], v[96:99]
	v_mfma_f32_16x16x32_bf16 v[84:87], v[168:171], v[202:205], v[84:87]
	v_mfma_f32_16x16x32_bf16 v[80:83], v[176:179], v[202:205], v[80:83]
	v_mfma_f32_16x16x32_bf16 v[68:71], v[168:171], v[210:213], v[68:71]
	v_mfma_f32_16x16x32_bf16 v[64:67], v[176:179], v[210:213], v[64:67]
	v_mfma_f32_16x16x32_bf16 v[116:119], v[172:175], v[188:191], v[116:119]
	v_mfma_f32_16x16x32_bf16 v[112:115], v[180:183], v[188:191], v[112:115]
	v_mfma_f32_16x16x32_bf16 v[100:103], v[172:175], v[198:201], v[100:103]
	v_mfma_f32_16x16x32_bf16 v[96:99], v[180:183], v[198:201], v[96:99]
	v_mfma_f32_16x16x32_bf16 v[84:87], v[172:175], v[206:209], v[84:87]
	v_mfma_f32_16x16x32_bf16 v[80:83], v[180:183], v[206:209], v[80:83]
	v_mfma_f32_16x16x32_bf16 v[68:71], v[172:175], v[214:217], v[68:71]
	v_mfma_f32_16x16x32_bf16 v[64:67], v[180:183], v[214:217], v[64:67]
	s_barrier
	s_add_i32 s58, s58, s35
	v_lshl_add_u64 v[148:149], s[24:25], 0, v[130:131]
	s_mov_b32 m0, s58
	ds_read_b128 v[184:187], v151 offset:16384
	ds_read_b128 v[188:191], v151 offset:17408
	ds_read_b128 v[194:197], v151 offset:18432
	ds_read_b128 v[198:201], v151 offset:19456
	ds_read_b128 v[202:205], v151 offset:20480
	ds_read_b128 v[206:209], v151 offset:21504
	ds_read_b128 v[210:213], v151 offset:22528
	ds_read_b128 v[214:217], v151 offset:23552
	global_load_lds_dwordx4 v[148:149], off
	s_add_i32 m0, s58, 0x2000
	s_add_u32 s60, s24, 0x40000
	v_lshl_add_u64 v[218:219], s[24:25], 0, v[134:135]
	s_addc_u32 s61, s25, 0
	s_add_i32 s58, s62, s35
	global_load_lds_dwordx4 v[218:219], off
	v_lshl_add_u64 v[220:221], s[60:61], 0, v[130:131]
	s_mov_b32 m0, s58
	v_lshl_add_u64 v[222:223], s[26:27], 0, v[132:133]
	global_load_lds_dwordx4 v[220:221], off
	v_lshl_add_u64 v[220:221], s[60:61], 0, v[134:135]
	s_add_i32 m0, s58, 0x2000
	s_nop 0
	global_load_lds_dwordx4 v[220:221], off
	v_lshl_add_u64 v[220:221], s[26:27], 0, v[128:129]
	s_mov_b32 m0, s36
	s_nop 0
	global_load_lds_dwordx4 v[220:221], off
	s_mov_b32 m0, s37
	s_nop 0
	global_load_lds_dwordx4 v[222:223], off
	s_waitcnt vmcnt(8)
	s_waitcnt lgkmcnt(0)
	s_barrier
; #define PG8_STAGE(bufoff, gbase, voff) do { _Pragma("unroll") for (int _i = 0; _i < 2; ++_i) \
;         __builtin_amdgcn_global_load_lds((const unsigned*)((const char*)(gbase) + (voff)[_i]), (LAS unsigned*)(lds + (bufoff) + ldsw + _i * 8192), 16, 0, 0); } while (0)
; #define PG8_LDA(dst, b, h) do { _Pragma("unroll") for (int m = 0; m < 4; ++m) _Pragma("unroll") for (int k = 0; k < 2; ++k) dst[m][k] = *(const LAS bf16x8*)(lds + PG8_SA(b, h) + aoff + m * 2048 + k * 1024); } while (0)
; #define PG8_LDB(dst, b, h) do { _Pragma("unroll") for (int n = 0; n < 2; ++n) _Pragma("unroll") for (int k = 0; k < 2; ++k) dst[n][k] = *(const LAS bf16x8*)(lds + PG8_SB(b, h) + boff + n * 2048 + k * 1024); } while (0)
; #define PG8_MMA(ai, bj, At, Bt) do { __builtin_amdgcn_s_setprio(1); _Pragma("unroll") for (int m = 0; m < 4; ++m) _Pragma("unroll") for (int n = 0; n < 2; ++n) _Pragma("unroll") for (int k = 0; k < 2; ++k) \
;         acc[ai][bj][m][n] = __builtin_amdgcn_mfma_f32_16x16x32_bf16(Bt[n][k], At[m][k], acc[ai][bj][m][n], 0, 0, 0); __builtin_amdgcn_s_setprio(0); } while (0)
; #define PG8_WAIT_V(n) asm volatile("s_waitcnt vmcnt(" #n ")" ::: "memory")
; #define PG8_WAIT_L(n) asm volatile("s_waitcnt lgkmcnt(" #n ")" ::: "memory")
; #define PG8_BAR __builtin_amdgcn_s_barrier()
; #define PG8_SCHED __builtin_amdgcn_sched_barrier(0)
; template <class Epi>
; DI void gemm_phase(int wv, LAS unsigned char* lds, LAS unsigned char* scr, const Sched& S, const Epi& E) {
;     ...
;             PG8_WAIT_V(8); PG8_WAIT_L(0); PG8_BAR; PG8_MMA(0, 0, At, B0); PG8_MMA(0, 1, At, B1); PG8_BAR; PG8_SCHED;
;             PG8_LDA(At, 0, 1); PG8_STAGE(PG8_SB(0, 0), b2, voffB); PG8_STAGE(PG8_SB(0, 1), b2 + hstepB, voffB); PG8_STAGE(PG8_SA(0, 0), a2, voffA);
;             PG8_WAIT_V(8); PG8_WAIT_L(0); PG8_BAR; PG8_MMA(1, 0, At, B0); PG8_MMA(1, 1, At, B1); PG8_BAR; PG8_SCHED;
;             PG8_LDB(B0, 1, 0); PG8_LDB(B1, 1, 1); PG8_SCHED; PG8_LDA(At, 1, 0); PG8_STAGE(PG8_SA(0, 1), a2 + hstepA, voffA);
;             PG8_WAIT_V(8); PG8_WAIT_L(0); PG8_BAR; PG8_MMA(0, 0, At, B0); PG8_MMA(0, 1, At, B1); PG8_BAR; PG8_SCHED;
	s_waitcnt lgkmcnt(0)
	v_mfma_f32_16x16x32_bf16 v[60:63], v[152:155], v[184:187], v[60:63]
	v_mfma_f32_16x16x32_bf16 v[56:59], v[160:163], v[184:187], v[56:59]
	v_mfma_f32_16x16x32_bf16 v[44:47], v[152:155], v[194:197], v[44:47]
	v_mfma_f32_16x16x32_bf16 v[40:43], v[160:163], v[194:197], v[40:43]
	v_mfma_f32_16x16x32_bf16 v[28:31], v[152:155], v[202:205], v[28:31]
	v_mfma_f32_16x16x32_bf16 v[24:27], v[160:163], v[202:205], v[24:27]
	v_mfma_f32_16x16x32_bf16 v[12:15], v[152:155], v[210:213], v[12:15]
	v_mfma_f32_16x16x32_bf16 v[8:11], v[160:163], v[210:213], v[8:11]
	v_mfma_f32_16x16x32_bf16 v[60:63], v[156:159], v[188:191], v[60:63]
	v_mfma_f32_16x16x32_bf16 v[56:59], v[164:167], v[188:191], v[56:59]
	v_mfma_f32_16x16x32_bf16 v[44:47], v[156:159], v[198:201], v[44:47]
	v_mfma_f32_16x16x32_bf16 v[40:43], v[164:167], v[198:201], v[40:43]
	v_mfma_f32_16x16x32_bf16 v[28:31], v[156:159], v[206:209], v[28:31]
	v_mfma_f32_16x16x32_bf16 v[24:27], v[164:167], v[206:209], v[24:27]
	v_mfma_f32_16x16x32_bf16 v[12:15], v[156:159], v[214:217], v[12:15]
	v_mfma_f32_16x16x32_bf16 v[8:11], v[164:167], v[214:217], v[8:11]
	v_mfma_f32_16x16x32_bf16 v[52:55], v[168:171], v[184:187], v[52:55]
	v_mfma_f32_16x16x32_bf16 v[48:51], v[176:179], v[184:187], v[48:51]
	v_mfma_f32_16x16x32_bf16 v[36:39], v[168:171], v[194:197], v[36:39]
	v_mfma_f32_16x16x32_bf16 v[32:35], v[176:179], v[194:197], v[32:35]
	v_mfma_f32_16x16x32_bf16 v[20:23], v[168:171], v[202:205], v[20:23]
	v_mfma_f32_16x16x32_bf16 v[16:19], v[176:179], v[202:205], v[16:19]
	v_mfma_f32_16x16x32_bf16 v[4:7], v[168:171], v[210:213], v[4:7]
	v_mfma_f32_16x16x32_bf16 v[0:3], v[176:179], v[210:213], v[0:3]
	v_mfma_f32_16x16x32_bf16 v[52:55], v[172:175], v[188:191], v[52:55]
	v_mfma_f32_16x16x32_bf16 v[48:51], v[180:183], v[188:191], v[48:51]
	v_mfma_f32_16x16x32_bf16 v[36:39], v[172:175], v[198:201], v[36:39]
	v_mfma_f32_16x16x32_bf16 v[32:35], v[180:183], v[198:201], v[32:35]
	v_mfma_f32_16x16x32_bf16 v[20:23], v[172:175], v[206:209], v[20:23]
	v_mfma_f32_16x16x32_bf16 v[16:19], v[180:183], v[206:209], v[16:19]
	v_mfma_f32_16x16x32_bf16 v[4:7], v[172:175], v[214:217], v[4:7]
	v_mfma_f32_16x16x32_bf16 v[0:3], v[180:183], v[214:217], v[0:3]
	s_barrier
	s_add_i32 s58, 0, 0x18000
	v_add_u32_e32 v145, s58, v150
	s_add_i32 s60, 0, 0x1c000
	ds_read_b128 v[152:155], v145
	ds_read_b128 v[156:159], v145 offset:1024
	ds_read_b128 v[160:163], v145 offset:2048
	ds_read_b128 v[164:167], v145 offset:3072
	v_add_u32_e32 v145, s60, v150
	ds_read_b128 v[168:171], v145
	ds_read_b128 v[172:175], v145 offset:1024
	ds_read_b128 v[176:179], v145 offset:2048
	ds_read_b128 v[180:183], v145 offset:3072
	s_add_u32 s26, s26, 0x40000
	s_addc_u32 s27, s27, 0
	s_mov_b32 m0, s38
	v_lshl_add_u64 v[224:225], s[26:27], 0, v[128:129]
	ds_read_b128 v[184:187], v151 offset:32768
	ds_read_b128 v[188:191], v151 offset:33792
	ds_read_b128 v[194:197], v151 offset:34816
	ds_read_b128 v[198:201], v151 offset:35840
	ds_read_b128 v[202:205], v151 offset:36864
	ds_read_b128 v[206:209], v151 offset:37888
	ds_read_b128 v[210:213], v151 offset:38912
	ds_read_b128 v[214:217], v151 offset:39936
	global_load_lds_dwordx4 v[224:225], off
	v_lshl_add_u64 v[224:225], s[26:27], 0, v[132:133]
	s_mov_b32 m0, s39
	s_nop 0
	global_load_lds_dwordx4 v[224:225], off
	s_waitcnt vmcnt(8)
	s_waitcnt lgkmcnt(0)
	s_barrier
	s_waitcnt lgkmcnt(0)
	v_mfma_f32_16x16x32_bf16 v[124:127], v[152:155], v[184:187], v[124:127]
	v_mfma_f32_16x16x32_bf16 v[120:123], v[160:163], v[184:187], v[120:123]
	v_mfma_f32_16x16x32_bf16 v[108:111], v[152:155], v[194:197], v[108:111]
	v_mfma_f32_16x16x32_bf16 v[104:107], v[160:163], v[194:197], v[104:107]
	v_mfma_f32_16x16x32_bf16 v[92:95], v[152:155], v[202:205], v[92:95]
	v_mfma_f32_16x16x32_bf16 v[88:91], v[160:163], v[202:205], v[88:91]
	v_mfma_f32_16x16x32_bf16 v[76:79], v[152:155], v[210:213], v[76:79]
	v_mfma_f32_16x16x32_bf16 v[72:75], v[160:163], v[210:213], v[72:75]
	v_mfma_f32_16x16x32_bf16 v[124:127], v[156:159], v[188:191], v[124:127]
	v_mfma_f32_16x16x32_bf16 v[120:123], v[164:167], v[188:191], v[120:123]
	v_mfma_f32_16x16x32_bf16 v[108:111], v[156:159], v[198:201], v[108:111]
	v_mfma_f32_16x16x32_bf16 v[104:107], v[164:167], v[198:201], v[104:107]
	v_mfma_f32_16x16x32_bf16 v[92:95], v[156:159], v[206:209], v[92:95]
	v_mfma_f32_16x16x32_bf16 v[88:91], v[164:167], v[206:209], v[88:91]
	v_mfma_f32_16x16x32_bf16 v[76:79], v[156:159], v[214:217], v[76:79]
	v_mfma_f32_16x16x32_bf16 v[72:75], v[164:167], v[214:217], v[72:75]
	v_mfma_f32_16x16x32_bf16 v[116:119], v[168:171], v[184:187], v[116:119]
	v_mfma_f32_16x16x32_bf16 v[112:115], v[176:179], v[184:187], v[112:115]
	v_mfma_f32_16x16x32_bf16 v[100:103], v[168:171], v[194:197], v[100:103]
	v_mfma_f32_16x16x32_bf16 v[96:99], v[176:179], v[194:197], v[96:99]
	v_mfma_f32_16x16x32_bf16 v[84:87], v[168:171], v[202:205], v[84:87]
	v_mfma_f32_16x16x32_bf16 v[80:83], v[176:179], v[202:205], v[80:83]
	v_mfma_f32_16x16x32_bf16 v[68:71], v[168:171], v[210:213], v[68:71]
	v_mfma_f32_16x16x32_bf16 v[64:67], v[176:179], v[210:213], v[64:67]
	v_mfma_f32_16x16x32_bf16 v[116:119], v[172:175], v[188:191], v[116:119]
	v_mfma_f32_16x16x32_bf16 v[112:115], v[180:183], v[188:191], v[112:115]
	v_mfma_f32_16x16x32_bf16 v[100:103], v[172:175], v[198:201], v[100:103]
	v_mfma_f32_16x16x32_bf16 v[96:99], v[180:183], v[198:201], v[96:99]
	v_mfma_f32_16x16x32_bf16 v[84:87], v[172:175], v[206:209], v[84:87]
	v_mfma_f32_16x16x32_bf16 v[80:83], v[180:183], v[206:209], v[80:83]
	v_mfma_f32_16x16x32_bf16 v[68:71], v[172:175], v[214:217], v[68:71]
	v_mfma_f32_16x16x32_bf16 v[64:67], v[180:183], v[214:217], v[64:67]
	s_barrier
; #define PG8_STAGE(bufoff, gbase, voff) do { _Pragma("unroll") for (int _i = 0; _i < 2; ++_i) \
;         __builtin_amdgcn_global_load_lds((const unsigned*)((const char*)(gbase) + (voff)[_i]), (LAS unsigned*)(lds + (bufoff) + ldsw + _i * 8192), 16, 0, 0); } while (0)
; #define PG8_LDA(dst, b, h) do { _Pragma("unroll") for (int m = 0; m < 4; ++m) _Pragma("unroll") for (int k = 0; k < 2; ++k) dst[m][k] = *(const LAS bf16x8*)(lds + PG8_SA(b, h) + aoff + m * 2048 + k * 1024); } while (0)
; #define PG8_MMA(ai, bj, At, Bt) do { __builtin_amdgcn_s_setprio(1); _Pragma("unroll") for (int m = 0; m < 4; ++m) _Pragma("unroll") for (int n = 0; n < 2; ++n) _Pragma("unroll") for (int k = 0; k < 2; ++k) \
;         acc[ai][bj][m][n] = __builtin_amdgcn_mfma_f32_16x16x32_bf16(Bt[n][k], At[m][k], acc[ai][bj][m][n], 0, 0, 0); __builtin_amdgcn_s_setprio(0); } while (0)
; #define PG8_WAIT_V(n) asm volatile("s_waitcnt vmcnt(" #n ")" ::: "memory")
; #define PG8_WAIT_L(n) asm volatile("s_waitcnt lgkmcnt(" #n ")" ::: "memory")
; #define PG8_BAR __builtin_amdgcn_s_barrier()
; #define PG8_SCHED __builtin_amdgcn_sched_barrier(0)
; template <class Epi>
; DI void gemm_phase(int wv, LAS unsigned char* lds, LAS unsigned char* scr, const Sched& S, const Epi& E) {
;     ...
;             PG8_LDA(At, 1, 1); PG8_STAGE(PG8_SB(1, 0), b3, voffB); PG8_STAGE(PG8_SB(1, 1), b3 + hstepB, voffB); PG8_STAGE(PG8_SA(1, 0), a3, voffA);
;             PG8_WAIT_V(8); PG8_WAIT_L(0); PG8_BAR; PG8_MMA(1, 0, At, B0); PG8_MMA(1, 1, At, B1); PG8_BAR; PG8_SCHED;
;         }
;         if (wr == 0) PG8_BAR;
	s_add_i32 s26, s58, s35
	v_lshl_add_u64 v[148:149], v[148:149], 0, s[2:3]
	s_mov_b32 m0, s26
	ds_read_b128 v[184:187], v151 offset:49152
	ds_read_b128 v[188:191], v151 offset:50176
	ds_read_b128 v[194:197], v151 offset:51200
	ds_read_b128 v[198:201], v151 offset:52224
	ds_read_b128 v[202:205], v151 offset:53248
	ds_read_b128 v[206:209], v151 offset:54272
	ds_read_b128 v[210:213], v151 offset:55296
	ds_read_b128 v[214:217], v151 offset:56320
	global_load_lds_dwordx4 v[148:149], off
	s_add_i32 m0, s26, 0x2000
	s_add_u32 s24, s24, 0x40080
	v_lshl_add_u64 v[148:149], v[218:219], 0, s[2:3]
	s_addc_u32 s25, s25, 0
	s_add_i32 s26, s60, s35
	global_load_lds_dwordx4 v[148:149], off
	v_lshl_add_u64 v[148:149], s[24:25], 0, v[130:131]
	s_mov_b32 m0, s26
	s_nop 0
	global_load_lds_dwordx4 v[148:149], off
	v_lshl_add_u64 v[148:149], s[24:25], 0, v[134:135]
	s_add_i32 m0, s26, 0x2000
	s_nop 0
	global_load_lds_dwordx4 v[148:149], off
	v_lshl_add_u64 v[148:149], v[220:221], 0, s[2:3]
	s_mov_b32 m0, s42
	s_nop 0
	global_load_lds_dwordx4 v[148:149], off
	v_lshl_add_u64 v[148:149], v[222:223], 0, s[2:3]
	s_mov_b32 m0, s43
	s_nop 0
	global_load_lds_dwordx4 v[148:149], off
	s_waitcnt vmcnt(8)
	s_waitcnt lgkmcnt(0)
	s_barrier
	s_waitcnt lgkmcnt(0)
	v_mfma_f32_16x16x32_bf16 v[60:63], v[152:155], v[184:187], v[60:63]
	v_mfma_f32_16x16x32_bf16 v[56:59], v[160:163], v[184:187], v[56:59]
	v_mfma_f32_16x16x32_bf16 v[44:47], v[152:155], v[194:197], v[44:47]
	v_mfma_f32_16x16x32_bf16 v[40:43], v[160:163], v[194:197], v[40:43]
	v_mfma_f32_16x16x32_bf16 v[28:31], v[152:155], v[202:205], v[28:31]
	v_mfma_f32_16x16x32_bf16 v[24:27], v[160:163], v[202:205], v[24:27]
	v_mfma_f32_16x16x32_bf16 v[12:15], v[152:155], v[210:213], v[12:15]
	v_mfma_f32_16x16x32_bf16 v[8:11], v[160:163], v[210:213], v[8:11]
	v_mfma_f32_16x16x32_bf16 v[60:63], v[156:159], v[188:191], v[60:63]
	v_mfma_f32_16x16x32_bf16 v[56:59], v[164:167], v[188:191], v[56:59]
	v_mfma_f32_16x16x32_bf16 v[44:47], v[156:159], v[198:201], v[44:47]
	v_mfma_f32_16x16x32_bf16 v[40:43], v[164:167], v[198:201], v[40:43]
	v_mfma_f32_16x16x32_bf16 v[28:31], v[156:159], v[206:209], v[28:31]
	v_mfma_f32_16x16x32_bf16 v[24:27], v[164:167], v[206:209], v[24:27]
	v_mfma_f32_16x16x32_bf16 v[12:15], v[156:159], v[214:217], v[12:15]
	v_mfma_f32_16x16x32_bf16 v[8:11], v[164:167], v[214:217], v[8:11]
	v_mfma_f32_16x16x32_bf16 v[52:55], v[168:171], v[184:187], v[52:55]
	v_mfma_f32_16x16x32_bf16 v[48:51], v[176:179], v[184:187], v[48:51]
	v_mfma_f32_16x16x32_bf16 v[36:39], v[168:171], v[194:197], v[36:39]
	v_mfma_f32_16x16x32_bf16 v[32:35], v[176:179], v[194:197], v[32:35]
	v_mfma_f32_16x16x32_bf16 v[20:23], v[168:171], v[202:205], v[20:23]
	v_mfma_f32_16x16x32_bf16 v[16:19], v[176:179], v[202:205], v[16:19]
	v_mfma_f32_16x16x32_bf16 v[4:7], v[168:171], v[210:213], v[4:7]
	v_mfma_f32_16x16x32_bf16 v[0:3], v[176:179], v[210:213], v[0:3]
	v_mfma_f32_16x16x32_bf16 v[52:55], v[172:175], v[188:191], v[52:55]
	v_mfma_f32_16x16x32_bf16 v[48:51], v[180:183], v[188:191], v[48:51]
	v_mfma_f32_16x16x32_bf16 v[36:39], v[172:175], v[198:201], v[36:39]
	v_mfma_f32_16x16x32_bf16 v[32:35], v[180:183], v[198:201], v[32:35]
	v_mfma_f32_16x16x32_bf16 v[20:23], v[172:175], v[206:209], v[20:23]
	v_mfma_f32_16x16x32_bf16 v[16:19], v[180:183], v[206:209], v[16:19]
	v_mfma_f32_16x16x32_bf16 v[4:7], v[172:175], v[214:217], v[4:7]
	v_mfma_f32_16x16x32_bf16 v[0:3], v[180:183], v[214:217], v[0:3]
	s_barrier
	s_add_i32 s57, s57, 2
	s_add_u32 s48, s48, 0x100
	s_addc_u32 s49, s49, 0
	s_add_u32 s22, s22, 0x100
	s_addc_u32 s23, s23, 0
	s_cmp_gt_u32 s57, 13
	s_cbranch_scc0 .LBB0_89
	s_and_b64 vcc, exec, s[10:11]
	s_cbranch_vccz .LBB0_92
	s_barrier

; #define PG8_STAGE(bufoff, gbase, voff) do { _Pragma("unroll") for (int _i = 0; _i < 2; ++_i) \
;         __builtin_amdgcn_global_load_lds((const unsigned*)((const char*)(gbase) + (voff)[_i]), (LAS unsigned*)(lds + (bufoff) + ldsw + _i * 8192), 16, 0, 0); } while (0)
; #define PG8_LDA(dst, b, h) do { _Pragma("unroll") for (int m = 0; m < 4; ++m) _Pragma("unroll") for (int k = 0; k < 2; ++k) dst[m][k] = *(const LAS bf16x8*)(lds + PG8_SA(b, h) + aoff + m * 2048 + k * 1024); } while (0)
; #define PG8_LDB(dst, b, h) do { _Pragma("unroll") for (int n = 0; n < 2; ++n) _Pragma("unroll") for (int k = 0; k < 2; ++k) dst[n][k] = *(const LAS bf16x8*)(lds + PG8_SB(b, h) + boff + n * 2048 + k * 1024); } while (0)
; #define PG8_MMA(ai, bj, At, Bt) do { __builtin_amdgcn_s_setprio(1); _Pragma("unroll") for (int m = 0; m < 4; ++m) _Pragma("unroll") for (int n = 0; n < 2; ++n) _Pragma("unroll") for (int k = 0; k < 2; ++k) \
;         acc[ai][bj][m][n] = __builtin_amdgcn_mfma_f32_16x16x32_bf16(Bt[n][k], At[m][k], acc[ai][bj][m][n], 0, 0, 0); __builtin_amdgcn_s_setprio(0); } while (0)
; #define PG8_WAIT_V(n) asm volatile("s_waitcnt vmcnt(" #n ")" ::: "memory")
; #define PG8_WAIT_L(n) asm volatile("s_waitcnt lgkmcnt(" #n ")" ::: "memory")
; #define PG8_BAR __builtin_amdgcn_s_barrier()
; #define PG8_SCHED __builtin_amdgcn_sched_barrier(0)
; template <class Epi>
; DI void gemm_phase(int wv, LAS unsigned char* lds, LAS unsigned char* scr, const Sched& S, const Epi& E) {
;     ...
;         for (int t = 0; t < nt; t += 2) {
;             const bool last = (t == nt - 2);
;             const char* a1 = cA + (size_t)(t + 1) * kstep;
;             const char* a2 = last ? nA : cA + (size_t)(t + 2) * kstep; const char* b2 = last ? nB : cB + (size_t)(t + 2) * kstep;
;             const char* a3 = a2 + kstep; const char* b3 = b2 + kstep;
;             PG8_LDB(B0, 0, 0); PG8_LDB(B1, 0, 1); PG8_SCHED; PG8_LDA(At, 0, 0); PG8_STAGE(PG8_SA(1, 1), a1 + hstepA, voffA);
;             PG8_WAIT_V(8); PG8_WAIT_L(0); PG8_BAR; PG8_MMA(0, 0, At, B0); PG8_MMA(0, 1, At, B1); PG8_BAR; PG8_SCHED;
;             PG8_LDA(At, 0, 1); PG8_STAGE(PG8_SB(0, 0), b2, voffB); PG8_STAGE(PG8_SB(0, 1), b2 + hstepB, voffB); PG8_STAGE(PG8_SA(0, 0), a2, voffA);
;             PG8_WAIT_V(8); PG8_WAIT_L(0); PG8_BAR; PG8_MMA(1, 0, At, B0); PG8_MMA(1, 1, At, B1); PG8_BAR; PG8_SCHED;
.LBB0_113:
	s_add_u32 s46, s44, 0xfffc0080
	s_addc_u32 s47, s45, -1
	s_add_i32 s75, 0, 0x10000
	s_cmp_eq_u32 s74, 12
	s_cselect_b32 s49, s29, s47
	s_cselect_b32 s48, s31, s46
	s_cselect_b32 s47, s35, s73
	s_cselect_b32 s46, s37, s72
	s_add_i32 s78, 0, 0x14000
	v_add_u32_e32 v156, s75, v142
	v_add_u32_e32 v172, s78, v142
	ds_read_b128 v[144:147], v156
	ds_read_b128 v[148:151], v156 offset:1024
	ds_read_b128 v[152:155], v156 offset:2048
	ds_read_b128 v[156:159], v156 offset:3072
	ds_read_b128 v[160:163], v172
	ds_read_b128 v[164:167], v172 offset:1024
	ds_read_b128 v[168:171], v172 offset:2048
	ds_read_b128 v[172:175], v172 offset:3072
	v_lshl_add_u64 v[210:211], s[44:45], 0, v[140:141]
	s_add_i32 m0, s62, 0xc000
	ds_read_b128 v[176:179], v143
	ds_read_b128 v[180:183], v143 offset:1024
	ds_read_b128 v[184:187], v143 offset:2048
	ds_read_b128 v[188:191], v143 offset:3072
	ds_read_b128 v[194:197], v143 offset:4096
	ds_read_b128 v[198:201], v143 offset:5120
	ds_read_b128 v[202:205], v143 offset:6144
	ds_read_b128 v[206:209], v143 offset:7168
	global_load_lds_dwordx4 v[210:211], off
	v_lshl_add_u64 v[210:211], s[44:45], 0, v[138:139]
	s_add_i32 m0, s62, 0xe000
	s_nop 0
	global_load_lds_dwordx4 v[210:211], off
	s_waitcnt vmcnt(8)
	s_waitcnt lgkmcnt(0)
	s_barrier
	s_waitcnt lgkmcnt(0)
	v_mfma_f32_16x16x32_bf16 v[124:127], v[144:147], v[176:179], v[124:127]
	v_mfma_f32_16x16x32_bf16 v[120:123], v[152:155], v[176:179], v[120:123]
	v_mfma_f32_16x16x32_bf16 v[116:119], v[144:147], v[184:187], v[116:119]
	v_mfma_f32_16x16x32_bf16 v[112:115], v[152:155], v[184:187], v[112:115]
	v_mfma_f32_16x16x32_bf16 v[100:103], v[144:147], v[194:197], v[100:103]
	v_mfma_f32_16x16x32_bf16 v[96:99], v[152:155], v[194:197], v[96:99]
	v_mfma_f32_16x16x32_bf16 v[84:87], v[144:147], v[202:205], v[84:87]
	v_mfma_f32_16x16x32_bf16 v[80:83], v[152:155], v[202:205], v[80:83]
	v_mfma_f32_16x16x32_bf16 v[124:127], v[148:151], v[180:183], v[124:127]
	v_mfma_f32_16x16x32_bf16 v[120:123], v[156:159], v[180:183], v[120:123]
	v_mfma_f32_16x16x32_bf16 v[116:119], v[148:151], v[188:191], v[116:119]
	v_mfma_f32_16x16x32_bf16 v[112:115], v[156:159], v[188:191], v[112:115]
	v_mfma_f32_16x16x32_bf16 v[100:103], v[148:151], v[198:201], v[100:103]
	v_mfma_f32_16x16x32_bf16 v[96:99], v[156:159], v[198:201], v[96:99]
	v_mfma_f32_16x16x32_bf16 v[84:87], v[148:151], v[206:209], v[84:87]
	v_mfma_f32_16x16x32_bf16 v[80:83], v[156:159], v[206:209], v[80:83]
	v_mfma_f32_16x16x32_bf16 v[108:111], v[160:163], v[176:179], v[108:111]
	v_mfma_f32_16x16x32_bf16 v[104:107], v[168:171], v[176:179], v[104:107]
	v_mfma_f32_16x16x32_bf16 v[92:95], v[160:163], v[184:187], v[92:95]
	v_mfma_f32_16x16x32_bf16 v[88:91], v[168:171], v[184:187], v[88:91]
	v_mfma_f32_16x16x32_bf16 v[76:79], v[160:163], v[194:197], v[76:79]
	v_mfma_f32_16x16x32_bf16 v[72:75], v[168:171], v[194:197], v[72:75]
	v_mfma_f32_16x16x32_bf16 v[68:71], v[160:163], v[202:205], v[68:71]
	v_mfma_f32_16x16x32_bf16 v[64:67], v[168:171], v[202:205], v[64:67]
	v_mfma_f32_16x16x32_bf16 v[108:111], v[164:167], v[180:183], v[108:111]
	v_mfma_f32_16x16x32_bf16 v[104:107], v[172:175], v[180:183], v[104:107]
	v_mfma_f32_16x16x32_bf16 v[92:95], v[164:167], v[188:191], v[92:95]
	v_mfma_f32_16x16x32_bf16 v[88:91], v[172:175], v[188:191], v[88:91]
	v_mfma_f32_16x16x32_bf16 v[76:79], v[164:167], v[198:201], v[76:79]
	v_mfma_f32_16x16x32_bf16 v[72:75], v[172:175], v[198:201], v[72:75]
	v_mfma_f32_16x16x32_bf16 v[68:71], v[164:167], v[206:209], v[68:71]
	v_mfma_f32_16x16x32_bf16 v[64:67], v[172:175], v[206:209], v[64:67]
	s_barrier
	s_add_i32 s75, s75, s60
	v_lshl_add_u64 v[210:211], s[46:47], 0, v[130:131]
	s_mov_b32 m0, s75
	ds_read_b128 v[176:179], v143 offset:16384
	ds_read_b128 v[180:183], v143 offset:17408
	ds_read_b128 v[184:187], v143 offset:18432
	ds_read_b128 v[188:191], v143 offset:19456
	ds_read_b128 v[194:197], v143 offset:20480
	ds_read_b128 v[198:201], v143 offset:21504
	ds_read_b128 v[202:205], v143 offset:22528
	ds_read_b128 v[206:209], v143 offset:23552
	global_load_lds_dwordx4 v[210:211], off
	s_add_i32 m0, s75, 0x2000
	s_add_u32 s76, s46, 0x40000
	v_lshl_add_u64 v[212:213], s[46:47], 0, v[134:135]
	s_addc_u32 s77, s47, 0
	s_add_i32 s75, s78, s60
	global_load_lds_dwordx4 v[212:213], off
	v_lshl_add_u64 v[214:215], s[76:77], 0, v[130:131]
	s_mov_b32 m0, s75
	v_lshl_add_u64 v[216:217], s[48:49], 0, v[132:133]
	global_load_lds_dwordx4 v[214:215], off
	v_lshl_add_u64 v[214:215], s[76:77], 0, v[134:135]
	s_add_i32 m0, s75, 0x2000
	s_nop 0
	global_load_lds_dwordx4 v[214:215], off
	v_lshl_add_u64 v[214:215], s[48:49], 0, v[128:129]
	s_mov_b32 m0, s62
	s_nop 0
	global_load_lds_dwordx4 v[214:215], off
	s_mov_b32 m0, s63
	s_nop 0
	global_load_lds_dwordx4 v[216:217], off
	s_waitcnt vmcnt(8)
	s_waitcnt lgkmcnt(0)
	s_barrier
; #define PG8_STAGE(bufoff, gbase, voff) do { _Pragma("unroll") for (int _i = 0; _i < 2; ++_i) \
;         __builtin_amdgcn_global_load_lds((const unsigned*)((const char*)(gbase) + (voff)[_i]), (LAS unsigned*)(lds + (bufoff) + ldsw + _i * 8192), 16, 0, 0); } while (0)
; #define PG8_LDA(dst, b, h) do { _Pragma("unroll") for (int m = 0; m < 4; ++m) _Pragma("unroll") for (int k = 0; k < 2; ++k) dst[m][k] = *(const LAS bf16x8*)(lds + PG8_SA(b, h) + aoff + m * 2048 + k * 1024); } while (0)
; #define PG8_LDB(dst, b, h) do { _Pragma("unroll") for (int n = 0; n < 2; ++n) _Pragma("unroll") for (int k = 0; k < 2; ++k) dst[n][k] = *(const LAS bf16x8*)(lds + PG8_SB(b, h) + boff + n * 2048 + k * 1024); } while (0)
; #define PG8_MMA(ai, bj, At, Bt) do { __builtin_amdgcn_s_setprio(1); _Pragma("unroll") for (int m = 0; m < 4; ++m) _Pragma("unroll") for (int n = 0; n < 2; ++n) _Pragma("unroll") for (int k = 0; k < 2; ++k) \
;         acc[ai][bj][m][n] = __builtin_amdgcn_mfma_f32_16x16x32_bf16(Bt[n][k], At[m][k], acc[ai][bj][m][n], 0, 0, 0); __builtin_amdgcn_s_setprio(0); } while (0)
; #define PG8_WAIT_V(n) asm volatile("s_waitcnt vmcnt(" #n ")" ::: "memory")
; #define PG8_WAIT_L(n) asm volatile("s_waitcnt lgkmcnt(" #n ")" ::: "memory")
; #define PG8_BAR __builtin_amdgcn_s_barrier()
; #define PG8_SCHED __builtin_amdgcn_sched_barrier(0)
; template <class Epi>
; DI void gemm_phase(int wv, LAS unsigned char* lds, LAS unsigned char* scr, const Sched& S, const Epi& E) {
;     ...
;             PG8_WAIT_V(8); PG8_WAIT_L(0); PG8_BAR; PG8_MMA(0, 0, At, B0); PG8_MMA(0, 1, At, B1); PG8_BAR; PG8_SCHED;
;             PG8_LDA(At, 0, 1); PG8_STAGE(PG8_SB(0, 0), b2, voffB); PG8_STAGE(PG8_SB(0, 1), b2 + hstepB, voffB); PG8_STAGE(PG8_SA(0, 0), a2, voffA);
;             PG8_WAIT_V(8); PG8_WAIT_L(0); PG8_BAR; PG8_MMA(1, 0, At, B0); PG8_MMA(1, 1, At, B1); PG8_BAR; PG8_SCHED;
;             PG8_LDB(B0, 1, 0); PG8_LDB(B1, 1, 1); PG8_SCHED; PG8_LDA(At, 1, 0); PG8_STAGE(PG8_SA(0, 1), a2 + hstepA, voffA);
;             PG8_WAIT_V(8); PG8_WAIT_L(0); PG8_BAR; PG8_MMA(0, 0, At, B0); PG8_MMA(0, 1, At, B1); PG8_BAR; PG8_SCHED;
	s_waitcnt lgkmcnt(0)
	v_mfma_f32_16x16x32_bf16 v[60:63], v[144:147], v[176:179], v[60:63]
	v_mfma_f32_16x16x32_bf16 v[56:59], v[152:155], v[176:179], v[56:59]
	v_mfma_f32_16x16x32_bf16 v[52:55], v[144:147], v[184:187], v[52:55]
	v_mfma_f32_16x16x32_bf16 v[48:51], v[152:155], v[184:187], v[48:51]
	v_mfma_f32_16x16x32_bf16 v[36:39], v[144:147], v[194:197], v[36:39]
	v_mfma_f32_16x16x32_bf16 v[32:35], v[152:155], v[194:197], v[32:35]
	v_mfma_f32_16x16x32_bf16 v[20:23], v[144:147], v[202:205], v[20:23]
	v_mfma_f32_16x16x32_bf16 v[16:19], v[152:155], v[202:205], v[16:19]
	v_mfma_f32_16x16x32_bf16 v[60:63], v[148:151], v[180:183], v[60:63]
	v_mfma_f32_16x16x32_bf16 v[56:59], v[156:159], v[180:183], v[56:59]
	v_mfma_f32_16x16x32_bf16 v[52:55], v[148:151], v[188:191], v[52:55]
	v_mfma_f32_16x16x32_bf16 v[48:51], v[156:159], v[188:191], v[48:51]
	v_mfma_f32_16x16x32_bf16 v[36:39], v[148:151], v[198:201], v[36:39]
	v_mfma_f32_16x16x32_bf16 v[32:35], v[156:159], v[198:201], v[32:35]
	v_mfma_f32_16x16x32_bf16 v[20:23], v[148:151], v[206:209], v[20:23]
	v_mfma_f32_16x16x32_bf16 v[16:19], v[156:159], v[206:209], v[16:19]
	v_mfma_f32_16x16x32_bf16 v[44:47], v[160:163], v[176:179], v[44:47]
	v_mfma_f32_16x16x32_bf16 v[40:43], v[168:171], v[176:179], v[40:43]
	v_mfma_f32_16x16x32_bf16 v[28:31], v[160:163], v[184:187], v[28:31]
	v_mfma_f32_16x16x32_bf16 v[24:27], v[168:171], v[184:187], v[24:27]
	v_mfma_f32_16x16x32_bf16 v[12:15], v[160:163], v[194:197], v[12:15]
	v_mfma_f32_16x16x32_bf16 v[8:11], v[168:171], v[194:197], v[8:11]
	v_mfma_f32_16x16x32_bf16 v[4:7], v[160:163], v[202:205], v[4:7]
	v_mfma_f32_16x16x32_bf16 v[0:3], v[168:171], v[202:205], v[0:3]
	v_mfma_f32_16x16x32_bf16 v[44:47], v[164:167], v[180:183], v[44:47]
	v_mfma_f32_16x16x32_bf16 v[40:43], v[172:175], v[180:183], v[40:43]
	v_mfma_f32_16x16x32_bf16 v[28:31], v[164:167], v[188:191], v[28:31]
	v_mfma_f32_16x16x32_bf16 v[24:27], v[172:175], v[188:191], v[24:27]
	v_mfma_f32_16x16x32_bf16 v[12:15], v[164:167], v[198:201], v[12:15]
	v_mfma_f32_16x16x32_bf16 v[8:11], v[172:175], v[198:201], v[8:11]
	v_mfma_f32_16x16x32_bf16 v[4:7], v[164:167], v[206:209], v[4:7]
	v_mfma_f32_16x16x32_bf16 v[0:3], v[172:175], v[206:209], v[0:3]
	s_barrier
	s_add_i32 s75, 0, 0x18000
	s_add_i32 s76, 0, 0x1c000
	v_add_u32_e32 v156, s75, v142
	v_add_u32_e32 v172, s76, v142
	ds_read_b128 v[144:147], v156
	ds_read_b128 v[148:151], v156 offset:1024
	ds_read_b128 v[152:155], v156 offset:2048
	ds_read_b128 v[156:159], v156 offset:3072
	ds_read_b128 v[160:163], v172
	ds_read_b128 v[164:167], v172 offset:1024
	ds_read_b128 v[168:171], v172 offset:2048
	ds_read_b128 v[172:175], v172 offset:3072
	s_add_u32 s48, s48, 0x40000
	s_addc_u32 s49, s49, 0
	s_mov_b32 m0, s64
	v_lshl_add_u64 v[218:219], s[48:49], 0, v[128:129]
	ds_read_b128 v[176:179], v143 offset:32768
	ds_read_b128 v[180:183], v143 offset:33792
	ds_read_b128 v[184:187], v143 offset:34816
	ds_read_b128 v[188:191], v143 offset:35840
	ds_read_b128 v[194:197], v143 offset:36864
	ds_read_b128 v[198:201], v143 offset:37888
	ds_read_b128 v[202:205], v143 offset:38912
	ds_read_b128 v[206:209], v143 offset:39936
	global_load_lds_dwordx4 v[218:219], off
	v_lshl_add_u64 v[218:219], s[48:49], 0, v[132:133]
	s_mov_b32 m0, s65
	s_nop 0
	global_load_lds_dwordx4 v[218:219], off
	s_waitcnt vmcnt(8)
	s_waitcnt lgkmcnt(0)
	s_barrier
	s_waitcnt lgkmcnt(0)
	v_mfma_f32_16x16x32_bf16 v[124:127], v[144:147], v[176:179], v[124:127]
	v_mfma_f32_16x16x32_bf16 v[120:123], v[152:155], v[176:179], v[120:123]
	v_mfma_f32_16x16x32_bf16 v[116:119], v[144:147], v[184:187], v[116:119]
	v_mfma_f32_16x16x32_bf16 v[112:115], v[152:155], v[184:187], v[112:115]
	v_mfma_f32_16x16x32_bf16 v[100:103], v[144:147], v[194:197], v[100:103]
	v_mfma_f32_16x16x32_bf16 v[96:99], v[152:155], v[194:197], v[96:99]
	v_mfma_f32_16x16x32_bf16 v[84:87], v[144:147], v[202:205], v[84:87]
	v_mfma_f32_16x16x32_bf16 v[80:83], v[152:155], v[202:205], v[80:83]
	v_mfma_f32_16x16x32_bf16 v[124:127], v[148:151], v[180:183], v[124:127]
	v_mfma_f32_16x16x32_bf16 v[120:123], v[156:159], v[180:183], v[120:123]
	v_mfma_f32_16x16x32_bf16 v[116:119], v[148:151], v[188:191], v[116:119]
	v_mfma_f32_16x16x32_bf16 v[112:115], v[156:159], v[188:191], v[112:115]
	v_mfma_f32_16x16x32_bf16 v[100:103], v[148:151], v[198:201], v[100:103]
	v_mfma_f32_16x16x32_bf16 v[96:99], v[156:159], v[198:201], v[96:99]
	v_mfma_f32_16x16x32_bf16 v[84:87], v[148:151], v[206:209], v[84:87]
	v_mfma_f32_16x16x32_bf16 v[80:83], v[156:159], v[206:209], v[80:83]
	v_mfma_f32_16x16x32_bf16 v[108:111], v[160:163], v[176:179], v[108:111]
	v_mfma_f32_16x16x32_bf16 v[104:107], v[168:171], v[176:179], v[104:107]
	v_mfma_f32_16x16x32_bf16 v[92:95], v[160:163], v[184:187], v[92:95]
	v_mfma_f32_16x16x32_bf16 v[88:91], v[168:171], v[184:187], v[88:91]
	v_mfma_f32_16x16x32_bf16 v[76:79], v[160:163], v[194:197], v[76:79]
	v_mfma_f32_16x16x32_bf16 v[72:75], v[168:171], v[194:197], v[72:75]
	v_mfma_f32_16x16x32_bf16 v[68:71], v[160:163], v[202:205], v[68:71]
	v_mfma_f32_16x16x32_bf16 v[64:67], v[168:171], v[202:205], v[64:67]
	v_mfma_f32_16x16x32_bf16 v[108:111], v[164:167], v[180:183], v[108:111]
	v_mfma_f32_16x16x32_bf16 v[104:107], v[172:175], v[180:183], v[104:107]
	v_mfma_f32_16x16x32_bf16 v[92:95], v[164:167], v[188:191], v[92:95]
	v_mfma_f32_16x16x32_bf16 v[88:91], v[172:175], v[188:191], v[88:91]
	v_mfma_f32_16x16x32_bf16 v[76:79], v[164:167], v[198:201], v[76:79]
	v_mfma_f32_16x16x32_bf16 v[72:75], v[172:175], v[198:201], v[72:75]
	v_mfma_f32_16x16x32_bf16 v[68:71], v[164:167], v[206:209], v[68:71]
	v_mfma_f32_16x16x32_bf16 v[64:67], v[172:175], v[206:209], v[64:67]
	s_barrier
; #define PG8_STAGE(bufoff, gbase, voff) do { _Pragma("unroll") for (int _i = 0; _i < 2; ++_i) \
;         __builtin_amdgcn_global_load_lds((const unsigned*)((const char*)(gbase) + (voff)[_i]), (LAS unsigned*)(lds + (bufoff) + ldsw + _i * 8192), 16, 0, 0); } while (0)
; #define PG8_LDA(dst, b, h) do { _Pragma("unroll") for (int m = 0; m < 4; ++m) _Pragma("unroll") for (int k = 0; k < 2; ++k) dst[m][k] = *(const LAS bf16x8*)(lds + PG8_SA(b, h) + aoff + m * 2048 + k * 1024); } while (0)
; #define PG8_MMA(ai, bj, At, Bt) do { __builtin_amdgcn_s_setprio(1); _Pragma("unroll") for (int m = 0; m < 4; ++m) _Pragma("unroll") for (int n = 0; n < 2; ++n) _Pragma("unroll") for (int k = 0; k < 2; ++k) \
;         acc[ai][bj][m][n] = __builtin_amdgcn_mfma_f32_16x16x32_bf16(Bt[n][k], At[m][k], acc[ai][bj][m][n], 0, 0, 0); __builtin_amdgcn_s_setprio(0); } while (0)
; #define PG8_WAIT_V(n) asm volatile("s_waitcnt vmcnt(" #n ")" ::: "memory")
; #define PG8_WAIT_L(n) asm volatile("s_waitcnt lgkmcnt(" #n ")" ::: "memory")
; #define PG8_BAR __builtin_amdgcn_s_barrier()
; #define PG8_SCHED __builtin_amdgcn_sched_barrier(0)
; template <class Epi>
; DI void gemm_phase(int wv, LAS unsigned char* lds, LAS unsigned char* scr, const Sched& S, const Epi& E) {
;     ...
;             PG8_LDA(At, 1, 1); PG8_STAGE(PG8_SB(1, 0), b3, voffB); PG8_STAGE(PG8_SB(1, 1), b3 + hstepB, voffB); PG8_STAGE(PG8_SA(1, 0), a3, voffA);
;             PG8_WAIT_V(8); PG8_WAIT_L(0); PG8_BAR; PG8_MMA(1, 0, At, B0); PG8_MMA(1, 1, At, B1); PG8_BAR; PG8_SCHED;
;         }
;         if (wr == 0) PG8_BAR;
	s_add_i32 s48, s75, s60
	v_lshl_add_u64 v[210:211], v[210:211], 0, s[2:3]
	s_mov_b32 m0, s48
	ds_read_b128 v[176:179], v143 offset:49152
	ds_read_b128 v[180:183], v143 offset:50176
	ds_read_b128 v[184:187], v143 offset:51200
	ds_read_b128 v[188:191], v143 offset:52224
	ds_read_b128 v[194:197], v143 offset:53248
	ds_read_b128 v[198:201], v143 offset:54272
	ds_read_b128 v[202:205], v143 offset:55296
	ds_read_b128 v[206:209], v143 offset:56320
	global_load_lds_dwordx4 v[210:211], off
	s_add_i32 m0, s48, 0x2000
	s_add_u32 s46, s46, 0x40080
	v_lshl_add_u64 v[210:211], v[212:213], 0, s[2:3]
	s_addc_u32 s47, s47, 0
	s_add_i32 s48, s76, s60
	global_load_lds_dwordx4 v[210:211], off
	v_lshl_add_u64 v[210:211], s[46:47], 0, v[130:131]
	s_mov_b32 m0, s48
	s_nop 0
	global_load_lds_dwordx4 v[210:211], off
	v_lshl_add_u64 v[210:211], s[46:47], 0, v[134:135]
	s_add_i32 m0, s48, 0x2000
	s_nop 0
	global_load_lds_dwordx4 v[210:211], off
	v_lshl_add_u64 v[210:211], v[214:215], 0, s[2:3]
	s_mov_b32 m0, s66
	s_nop 0
	global_load_lds_dwordx4 v[210:211], off
	v_lshl_add_u64 v[210:211], v[216:217], 0, s[2:3]
	s_mov_b32 m0, s67
	s_nop 0
	global_load_lds_dwordx4 v[210:211], off
	s_waitcnt vmcnt(8)
	s_waitcnt lgkmcnt(0)
	s_barrier
	s_waitcnt lgkmcnt(0)
	v_mfma_f32_16x16x32_bf16 v[60:63], v[144:147], v[176:179], v[60:63]
	v_mfma_f32_16x16x32_bf16 v[56:59], v[152:155], v[176:179], v[56:59]
	v_mfma_f32_16x16x32_bf16 v[52:55], v[144:147], v[184:187], v[52:55]
	v_mfma_f32_16x16x32_bf16 v[48:51], v[152:155], v[184:187], v[48:51]
	v_mfma_f32_16x16x32_bf16 v[36:39], v[144:147], v[194:197], v[36:39]
	v_mfma_f32_16x16x32_bf16 v[32:35], v[152:155], v[194:197], v[32:35]
	v_mfma_f32_16x16x32_bf16 v[20:23], v[144:147], v[202:205], v[20:23]
	v_mfma_f32_16x16x32_bf16 v[16:19], v[152:155], v[202:205], v[16:19]
	v_mfma_f32_16x16x32_bf16 v[60:63], v[148:151], v[180:183], v[60:63]
	v_mfma_f32_16x16x32_bf16 v[56:59], v[156:159], v[180:183], v[56:59]
	v_mfma_f32_16x16x32_bf16 v[52:55], v[148:151], v[188:191], v[52:55]
	v_mfma_f32_16x16x32_bf16 v[48:51], v[156:159], v[188:191], v[48:51]
	v_mfma_f32_16x16x32_bf16 v[36:39], v[148:151], v[198:201], v[36:39]
	v_mfma_f32_16x16x32_bf16 v[32:35], v[156:159], v[198:201], v[32:35]
	v_mfma_f32_16x16x32_bf16 v[20:23], v[148:151], v[206:209], v[20:23]
	v_mfma_f32_16x16x32_bf16 v[16:19], v[156:159], v[206:209], v[16:19]
	v_mfma_f32_16x16x32_bf16 v[44:47], v[160:163], v[176:179], v[44:47]
	v_mfma_f32_16x16x32_bf16 v[40:43], v[168:171], v[176:179], v[40:43]
	v_mfma_f32_16x16x32_bf16 v[28:31], v[160:163], v[184:187], v[28:31]
	v_mfma_f32_16x16x32_bf16 v[24:27], v[168:171], v[184:187], v[24:27]
	v_mfma_f32_16x16x32_bf16 v[12:15], v[160:163], v[194:197], v[12:15]
	v_mfma_f32_16x16x32_bf16 v[8:11], v[168:171], v[194:197], v[8:11]
	v_mfma_f32_16x16x32_bf16 v[4:7], v[160:163], v[202:205], v[4:7]
	v_mfma_f32_16x16x32_bf16 v[0:3], v[168:171], v[202:205], v[0:3]
	v_mfma_f32_16x16x32_bf16 v[44:47], v[164:167], v[180:183], v[44:47]
	v_mfma_f32_16x16x32_bf16 v[40:43], v[172:175], v[180:183], v[40:43]
	v_mfma_f32_16x16x32_bf16 v[28:31], v[164:167], v[188:191], v[28:31]
	v_mfma_f32_16x16x32_bf16 v[24:27], v[172:175], v[188:191], v[24:27]
	v_mfma_f32_16x16x32_bf16 v[12:15], v[164:167], v[198:201], v[12:15]
	v_mfma_f32_16x16x32_bf16 v[8:11], v[172:175], v[198:201], v[8:11]
	v_mfma_f32_16x16x32_bf16 v[4:7], v[164:167], v[206:209], v[4:7]
	v_mfma_f32_16x16x32_bf16 v[0:3], v[172:175], v[206:209], v[0:3]
	s_barrier
	s_add_i32 s74, s74, 2
	s_add_u32 s72, s72, 0x100
	s_addc_u32 s73, s73, 0
	s_add_u32 s44, s44, 0x100
	s_addc_u32 s45, s45, 0
	s_cmp_gt_u32 s74, 13
	s_cbranch_scc0 .LBB0_113
	s_and_b64 vcc, exec, s[14:15]
	s_movk_i32 s74, 0x4000
	s_mov_b64 s[72:73], s[92:93]
	s_cbranch_vccz .LBB0_116
	s_barrier

; #define PG8_STAGE(bufoff, gbase, voff) do { _Pragma("unroll") for (int _i = 0; _i < 2; ++_i) \
;         __builtin_amdgcn_global_load_lds((const unsigned*)((const char*)(gbase) + (voff)[_i]), (LAS unsigned*)(lds + (bufoff) + ldsw + _i * 8192), 16, 0, 0); } while (0)
; #define PG8_LDA(dst, b, h) do { _Pragma("unroll") for (int m = 0; m < 4; ++m) _Pragma("unroll") for (int k = 0; k < 2; ++k) dst[m][k] = *(const LAS bf16x8*)(lds + PG8_SA(b, h) + aoff + m * 2048 + k * 1024); } while (0)
; #define PG8_LDB(dst, b, h) do { _Pragma("unroll") for (int n = 0; n < 2; ++n) _Pragma("unroll") for (int k = 0; k < 2; ++k) dst[n][k] = *(const LAS bf16x8*)(lds + PG8_SB(b, h) + boff + n * 2048 + k * 1024); } while (0)
; #define PG8_MMA(ai, bj, At, Bt) do { __builtin_amdgcn_s_setprio(1); _Pragma("unroll") for (int m = 0; m < 4; ++m) _Pragma("unroll") for (int n = 0; n < 2; ++n) _Pragma("unroll") for (int k = 0; k < 2; ++k) \
;         acc[ai][bj][m][n] = __builtin_amdgcn_mfma_f32_16x16x32_bf16(Bt[n][k], At[m][k], acc[ai][bj][m][n], 0, 0, 0); __builtin_amdgcn_s_setprio(0); } while (0)
; #define PG8_WAIT_V(n) asm volatile("s_waitcnt vmcnt(" #n ")" ::: "memory")
; #define PG8_WAIT_L(n) asm volatile("s_waitcnt lgkmcnt(" #n ")" ::: "memory")
; #define PG8_BAR __builtin_amdgcn_s_barrier()
; #define PG8_SCHED __builtin_amdgcn_sched_barrier(0)
; template <class Epi>
; DI void gemm_phase(int wv, LAS unsigned char* lds, LAS unsigned char* scr, const Sched& S, const Epi& E) {
;     ...
;         for (int t = 0; t < nt; t += 2) {
;             const bool last = (t == nt - 2);
;             const char* a1 = cA + (size_t)(t + 1) * kstep;
;             const char* a2 = last ? nA : cA + (size_t)(t + 2) * kstep; const char* b2 = last ? nB : cB + (size_t)(t + 2) * kstep;
;             const char* a3 = a2 + kstep; const char* b3 = b2 + kstep;
;             PG8_LDB(B0, 0, 0); PG8_LDB(B1, 0, 1); PG8_SCHED; PG8_LDA(At, 0, 0); PG8_STAGE(PG8_SA(1, 1), a1 + hstepA, voffA);
;             PG8_WAIT_V(8); PG8_WAIT_L(0); PG8_BAR; PG8_MMA(0, 0, At, B0); PG8_MMA(0, 1, At, B1); PG8_BAR; PG8_SCHED;
;             PG8_LDA(At, 0, 1); PG8_STAGE(PG8_SB(0, 0), b2, voffB); PG8_STAGE(PG8_SB(0, 1), b2 + hstepB, voffB); PG8_STAGE(PG8_SA(0, 0), a2, voffA);
;             PG8_WAIT_V(8); PG8_WAIT_L(0); PG8_BAR; PG8_MMA(1, 0, At, B0); PG8_MMA(1, 1, At, B1); PG8_BAR; PG8_SCHED;
.LBB0_137:
	s_add_u32 s34, s30, 0xfffc0080
	s_addc_u32 s35, s31, -1
	s_add_i32 s65, 0, 0x10000
	s_cmp_eq_u32 s64, 12
	s_cselect_b32 s37, s25, s35
	s_cselect_b32 s36, s60, s34
	v_add_u32_e32 v143, s65, v140
	s_cselect_b32 s35, s23, s63
	s_cselect_b32 s34, s61, s62
	s_add_i32 s68, 0, 0x14000
	ds_read_b128 v[144:147], v143
	ds_read_b128 v[148:151], v143 offset:1024
	ds_read_b128 v[152:155], v143 offset:2048
	ds_read_b128 v[156:159], v143 offset:3072
	v_add_u32_e32 v143, s68, v140
	ds_read_b128 v[160:163], v143
	ds_read_b128 v[164:167], v143 offset:1024
	ds_read_b128 v[168:171], v143 offset:2048
	ds_read_b128 v[172:175], v143 offset:3072
	v_lshl_add_u64 v[210:211], s[30:31], 0, v[138:139]
	s_add_i32 m0, s17, 0xc000
	ds_read_b128 v[176:179], v142
	ds_read_b128 v[180:183], v142 offset:1024
	ds_read_b128 v[184:187], v142 offset:2048
	ds_read_b128 v[188:191], v142 offset:3072
	ds_read_b128 v[194:197], v142 offset:4096
	ds_read_b128 v[198:201], v142 offset:5120
	ds_read_b128 v[202:205], v142 offset:6144
	ds_read_b128 v[206:209], v142 offset:7168
	global_load_lds_dwordx4 v[210:211], off
	v_lshl_add_u64 v[210:211], s[30:31], 0, v[136:137]
	s_add_i32 m0, s17, 0xe000
	s_nop 0
	global_load_lds_dwordx4 v[210:211], off
	s_waitcnt vmcnt(8)
	s_waitcnt lgkmcnt(0)
	s_barrier
	s_waitcnt lgkmcnt(0)
	v_mfma_f32_16x16x32_bf16 v[124:127], v[144:147], v[176:179], v[124:127]
	v_mfma_f32_16x16x32_bf16 v[120:123], v[152:155], v[176:179], v[120:123]
	v_mfma_f32_16x16x32_bf16 v[116:119], v[144:147], v[184:187], v[116:119]
	v_mfma_f32_16x16x32_bf16 v[112:115], v[152:155], v[184:187], v[112:115]
	v_mfma_f32_16x16x32_bf16 v[100:103], v[144:147], v[194:197], v[100:103]
	v_mfma_f32_16x16x32_bf16 v[96:99], v[152:155], v[194:197], v[96:99]
	v_mfma_f32_16x16x32_bf16 v[84:87], v[144:147], v[202:205], v[84:87]
	v_mfma_f32_16x16x32_bf16 v[80:83], v[152:155], v[202:205], v[80:83]
	v_mfma_f32_16x16x32_bf16 v[124:127], v[148:151], v[180:183], v[124:127]
	v_mfma_f32_16x16x32_bf16 v[120:123], v[156:159], v[180:183], v[120:123]
	v_mfma_f32_16x16x32_bf16 v[116:119], v[148:151], v[188:191], v[116:119]
	v_mfma_f32_16x16x32_bf16 v[112:115], v[156:159], v[188:191], v[112:115]
	v_mfma_f32_16x16x32_bf16 v[100:103], v[148:151], v[198:201], v[100:103]
	v_mfma_f32_16x16x32_bf16 v[96:99], v[156:159], v[198:201], v[96:99]
	v_mfma_f32_16x16x32_bf16 v[84:87], v[148:151], v[206:209], v[84:87]
	v_mfma_f32_16x16x32_bf16 v[80:83], v[156:159], v[206:209], v[80:83]
	v_mfma_f32_16x16x32_bf16 v[108:111], v[160:163], v[176:179], v[108:111]
	v_mfma_f32_16x16x32_bf16 v[104:107], v[168:171], v[176:179], v[104:107]
	v_mfma_f32_16x16x32_bf16 v[92:95], v[160:163], v[184:187], v[92:95]
	v_mfma_f32_16x16x32_bf16 v[88:91], v[168:171], v[184:187], v[88:91]
	v_mfma_f32_16x16x32_bf16 v[76:79], v[160:163], v[194:197], v[76:79]
	v_mfma_f32_16x16x32_bf16 v[72:75], v[168:171], v[194:197], v[72:75]
	v_mfma_f32_16x16x32_bf16 v[68:71], v[160:163], v[202:205], v[68:71]
	v_mfma_f32_16x16x32_bf16 v[64:67], v[168:171], v[202:205], v[64:67]
	v_mfma_f32_16x16x32_bf16 v[108:111], v[164:167], v[180:183], v[108:111]
	v_mfma_f32_16x16x32_bf16 v[104:107], v[172:175], v[180:183], v[104:107]
	v_mfma_f32_16x16x32_bf16 v[92:95], v[164:167], v[188:191], v[92:95]
	v_mfma_f32_16x16x32_bf16 v[88:91], v[172:175], v[188:191], v[88:91]
	v_mfma_f32_16x16x32_bf16 v[76:79], v[164:167], v[198:201], v[76:79]
	v_mfma_f32_16x16x32_bf16 v[72:75], v[172:175], v[198:201], v[72:75]
	v_mfma_f32_16x16x32_bf16 v[68:71], v[164:167], v[206:209], v[68:71]
	v_mfma_f32_16x16x32_bf16 v[64:67], v[172:175], v[206:209], v[64:67]
	s_barrier
	s_add_i32 s65, s65, s39
	v_lshl_add_u64 v[210:211], s[34:35], 0, v[192:193]
	s_mov_b32 m0, s65
	ds_read_b128 v[176:179], v142 offset:16384
	ds_read_b128 v[180:183], v142 offset:17408
	ds_read_b128 v[184:187], v142 offset:18432
	ds_read_b128 v[188:191], v142 offset:19456
	ds_read_b128 v[194:197], v142 offset:20480
	ds_read_b128 v[198:201], v142 offset:21504
	ds_read_b128 v[202:205], v142 offset:22528
	ds_read_b128 v[206:209], v142 offset:23552
	global_load_lds_dwordx4 v[210:211], off
	s_add_i32 m0, s65, 0x2000
	s_add_u32 s66, s34, 0x40000
	v_lshl_add_u64 v[212:213], s[34:35], 0, v[132:133]
	s_addc_u32 s67, s35, 0
	s_add_i32 s65, s68, s39
	global_load_lds_dwordx4 v[212:213], off
	v_lshl_add_u64 v[214:215], s[66:67], 0, v[192:193]
	s_mov_b32 m0, s65
	v_lshl_add_u64 v[216:217], s[36:37], 0, v[130:131]
	global_load_lds_dwordx4 v[214:215], off
	v_lshl_add_u64 v[214:215], s[66:67], 0, v[132:133]
	s_add_i32 m0, s65, 0x2000
	s_nop 0
	global_load_lds_dwordx4 v[214:215], off
	v_lshl_add_u64 v[214:215], s[36:37], 0, v[128:129]
	s_mov_b32 m0, s17
	s_nop 0
	global_load_lds_dwordx4 v[214:215], off
	s_mov_b32 m0, s21
	s_nop 0
	global_load_lds_dwordx4 v[216:217], off
	s_waitcnt vmcnt(8)
	s_waitcnt lgkmcnt(0)
	s_barrier
; #define PG8_STAGE(bufoff, gbase, voff) do { _Pragma("unroll") for (int _i = 0; _i < 2; ++_i) \
;         __builtin_amdgcn_global_load_lds((const unsigned*)((const char*)(gbase) + (voff)[_i]), (LAS unsigned*)(lds + (bufoff) + ldsw + _i * 8192), 16, 0, 0); } while (0)
; #define PG8_LDA(dst, b, h) do { _Pragma("unroll") for (int m = 0; m < 4; ++m) _Pragma("unroll") for (int k = 0; k < 2; ++k) dst[m][k] = *(const LAS bf16x8*)(lds + PG8_SA(b, h) + aoff + m * 2048 + k * 1024); } while (0)
; #define PG8_LDB(dst, b, h) do { _Pragma("unroll") for (int n = 0; n < 2; ++n) _Pragma("unroll") for (int k = 0; k < 2; ++k) dst[n][k] = *(const LAS bf16x8*)(lds + PG8_SB(b, h) + boff + n * 2048 + k * 1024); } while (0)
; #define PG8_MMA(ai, bj, At, Bt) do { __builtin_amdgcn_s_setprio(1); _Pragma("unroll") for (int m = 0; m < 4; ++m) _Pragma("unroll") for (int n = 0; n < 2; ++n) _Pragma("unroll") for (int k = 0; k < 2; ++k) \
;         acc[ai][bj][m][n] = __builtin_amdgcn_mfma_f32_16x16x32_bf16(Bt[n][k], At[m][k], acc[ai][bj][m][n], 0, 0, 0); __builtin_amdgcn_s_setprio(0); } while (0)
; #define PG8_WAIT_V(n) asm volatile("s_waitcnt vmcnt(" #n ")" ::: "memory")
; #define PG8_WAIT_L(n) asm volatile("s_waitcnt lgkmcnt(" #n ")" ::: "memory")
; #define PG8_BAR __builtin_amdgcn_s_barrier()
; #define PG8_SCHED __builtin_amdgcn_sched_barrier(0)
; template <class Epi>
; DI void gemm_phase(int wv, LAS unsigned char* lds, LAS unsigned char* scr, const Sched& S, const Epi& E) {
;     ...
;             PG8_WAIT_V(8); PG8_WAIT_L(0); PG8_BAR; PG8_MMA(0, 0, At, B0); PG8_MMA(0, 1, At, B1); PG8_BAR; PG8_SCHED;
;             PG8_LDA(At, 0, 1); PG8_STAGE(PG8_SB(0, 0), b2, voffB); PG8_STAGE(PG8_SB(0, 1), b2 + hstepB, voffB); PG8_STAGE(PG8_SA(0, 0), a2, voffA);
;             PG8_WAIT_V(8); PG8_WAIT_L(0); PG8_BAR; PG8_MMA(1, 0, At, B0); PG8_MMA(1, 1, At, B1); PG8_BAR; PG8_SCHED;
;             PG8_LDB(B0, 1, 0); PG8_LDB(B1, 1, 1); PG8_SCHED; PG8_LDA(At, 1, 0); PG8_STAGE(PG8_SA(0, 1), a2 + hstepA, voffA);
;             PG8_WAIT_V(8); PG8_WAIT_L(0); PG8_BAR; PG8_MMA(0, 0, At, B0); PG8_MMA(0, 1, At, B1); PG8_BAR; PG8_SCHED;
	s_waitcnt lgkmcnt(0)
	v_mfma_f32_16x16x32_bf16 v[60:63], v[144:147], v[176:179], v[60:63]
	v_mfma_f32_16x16x32_bf16 v[56:59], v[152:155], v[176:179], v[56:59]
	v_mfma_f32_16x16x32_bf16 v[52:55], v[144:147], v[184:187], v[52:55]
	v_mfma_f32_16x16x32_bf16 v[48:51], v[152:155], v[184:187], v[48:51]
	v_mfma_f32_16x16x32_bf16 v[36:39], v[144:147], v[194:197], v[36:39]
	v_mfma_f32_16x16x32_bf16 v[32:35], v[152:155], v[194:197], v[32:35]
	v_mfma_f32_16x16x32_bf16 v[20:23], v[144:147], v[202:205], v[20:23]
	v_mfma_f32_16x16x32_bf16 v[16:19], v[152:155], v[202:205], v[16:19]
	v_mfma_f32_16x16x32_bf16 v[60:63], v[148:151], v[180:183], v[60:63]
	v_mfma_f32_16x16x32_bf16 v[56:59], v[156:159], v[180:183], v[56:59]
	v_mfma_f32_16x16x32_bf16 v[52:55], v[148:151], v[188:191], v[52:55]
	v_mfma_f32_16x16x32_bf16 v[48:51], v[156:159], v[188:191], v[48:51]
	v_mfma_f32_16x16x32_bf16 v[36:39], v[148:151], v[198:201], v[36:39]
	v_mfma_f32_16x16x32_bf16 v[32:35], v[156:159], v[198:201], v[32:35]
	v_mfma_f32_16x16x32_bf16 v[20:23], v[148:151], v[206:209], v[20:23]
	v_mfma_f32_16x16x32_bf16 v[16:19], v[156:159], v[206:209], v[16:19]
	v_mfma_f32_16x16x32_bf16 v[44:47], v[160:163], v[176:179], v[44:47]
	v_mfma_f32_16x16x32_bf16 v[40:43], v[168:171], v[176:179], v[40:43]
	v_mfma_f32_16x16x32_bf16 v[28:31], v[160:163], v[184:187], v[28:31]
	v_mfma_f32_16x16x32_bf16 v[24:27], v[168:171], v[184:187], v[24:27]
	v_mfma_f32_16x16x32_bf16 v[12:15], v[160:163], v[194:197], v[12:15]
	v_mfma_f32_16x16x32_bf16 v[8:11], v[168:171], v[194:197], v[8:11]
	v_mfma_f32_16x16x32_bf16 v[4:7], v[160:163], v[202:205], v[4:7]
	v_mfma_f32_16x16x32_bf16 v[0:3], v[168:171], v[202:205], v[0:3]
	v_mfma_f32_16x16x32_bf16 v[44:47], v[164:167], v[180:183], v[44:47]
	v_mfma_f32_16x16x32_bf16 v[40:43], v[172:175], v[180:183], v[40:43]
	v_mfma_f32_16x16x32_bf16 v[28:31], v[164:167], v[188:191], v[28:31]
	v_mfma_f32_16x16x32_bf16 v[24:27], v[172:175], v[188:191], v[24:27]
	v_mfma_f32_16x16x32_bf16 v[12:15], v[164:167], v[198:201], v[12:15]
	v_mfma_f32_16x16x32_bf16 v[8:11], v[172:175], v[198:201], v[8:11]
	v_mfma_f32_16x16x32_bf16 v[4:7], v[164:167], v[206:209], v[4:7]
	v_mfma_f32_16x16x32_bf16 v[0:3], v[172:175], v[206:209], v[0:3]
	s_barrier
	s_add_i32 s65, 0, 0x18000
	v_add_u32_e32 v143, s65, v140
	s_add_i32 s66, 0, 0x1c000
	ds_read_b128 v[144:147], v143
	ds_read_b128 v[148:151], v143 offset:1024
	ds_read_b128 v[152:155], v143 offset:2048
	ds_read_b128 v[156:159], v143 offset:3072
	v_add_u32_e32 v143, s66, v140
	ds_read_b128 v[160:163], v143
	ds_read_b128 v[164:167], v143 offset:1024
	ds_read_b128 v[168:171], v143 offset:2048
	ds_read_b128 v[172:175], v143 offset:3072
	s_add_u32 s36, s36, 0x40000
	s_addc_u32 s37, s37, 0
	s_mov_b32 m0, s42
	v_lshl_add_u64 v[218:219], s[36:37], 0, v[128:129]
	ds_read_b128 v[176:179], v142 offset:32768
	ds_read_b128 v[180:183], v142 offset:33792
	ds_read_b128 v[184:187], v142 offset:34816
	ds_read_b128 v[188:191], v142 offset:35840
	ds_read_b128 v[194:197], v142 offset:36864
	ds_read_b128 v[198:201], v142 offset:37888
	ds_read_b128 v[202:205], v142 offset:38912
	ds_read_b128 v[206:209], v142 offset:39936
	global_load_lds_dwordx4 v[218:219], off
	v_lshl_add_u64 v[218:219], s[36:37], 0, v[130:131]
	s_mov_b32 m0, s43
	s_nop 0
	global_load_lds_dwordx4 v[218:219], off
	s_waitcnt vmcnt(8)
	s_waitcnt lgkmcnt(0)
	s_barrier
	s_waitcnt lgkmcnt(0)
	v_mfma_f32_16x16x32_bf16 v[124:127], v[144:147], v[176:179], v[124:127]
	v_mfma_f32_16x16x32_bf16 v[120:123], v[152:155], v[176:179], v[120:123]
	v_mfma_f32_16x16x32_bf16 v[116:119], v[144:147], v[184:187], v[116:119]
	v_mfma_f32_16x16x32_bf16 v[112:115], v[152:155], v[184:187], v[112:115]
	v_mfma_f32_16x16x32_bf16 v[100:103], v[144:147], v[194:197], v[100:103]
	v_mfma_f32_16x16x32_bf16 v[96:99], v[152:155], v[194:197], v[96:99]
	v_mfma_f32_16x16x32_bf16 v[84:87], v[144:147], v[202:205], v[84:87]
	v_mfma_f32_16x16x32_bf16 v[80:83], v[152:155], v[202:205], v[80:83]
	v_mfma_f32_16x16x32_bf16 v[124:127], v[148:151], v[180:183], v[124:127]
	v_mfma_f32_16x16x32_bf16 v[120:123], v[156:159], v[180:183], v[120:123]
	v_mfma_f32_16x16x32_bf16 v[116:119], v[148:151], v[188:191], v[116:119]
	v_mfma_f32_16x16x32_bf16 v[112:115], v[156:159], v[188:191], v[112:115]
	v_mfma_f32_16x16x32_bf16 v[100:103], v[148:151], v[198:201], v[100:103]
	v_mfma_f32_16x16x32_bf16 v[96:99], v[156:159], v[198:201], v[96:99]
	v_mfma_f32_16x16x32_bf16 v[84:87], v[148:151], v[206:209], v[84:87]
	v_mfma_f32_16x16x32_bf16 v[80:83], v[156:159], v[206:209], v[80:83]
	v_mfma_f32_16x16x32_bf16 v[108:111], v[160:163], v[176:179], v[108:111]
	v_mfma_f32_16x16x32_bf16 v[104:107], v[168:171], v[176:179], v[104:107]
	v_mfma_f32_16x16x32_bf16 v[92:95], v[160:163], v[184:187], v[92:95]
	v_mfma_f32_16x16x32_bf16 v[88:91], v[168:171], v[184:187], v[88:91]
	v_mfma_f32_16x16x32_bf16 v[76:79], v[160:163], v[194:197], v[76:79]
	v_mfma_f32_16x16x32_bf16 v[72:75], v[168:171], v[194:197], v[72:75]
	v_mfma_f32_16x16x32_bf16 v[68:71], v[160:163], v[202:205], v[68:71]
	v_mfma_f32_16x16x32_bf16 v[64:67], v[168:171], v[202:205], v[64:67]
	v_mfma_f32_16x16x32_bf16 v[108:111], v[164:167], v[180:183], v[108:111]
	v_mfma_f32_16x16x32_bf16 v[104:107], v[172:175], v[180:183], v[104:107]
	v_mfma_f32_16x16x32_bf16 v[92:95], v[164:167], v[188:191], v[92:95]
	v_mfma_f32_16x16x32_bf16 v[88:91], v[172:175], v[188:191], v[88:91]
	v_mfma_f32_16x16x32_bf16 v[76:79], v[164:167], v[198:201], v[76:79]
	v_mfma_f32_16x16x32_bf16 v[72:75], v[172:175], v[198:201], v[72:75]
	v_mfma_f32_16x16x32_bf16 v[68:71], v[164:167], v[206:209], v[68:71]
	v_mfma_f32_16x16x32_bf16 v[64:67], v[172:175], v[206:209], v[64:67]
	s_barrier
; #define PG8_STAGE(bufoff, gbase, voff) do { _Pragma("unroll") for (int _i = 0; _i < 2; ++_i) \
;         __builtin_amdgcn_global_load_lds((const unsigned*)((const char*)(gbase) + (voff)[_i]), (LAS unsigned*)(lds + (bufoff) + ldsw + _i * 8192), 16, 0, 0); } while (0)
; #define PG8_LDA(dst, b, h) do { _Pragma("unroll") for (int m = 0; m < 4; ++m) _Pragma("unroll") for (int k = 0; k < 2; ++k) dst[m][k] = *(const LAS bf16x8*)(lds + PG8_SA(b, h) + aoff + m * 2048 + k * 1024); } while (0)
; #define PG8_MMA(ai, bj, At, Bt) do { __builtin_amdgcn_s_setprio(1); _Pragma("unroll") for (int m = 0; m < 4; ++m) _Pragma("unroll") for (int n = 0; n < 2; ++n) _Pragma("unroll") for (int k = 0; k < 2; ++k) \
;         acc[ai][bj][m][n] = __builtin_amdgcn_mfma_f32_16x16x32_bf16(Bt[n][k], At[m][k], acc[ai][bj][m][n], 0, 0, 0); __builtin_amdgcn_s_setprio(0); } while (0)
; #define PG8_WAIT_V(n) asm volatile("s_waitcnt vmcnt(" #n ")" ::: "memory")
; #define PG8_WAIT_L(n) asm volatile("s_waitcnt lgkmcnt(" #n ")" ::: "memory")
; #define PG8_BAR __builtin_amdgcn_s_barrier()
; #define PG8_SCHED __builtin_amdgcn_sched_barrier(0)
; template <class Epi>
; DI void gemm_phase(int wv, LAS unsigned char* lds, LAS unsigned char* scr, const Sched& S, const Epi& E) {
;     ...
;             PG8_LDA(At, 1, 1); PG8_STAGE(PG8_SB(1, 0), b3, voffB); PG8_STAGE(PG8_SB(1, 1), b3 + hstepB, voffB); PG8_STAGE(PG8_SA(1, 0), a3, voffA);
;             PG8_WAIT_V(8); PG8_WAIT_L(0); PG8_BAR; PG8_MMA(1, 0, At, B0); PG8_MMA(1, 1, At, B1); PG8_BAR; PG8_SCHED;
;         }
;         if (wr == 0) PG8_BAR;
	s_add_i32 s36, s65, s39
	v_lshl_add_u64 v[210:211], v[210:211], 0, s[2:3]
	s_mov_b32 m0, s36
	ds_read_b128 v[176:179], v142 offset:49152
	ds_read_b128 v[180:183], v142 offset:50176
	ds_read_b128 v[184:187], v142 offset:51200
	ds_read_b128 v[188:191], v142 offset:52224
	ds_read_b128 v[194:197], v142 offset:53248
	ds_read_b128 v[198:201], v142 offset:54272
	ds_read_b128 v[202:205], v142 offset:55296
	ds_read_b128 v[206:209], v142 offset:56320
	global_load_lds_dwordx4 v[210:211], off
	s_add_i32 m0, s36, 0x2000
	s_add_u32 s34, s34, 0x40080
	v_lshl_add_u64 v[210:211], v[212:213], 0, s[2:3]
	s_addc_u32 s35, s35, 0
	s_add_i32 s36, s66, s39
	global_load_lds_dwordx4 v[210:211], off
	v_lshl_add_u64 v[210:211], s[34:35], 0, v[192:193]
	s_mov_b32 m0, s36
	s_nop 0
	global_load_lds_dwordx4 v[210:211], off
	v_lshl_add_u64 v[210:211], s[34:35], 0, v[132:133]
	s_add_i32 m0, s36, 0x2000
	s_nop 0
	global_load_lds_dwordx4 v[210:211], off
	v_lshl_add_u64 v[210:211], v[214:215], 0, s[2:3]
	s_mov_b32 m0, s44
	s_nop 0
	global_load_lds_dwordx4 v[210:211], off
	v_lshl_add_u64 v[210:211], v[216:217], 0, s[2:3]
	s_mov_b32 m0, s45
	s_nop 0
	global_load_lds_dwordx4 v[210:211], off
	s_waitcnt vmcnt(8)
	s_waitcnt lgkmcnt(0)
	s_barrier
	s_waitcnt lgkmcnt(0)
	v_mfma_f32_16x16x32_bf16 v[60:63], v[144:147], v[176:179], v[60:63]
	v_mfma_f32_16x16x32_bf16 v[56:59], v[152:155], v[176:179], v[56:59]
	v_mfma_f32_16x16x32_bf16 v[52:55], v[144:147], v[184:187], v[52:55]
	v_mfma_f32_16x16x32_bf16 v[48:51], v[152:155], v[184:187], v[48:51]
	v_mfma_f32_16x16x32_bf16 v[36:39], v[144:147], v[194:197], v[36:39]
	v_mfma_f32_16x16x32_bf16 v[32:35], v[152:155], v[194:197], v[32:35]
	v_mfma_f32_16x16x32_bf16 v[20:23], v[144:147], v[202:205], v[20:23]
	v_mfma_f32_16x16x32_bf16 v[16:19], v[152:155], v[202:205], v[16:19]
	v_mfma_f32_16x16x32_bf16 v[60:63], v[148:151], v[180:183], v[60:63]
	v_mfma_f32_16x16x32_bf16 v[56:59], v[156:159], v[180:183], v[56:59]
	v_mfma_f32_16x16x32_bf16 v[52:55], v[148:151], v[188:191], v[52:55]
	v_mfma_f32_16x16x32_bf16 v[48:51], v[156:159], v[188:191], v[48:51]
	v_mfma_f32_16x16x32_bf16 v[36:39], v[148:151], v[198:201], v[36:39]
	v_mfma_f32_16x16x32_bf16 v[32:35], v[156:159], v[198:201], v[32:35]
	v_mfma_f32_16x16x32_bf16 v[20:23], v[148:151], v[206:209], v[20:23]
	v_mfma_f32_16x16x32_bf16 v[16:19], v[156:159], v[206:209], v[16:19]
	v_mfma_f32_16x16x32_bf16 v[44:47], v[160:163], v[176:179], v[44:47]
	v_mfma_f32_16x16x32_bf16 v[40:43], v[168:171], v[176:179], v[40:43]
	v_mfma_f32_16x16x32_bf16 v[28:31], v[160:163], v[184:187], v[28:31]
	v_mfma_f32_16x16x32_bf16 v[24:27], v[168:171], v[184:187], v[24:27]
	v_mfma_f32_16x16x32_bf16 v[12:15], v[160:163], v[194:197], v[12:15]
	v_mfma_f32_16x16x32_bf16 v[8:11], v[168:171], v[194:197], v[8:11]
	v_mfma_f32_16x16x32_bf16 v[4:7], v[160:163], v[202:205], v[4:7]
	v_mfma_f32_16x16x32_bf16 v[0:3], v[168:171], v[202:205], v[0:3]
	v_mfma_f32_16x16x32_bf16 v[44:47], v[164:167], v[180:183], v[44:47]
	v_mfma_f32_16x16x32_bf16 v[40:43], v[172:175], v[180:183], v[40:43]
	v_mfma_f32_16x16x32_bf16 v[28:31], v[164:167], v[188:191], v[28:31]
	v_mfma_f32_16x16x32_bf16 v[24:27], v[172:175], v[188:191], v[24:27]
	v_mfma_f32_16x16x32_bf16 v[12:15], v[164:167], v[198:201], v[12:15]
	v_mfma_f32_16x16x32_bf16 v[8:11], v[172:175], v[198:201], v[8:11]
	v_mfma_f32_16x16x32_bf16 v[4:7], v[164:167], v[206:209], v[4:7]
	v_mfma_f32_16x16x32_bf16 v[0:3], v[172:175], v[206:209], v[0:3]
	s_barrier
	s_add_i32 s64, s64, 2
	s_add_u32 s62, s62, 0x100
	s_addc_u32 s63, s63, 0
	s_add_u32 s30, s30, 0x100
	s_addc_u32 s31, s31, 0
	s_cmp_gt_u32 s64, 13
	s_cbranch_scc0 .LBB0_137
	s_and_b64 vcc, exec, s[18:19]
	s_cbranch_vccz .LBB0_140
	s_barrier

; #define PG8_STAGE(bufoff, gbase, voff) do { _Pragma("unroll") for (int _i = 0; _i < 2; ++_i) \
;         __builtin_amdgcn_global_load_lds((const unsigned*)((const char*)(gbase) + (voff)[_i]), (LAS unsigned*)(lds + (bufoff) + ldsw + _i * 8192), 16, 0, 0); } while (0)
; #define PG8_LDA(dst, b, h) do { _Pragma("unroll") for (int m = 0; m < 4; ++m) _Pragma("unroll") for (int k = 0; k < 2; ++k) dst[m][k] = *(const LAS bf16x8*)(lds + PG8_SA(b, h) + aoff + m * 2048 + k * 1024); } while (0)
; #define PG8_LDB(dst, b, h) do { _Pragma("unroll") for (int n = 0; n < 2; ++n) _Pragma("unroll") for (int k = 0; k < 2; ++k) dst[n][k] = *(const LAS bf16x8*)(lds + PG8_SB(b, h) + boff + n * 2048 + k * 1024); } while (0)
; #define PG8_MMA(ai, bj, At, Bt) do { __builtin_amdgcn_s_setprio(1); _Pragma("unroll") for (int m = 0; m < 4; ++m) _Pragma("unroll") for (int n = 0; n < 2; ++n) _Pragma("unroll") for (int k = 0; k < 2; ++k) \
;         acc[ai][bj][m][n] = __builtin_amdgcn_mfma_f32_16x16x32_bf16(Bt[n][k], At[m][k], acc[ai][bj][m][n], 0, 0, 0); __builtin_amdgcn_s_setprio(0); } while (0)
; #define PG8_WAIT_V(n) asm volatile("s_waitcnt vmcnt(" #n ")" ::: "memory")
; #define PG8_WAIT_L(n) asm volatile("s_waitcnt lgkmcnt(" #n ")" ::: "memory")
; #define PG8_BAR __builtin_amdgcn_s_barrier()
; #define PG8_SCHED __builtin_amdgcn_sched_barrier(0)
; template <class Epi>
; DI void gemm_phase(int wv, LAS unsigned char* lds, LAS unsigned char* scr, const Sched& S, const Epi& E) {
;     ...
;         for (int t = 0; t < nt; t += 2) {
;             const bool last = (t == nt - 2);
;             const char* a1 = cA + (size_t)(t + 1) * kstep;
;             const char* a2 = last ? nA : cA + (size_t)(t + 2) * kstep; const char* b2 = last ? nB : cB + (size_t)(t + 2) * kstep;
;             const char* a3 = a2 + kstep; const char* b3 = b2 + kstep;
;             PG8_LDB(B0, 0, 0); PG8_LDB(B1, 0, 1); PG8_SCHED; PG8_LDA(At, 0, 0); PG8_STAGE(PG8_SA(1, 1), a1 + hstepA, voffA);
;             PG8_WAIT_V(8); PG8_WAIT_L(0); PG8_BAR; PG8_MMA(0, 0, At, B0); PG8_MMA(0, 1, At, B1); PG8_BAR; PG8_SCHED;
;             PG8_LDA(At, 0, 1); PG8_STAGE(PG8_SB(0, 0), b2, voffB); PG8_STAGE(PG8_SB(0, 1), b2 + hstepB, voffB); PG8_STAGE(PG8_SA(0, 0), a2, voffA);
;             PG8_WAIT_V(8); PG8_WAIT_L(0); PG8_BAR; PG8_MMA(1, 0, At, B0); PG8_MMA(1, 1, At, B1); PG8_BAR; PG8_SCHED;
.LBB0_163:
	s_add_u32 s26, s6, 0xfffc0080
	s_addc_u32 s27, s7, -1
	s_add_i32 s62, 0, 0x10000
	s_cmp_eq_u32 s61, 12
	s_cselect_b32 s29, s21, s27
	s_cselect_b32 s28, s40, s26
	v_add_u32_e32 v143, s62, v140
	s_cselect_b32 s27, s23, s60
	s_cselect_b32 s26, s22, s55
	s_add_i32 s64, 0, 0x14000
	ds_read_b128 v[144:147], v143
	ds_read_b128 v[148:151], v143 offset:1024
	ds_read_b128 v[152:155], v143 offset:2048
	ds_read_b128 v[156:159], v143 offset:3072
	v_add_u32_e32 v143, s64, v140
	ds_read_b128 v[160:163], v143
	ds_read_b128 v[164:167], v143 offset:1024
	ds_read_b128 v[168:171], v143 offset:2048
	ds_read_b128 v[172:175], v143 offset:3072
	v_lshl_add_u64 v[210:211], s[6:7], 0, v[138:139]
	s_add_i32 m0, s37, 0xc000
	ds_read_b128 v[176:179], v142
	ds_read_b128 v[180:183], v142 offset:1024
	ds_read_b128 v[184:187], v142 offset:2048
	ds_read_b128 v[188:191], v142 offset:3072
	ds_read_b128 v[194:197], v142 offset:4096
	ds_read_b128 v[198:201], v142 offset:5120
	ds_read_b128 v[202:205], v142 offset:6144
	ds_read_b128 v[206:209], v142 offset:7168
	global_load_lds_dwordx4 v[210:211], off
	v_lshl_add_u64 v[210:211], s[6:7], 0, v[136:137]
	s_add_i32 m0, s37, 0xe000
	s_nop 0
	global_load_lds_dwordx4 v[210:211], off
	s_waitcnt vmcnt(8)
	s_waitcnt lgkmcnt(0)
	s_barrier
	s_waitcnt lgkmcnt(0)
	v_mfma_f32_16x16x32_bf16 v[124:127], v[144:147], v[176:179], v[124:127]
	v_mfma_f32_16x16x32_bf16 v[120:123], v[152:155], v[176:179], v[120:123]
	v_mfma_f32_16x16x32_bf16 v[116:119], v[144:147], v[184:187], v[116:119]
	v_mfma_f32_16x16x32_bf16 v[112:115], v[152:155], v[184:187], v[112:115]
	v_mfma_f32_16x16x32_bf16 v[100:103], v[144:147], v[194:197], v[100:103]
	v_mfma_f32_16x16x32_bf16 v[96:99], v[152:155], v[194:197], v[96:99]
	v_mfma_f32_16x16x32_bf16 v[84:87], v[144:147], v[202:205], v[84:87]
	v_mfma_f32_16x16x32_bf16 v[80:83], v[152:155], v[202:205], v[80:83]
	v_mfma_f32_16x16x32_bf16 v[124:127], v[148:151], v[180:183], v[124:127]
	v_mfma_f32_16x16x32_bf16 v[120:123], v[156:159], v[180:183], v[120:123]
	v_mfma_f32_16x16x32_bf16 v[116:119], v[148:151], v[188:191], v[116:119]
	v_mfma_f32_16x16x32_bf16 v[112:115], v[156:159], v[188:191], v[112:115]
	v_mfma_f32_16x16x32_bf16 v[100:103], v[148:151], v[198:201], v[100:103]
	v_mfma_f32_16x16x32_bf16 v[96:99], v[156:159], v[198:201], v[96:99]
	v_mfma_f32_16x16x32_bf16 v[84:87], v[148:151], v[206:209], v[84:87]
	v_mfma_f32_16x16x32_bf16 v[80:83], v[156:159], v[206:209], v[80:83]
	v_mfma_f32_16x16x32_bf16 v[108:111], v[160:163], v[176:179], v[108:111]
	v_mfma_f32_16x16x32_bf16 v[104:107], v[168:171], v[176:179], v[104:107]
	v_mfma_f32_16x16x32_bf16 v[92:95], v[160:163], v[184:187], v[92:95]
	v_mfma_f32_16x16x32_bf16 v[88:91], v[168:171], v[184:187], v[88:91]
	v_mfma_f32_16x16x32_bf16 v[76:79], v[160:163], v[194:197], v[76:79]
	v_mfma_f32_16x16x32_bf16 v[72:75], v[168:171], v[194:197], v[72:75]
	v_mfma_f32_16x16x32_bf16 v[68:71], v[160:163], v[202:205], v[68:71]
	v_mfma_f32_16x16x32_bf16 v[64:67], v[168:171], v[202:205], v[64:67]
	v_mfma_f32_16x16x32_bf16 v[108:111], v[164:167], v[180:183], v[108:111]
	v_mfma_f32_16x16x32_bf16 v[104:107], v[172:175], v[180:183], v[104:107]
	v_mfma_f32_16x16x32_bf16 v[92:95], v[164:167], v[188:191], v[92:95]
	v_mfma_f32_16x16x32_bf16 v[88:91], v[172:175], v[188:191], v[88:91]
	v_mfma_f32_16x16x32_bf16 v[76:79], v[164:167], v[198:201], v[76:79]
	v_mfma_f32_16x16x32_bf16 v[72:75], v[172:175], v[198:201], v[72:75]
	v_mfma_f32_16x16x32_bf16 v[68:71], v[164:167], v[206:209], v[68:71]
	v_mfma_f32_16x16x32_bf16 v[64:67], v[172:175], v[206:209], v[64:67]
	s_barrier
	s_add_i32 s62, s62, s33
	v_lshl_add_u64 v[210:211], s[26:27], 0, v[192:193]
	s_mov_b32 m0, s62
	ds_read_b128 v[176:179], v142 offset:16384
	ds_read_b128 v[180:183], v142 offset:17408
	ds_read_b128 v[184:187], v142 offset:18432
	ds_read_b128 v[188:191], v142 offset:19456
	ds_read_b128 v[194:197], v142 offset:20480
	ds_read_b128 v[198:201], v142 offset:21504
	ds_read_b128 v[202:205], v142 offset:22528
	ds_read_b128 v[206:209], v142 offset:23552
	global_load_lds_dwordx4 v[210:211], off
	s_add_i32 m0, s62, 0x2000
	s_add_u32 s62, s26, 0x100000
	v_lshl_add_u64 v[212:213], s[26:27], 0, v[132:133]
	s_addc_u32 s63, s27, 0
	s_add_i32 s64, s64, s33
	global_load_lds_dwordx4 v[212:213], off
	v_lshl_add_u64 v[214:215], s[62:63], 0, v[192:193]
	s_mov_b32 m0, s64
	v_lshl_add_u64 v[216:217], s[28:29], 0, v[130:131]
	global_load_lds_dwordx4 v[214:215], off
	v_lshl_add_u64 v[214:215], s[62:63], 0, v[132:133]
	s_add_i32 m0, s64, 0x2000
	s_nop 0
	global_load_lds_dwordx4 v[214:215], off
	v_lshl_add_u64 v[214:215], s[28:29], 0, v[128:129]
	s_mov_b32 m0, s37
	s_nop 0
	global_load_lds_dwordx4 v[214:215], off
	s_mov_b32 m0, s38
	s_nop 0
	global_load_lds_dwordx4 v[216:217], off
	s_waitcnt vmcnt(8)
	s_waitcnt lgkmcnt(0)
	s_barrier
; #define PG8_STAGE(bufoff, gbase, voff) do { _Pragma("unroll") for (int _i = 0; _i < 2; ++_i) \
;         __builtin_amdgcn_global_load_lds((const unsigned*)((const char*)(gbase) + (voff)[_i]), (LAS unsigned*)(lds + (bufoff) + ldsw + _i * 8192), 16, 0, 0); } while (0)
; #define PG8_LDA(dst, b, h) do { _Pragma("unroll") for (int m = 0; m < 4; ++m) _Pragma("unroll") for (int k = 0; k < 2; ++k) dst[m][k] = *(const LAS bf16x8*)(lds + PG8_SA(b, h) + aoff + m * 2048 + k * 1024); } while (0)
; #define PG8_LDB(dst, b, h) do { _Pragma("unroll") for (int n = 0; n < 2; ++n) _Pragma("unroll") for (int k = 0; k < 2; ++k) dst[n][k] = *(const LAS bf16x8*)(lds + PG8_SB(b, h) + boff + n * 2048 + k * 1024); } while (0)
; #define PG8_MMA(ai, bj, At, Bt) do { __builtin_amdgcn_s_setprio(1); _Pragma("unroll") for (int m = 0; m < 4; ++m) _Pragma("unroll") for (int n = 0; n < 2; ++n) _Pragma("unroll") for (int k = 0; k < 2; ++k) \
;         acc[ai][bj][m][n] = __builtin_amdgcn_mfma_f32_16x16x32_bf16(Bt[n][k], At[m][k], acc[ai][bj][m][n], 0, 0, 0); __builtin_amdgcn_s_setprio(0); } while (0)
; #define PG8_WAIT_V(n) asm volatile("s_waitcnt vmcnt(" #n ")" ::: "memory")
; #define PG8_WAIT_L(n) asm volatile("s_waitcnt lgkmcnt(" #n ")" ::: "memory")
; #define PG8_BAR __builtin_amdgcn_s_barrier()
; #define PG8_SCHED __builtin_amdgcn_sched_barrier(0)
; template <class Epi>
; DI void gemm_phase(int wv, LAS unsigned char* lds, LAS unsigned char* scr, const Sched& S, const Epi& E) {
;     ...
;             PG8_WAIT_V(8); PG8_WAIT_L(0); PG8_BAR; PG8_MMA(0, 0, At, B0); PG8_MMA(0, 1, At, B1); PG8_BAR; PG8_SCHED;
;             PG8_LDA(At, 0, 1); PG8_STAGE(PG8_SB(0, 0), b2, voffB); PG8_STAGE(PG8_SB(0, 1), b2 + hstepB, voffB); PG8_STAGE(PG8_SA(0, 0), a2, voffA);
;             PG8_WAIT_V(8); PG8_WAIT_L(0); PG8_BAR; PG8_MMA(1, 0, At, B0); PG8_MMA(1, 1, At, B1); PG8_BAR; PG8_SCHED;
;             PG8_LDB(B0, 1, 0); PG8_LDB(B1, 1, 1); PG8_SCHED; PG8_LDA(At, 1, 0); PG8_STAGE(PG8_SA(0, 1), a2 + hstepA, voffA);
;             PG8_WAIT_V(8); PG8_WAIT_L(0); PG8_BAR; PG8_MMA(0, 0, At, B0); PG8_MMA(0, 1, At, B1); PG8_BAR; PG8_SCHED;
	s_waitcnt lgkmcnt(0)
	v_mfma_f32_16x16x32_bf16 v[60:63], v[144:147], v[176:179], v[60:63]
	v_mfma_f32_16x16x32_bf16 v[56:59], v[152:155], v[176:179], v[56:59]
	v_mfma_f32_16x16x32_bf16 v[52:55], v[144:147], v[184:187], v[52:55]
	v_mfma_f32_16x16x32_bf16 v[48:51], v[152:155], v[184:187], v[48:51]
	v_mfma_f32_16x16x32_bf16 v[36:39], v[144:147], v[194:197], v[36:39]
	v_mfma_f32_16x16x32_bf16 v[32:35], v[152:155], v[194:197], v[32:35]
	v_mfma_f32_16x16x32_bf16 v[20:23], v[144:147], v[202:205], v[20:23]
	v_mfma_f32_16x16x32_bf16 v[16:19], v[152:155], v[202:205], v[16:19]
	v_mfma_f32_16x16x32_bf16 v[60:63], v[148:151], v[180:183], v[60:63]
	v_mfma_f32_16x16x32_bf16 v[56:59], v[156:159], v[180:183], v[56:59]
	v_mfma_f32_16x16x32_bf16 v[52:55], v[148:151], v[188:191], v[52:55]
	v_mfma_f32_16x16x32_bf16 v[48:51], v[156:159], v[188:191], v[48:51]
	v_mfma_f32_16x16x32_bf16 v[36:39], v[148:151], v[198:201], v[36:39]
	v_mfma_f32_16x16x32_bf16 v[32:35], v[156:159], v[198:201], v[32:35]
	v_mfma_f32_16x16x32_bf16 v[20:23], v[148:151], v[206:209], v[20:23]
	v_mfma_f32_16x16x32_bf16 v[16:19], v[156:159], v[206:209], v[16:19]
	v_mfma_f32_16x16x32_bf16 v[44:47], v[160:163], v[176:179], v[44:47]
	v_mfma_f32_16x16x32_bf16 v[40:43], v[168:171], v[176:179], v[40:43]
	v_mfma_f32_16x16x32_bf16 v[28:31], v[160:163], v[184:187], v[28:31]
	v_mfma_f32_16x16x32_bf16 v[24:27], v[168:171], v[184:187], v[24:27]
	v_mfma_f32_16x16x32_bf16 v[12:15], v[160:163], v[194:197], v[12:15]
	v_mfma_f32_16x16x32_bf16 v[8:11], v[168:171], v[194:197], v[8:11]
	v_mfma_f32_16x16x32_bf16 v[4:7], v[160:163], v[202:205], v[4:7]
	v_mfma_f32_16x16x32_bf16 v[0:3], v[168:171], v[202:205], v[0:3]
	v_mfma_f32_16x16x32_bf16 v[44:47], v[164:167], v[180:183], v[44:47]
	v_mfma_f32_16x16x32_bf16 v[40:43], v[172:175], v[180:183], v[40:43]
	v_mfma_f32_16x16x32_bf16 v[28:31], v[164:167], v[188:191], v[28:31]
	v_mfma_f32_16x16x32_bf16 v[24:27], v[172:175], v[188:191], v[24:27]
	v_mfma_f32_16x16x32_bf16 v[12:15], v[164:167], v[198:201], v[12:15]
	v_mfma_f32_16x16x32_bf16 v[8:11], v[172:175], v[198:201], v[8:11]
	v_mfma_f32_16x16x32_bf16 v[4:7], v[164:167], v[206:209], v[4:7]
	v_mfma_f32_16x16x32_bf16 v[0:3], v[172:175], v[206:209], v[0:3]
	s_barrier
	s_add_i32 s62, 0, 0x18000
	v_add_u32_e32 v143, s62, v140
	s_add_i32 s63, 0, 0x1c000
	ds_read_b128 v[144:147], v143
	ds_read_b128 v[148:151], v143 offset:1024
	ds_read_b128 v[152:155], v143 offset:2048
	ds_read_b128 v[156:159], v143 offset:3072
	v_add_u32_e32 v143, s63, v140
	ds_read_b128 v[160:163], v143
	ds_read_b128 v[164:167], v143 offset:1024
	ds_read_b128 v[168:171], v143 offset:2048
	ds_read_b128 v[172:175], v143 offset:3072
	s_add_u32 s28, s28, 0x40000
	s_addc_u32 s29, s29, 0
	s_mov_b32 m0, s39
	v_lshl_add_u64 v[218:219], s[28:29], 0, v[128:129]
	ds_read_b128 v[176:179], v142 offset:32768
	ds_read_b128 v[180:183], v142 offset:33792
	ds_read_b128 v[184:187], v142 offset:34816
	ds_read_b128 v[188:191], v142 offset:35840
	ds_read_b128 v[194:197], v142 offset:36864
	ds_read_b128 v[198:201], v142 offset:37888
	ds_read_b128 v[202:205], v142 offset:38912
	ds_read_b128 v[206:209], v142 offset:39936
	global_load_lds_dwordx4 v[218:219], off
	v_lshl_add_u64 v[218:219], s[28:29], 0, v[130:131]
	s_mov_b32 m0, s42
	s_nop 0
	global_load_lds_dwordx4 v[218:219], off
	s_waitcnt vmcnt(8)
	s_waitcnt lgkmcnt(0)
	s_barrier
	s_waitcnt lgkmcnt(0)
	v_mfma_f32_16x16x32_bf16 v[124:127], v[144:147], v[176:179], v[124:127]
	v_mfma_f32_16x16x32_bf16 v[120:123], v[152:155], v[176:179], v[120:123]
	v_mfma_f32_16x16x32_bf16 v[116:119], v[144:147], v[184:187], v[116:119]
	v_mfma_f32_16x16x32_bf16 v[112:115], v[152:155], v[184:187], v[112:115]
	v_mfma_f32_16x16x32_bf16 v[100:103], v[144:147], v[194:197], v[100:103]
	v_mfma_f32_16x16x32_bf16 v[96:99], v[152:155], v[194:197], v[96:99]
	v_mfma_f32_16x16x32_bf16 v[84:87], v[144:147], v[202:205], v[84:87]
	v_mfma_f32_16x16x32_bf16 v[80:83], v[152:155], v[202:205], v[80:83]
	v_mfma_f32_16x16x32_bf16 v[124:127], v[148:151], v[180:183], v[124:127]
	v_mfma_f32_16x16x32_bf16 v[120:123], v[156:159], v[180:183], v[120:123]
	v_mfma_f32_16x16x32_bf16 v[116:119], v[148:151], v[188:191], v[116:119]
	v_mfma_f32_16x16x32_bf16 v[112:115], v[156:159], v[188:191], v[112:115]
	v_mfma_f32_16x16x32_bf16 v[100:103], v[148:151], v[198:201], v[100:103]
	v_mfma_f32_16x16x32_bf16 v[96:99], v[156:159], v[198:201], v[96:99]
	v_mfma_f32_16x16x32_bf16 v[84:87], v[148:151], v[206:209], v[84:87]
	v_mfma_f32_16x16x32_bf16 v[80:83], v[156:159], v[206:209], v[80:83]
	v_mfma_f32_16x16x32_bf16 v[108:111], v[160:163], v[176:179], v[108:111]
	v_mfma_f32_16x16x32_bf16 v[104:107], v[168:171], v[176:179], v[104:107]
	v_mfma_f32_16x16x32_bf16 v[92:95], v[160:163], v[184:187], v[92:95]
	v_mfma_f32_16x16x32_bf16 v[88:91], v[168:171], v[184:187], v[88:91]
	v_mfma_f32_16x16x32_bf16 v[76:79], v[160:163], v[194:197], v[76:79]
	v_mfma_f32_16x16x32_bf16 v[72:75], v[168:171], v[194:197], v[72:75]
	v_mfma_f32_16x16x32_bf16 v[68:71], v[160:163], v[202:205], v[68:71]
	v_mfma_f32_16x16x32_bf16 v[64:67], v[168:171], v[202:205], v[64:67]
	v_mfma_f32_16x16x32_bf16 v[108:111], v[164:167], v[180:183], v[108:111]
	v_mfma_f32_16x16x32_bf16 v[104:107], v[172:175], v[180:183], v[104:107]
	v_mfma_f32_16x16x32_bf16 v[92:95], v[164:167], v[188:191], v[92:95]
	v_mfma_f32_16x16x32_bf16 v[88:91], v[172:175], v[188:191], v[88:91]
	v_mfma_f32_16x16x32_bf16 v[76:79], v[164:167], v[198:201], v[76:79]
	v_mfma_f32_16x16x32_bf16 v[72:75], v[172:175], v[198:201], v[72:75]
	v_mfma_f32_16x16x32_bf16 v[68:71], v[164:167], v[206:209], v[68:71]
	v_mfma_f32_16x16x32_bf16 v[64:67], v[172:175], v[206:209], v[64:67]
	s_barrier
; #define PG8_STAGE(bufoff, gbase, voff) do { _Pragma("unroll") for (int _i = 0; _i < 2; ++_i) \
;         __builtin_amdgcn_global_load_lds((const unsigned*)((const char*)(gbase) + (voff)[_i]), (LAS unsigned*)(lds + (bufoff) + ldsw + _i * 8192), 16, 0, 0); } while (0)
; #define PG8_LDA(dst, b, h) do { _Pragma("unroll") for (int m = 0; m < 4; ++m) _Pragma("unroll") for (int k = 0; k < 2; ++k) dst[m][k] = *(const LAS bf16x8*)(lds + PG8_SA(b, h) + aoff + m * 2048 + k * 1024); } while (0)
; #define PG8_MMA(ai, bj, At, Bt) do { __builtin_amdgcn_s_setprio(1); _Pragma("unroll") for (int m = 0; m < 4; ++m) _Pragma("unroll") for (int n = 0; n < 2; ++n) _Pragma("unroll") for (int k = 0; k < 2; ++k) \
;         acc[ai][bj][m][n] = __builtin_amdgcn_mfma_f32_16x16x32_bf16(Bt[n][k], At[m][k], acc[ai][bj][m][n], 0, 0, 0); __builtin_amdgcn_s_setprio(0); } while (0)
; #define PG8_WAIT_V(n) asm volatile("s_waitcnt vmcnt(" #n ")" ::: "memory")
; #define PG8_WAIT_L(n) asm volatile("s_waitcnt lgkmcnt(" #n ")" ::: "memory")
; #define PG8_BAR __builtin_amdgcn_s_barrier()
; #define PG8_SCHED __builtin_amdgcn_sched_barrier(0)
; template <class Epi>
; DI void gemm_phase(int wv, LAS unsigned char* lds, LAS unsigned char* scr, const Sched& S, const Epi& E) {
;     ...
;             PG8_LDA(At, 1, 1); PG8_STAGE(PG8_SB(1, 0), b3, voffB); PG8_STAGE(PG8_SB(1, 1), b3 + hstepB, voffB); PG8_STAGE(PG8_SA(1, 0), a3, voffA);
;             PG8_WAIT_V(8); PG8_WAIT_L(0); PG8_BAR; PG8_MMA(1, 0, At, B0); PG8_MMA(1, 1, At, B1); PG8_BAR; PG8_SCHED;
;         }
;         if (wr == 0) PG8_BAR;
	s_add_i32 s28, s62, s33
	v_lshl_add_u64 v[210:211], v[210:211], 0, s[2:3]
	s_mov_b32 m0, s28
	ds_read_b128 v[176:179], v142 offset:49152
	ds_read_b128 v[180:183], v142 offset:50176
	ds_read_b128 v[184:187], v142 offset:51200
	ds_read_b128 v[188:191], v142 offset:52224
	ds_read_b128 v[194:197], v142 offset:53248
	ds_read_b128 v[198:201], v142 offset:54272
	ds_read_b128 v[202:205], v142 offset:55296
	ds_read_b128 v[206:209], v142 offset:56320
	global_load_lds_dwordx4 v[210:211], off
	s_add_i32 m0, s28, 0x2000
	s_add_u32 s26, s26, 0x100080
	v_lshl_add_u64 v[210:211], v[212:213], 0, s[2:3]
	s_addc_u32 s27, s27, 0
	s_add_i32 s28, s63, s33
	global_load_lds_dwordx4 v[210:211], off
	v_lshl_add_u64 v[210:211], s[26:27], 0, v[192:193]
	s_mov_b32 m0, s28
	s_nop 0
	global_load_lds_dwordx4 v[210:211], off
	v_lshl_add_u64 v[210:211], s[26:27], 0, v[132:133]
	s_add_i32 m0, s28, 0x2000
	s_nop 0
	global_load_lds_dwordx4 v[210:211], off
	v_lshl_add_u64 v[210:211], v[214:215], 0, s[2:3]
	s_mov_b32 m0, s43
	s_nop 0
	global_load_lds_dwordx4 v[210:211], off
	v_lshl_add_u64 v[210:211], v[216:217], 0, s[2:3]
	s_mov_b32 m0, s44
	s_nop 0
	global_load_lds_dwordx4 v[210:211], off
	s_waitcnt vmcnt(8)
	s_waitcnt lgkmcnt(0)
	s_barrier
	s_waitcnt lgkmcnt(0)
	v_mfma_f32_16x16x32_bf16 v[60:63], v[144:147], v[176:179], v[60:63]
	v_mfma_f32_16x16x32_bf16 v[56:59], v[152:155], v[176:179], v[56:59]
	v_mfma_f32_16x16x32_bf16 v[52:55], v[144:147], v[184:187], v[52:55]
	v_mfma_f32_16x16x32_bf16 v[48:51], v[152:155], v[184:187], v[48:51]
	v_mfma_f32_16x16x32_bf16 v[36:39], v[144:147], v[194:197], v[36:39]
	v_mfma_f32_16x16x32_bf16 v[32:35], v[152:155], v[194:197], v[32:35]
	v_mfma_f32_16x16x32_bf16 v[20:23], v[144:147], v[202:205], v[20:23]
	v_mfma_f32_16x16x32_bf16 v[16:19], v[152:155], v[202:205], v[16:19]
	v_mfma_f32_16x16x32_bf16 v[60:63], v[148:151], v[180:183], v[60:63]
	v_mfma_f32_16x16x32_bf16 v[56:59], v[156:159], v[180:183], v[56:59]
	v_mfma_f32_16x16x32_bf16 v[52:55], v[148:151], v[188:191], v[52:55]
	v_mfma_f32_16x16x32_bf16 v[48:51], v[156:159], v[188:191], v[48:51]
	v_mfma_f32_16x16x32_bf16 v[36:39], v[148:151], v[198:201], v[36:39]
	v_mfma_f32_16x16x32_bf16 v[32:35], v[156:159], v[198:201], v[32:35]
	v_mfma_f32_16x16x32_bf16 v[20:23], v[148:151], v[206:209], v[20:23]
	v_mfma_f32_16x16x32_bf16 v[16:19], v[156:159], v[206:209], v[16:19]
	v_mfma_f32_16x16x32_bf16 v[44:47], v[160:163], v[176:179], v[44:47]
	v_mfma_f32_16x16x32_bf16 v[40:43], v[168:171], v[176:179], v[40:43]
	v_mfma_f32_16x16x32_bf16 v[28:31], v[160:163], v[184:187], v[28:31]
	v_mfma_f32_16x16x32_bf16 v[24:27], v[168:171], v[184:187], v[24:27]
	v_mfma_f32_16x16x32_bf16 v[12:15], v[160:163], v[194:197], v[12:15]
	v_mfma_f32_16x16x32_bf16 v[8:11], v[168:171], v[194:197], v[8:11]
	v_mfma_f32_16x16x32_bf16 v[4:7], v[160:163], v[202:205], v[4:7]
	v_mfma_f32_16x16x32_bf16 v[0:3], v[168:171], v[202:205], v[0:3]
	v_mfma_f32_16x16x32_bf16 v[44:47], v[164:167], v[180:183], v[44:47]
	v_mfma_f32_16x16x32_bf16 v[40:43], v[172:175], v[180:183], v[40:43]
	v_mfma_f32_16x16x32_bf16 v[28:31], v[164:167], v[188:191], v[28:31]
	v_mfma_f32_16x16x32_bf16 v[24:27], v[172:175], v[188:191], v[24:27]
	v_mfma_f32_16x16x32_bf16 v[12:15], v[164:167], v[198:201], v[12:15]
	v_mfma_f32_16x16x32_bf16 v[8:11], v[172:175], v[198:201], v[8:11]
	v_mfma_f32_16x16x32_bf16 v[4:7], v[164:167], v[206:209], v[4:7]
	v_mfma_f32_16x16x32_bf16 v[0:3], v[172:175], v[206:209], v[0:3]
	s_barrier
	s_add_i32 s61, s61, 2
	s_add_u32 s55, s55, 0x100
	s_addc_u32 s60, s60, 0
	s_add_u32 s6, s6, 0x100
	s_addc_u32 s7, s7, 0
	s_cmp_gt_u32 s61, 13
	s_cbranch_scc0 .LBB0_163
	s_and_b64 vcc, exec, s[18:19]
	s_cbranch_vccz .LBB0_166
	s_barrier

; #define PG8_STAGE(bufoff, gbase, voff) do { _Pragma("unroll") for (int _i = 0; _i < 2; ++_i) \
;         __builtin_amdgcn_global_load_lds((const unsigned*)((const char*)(gbase) + (voff)[_i]), (LAS unsigned*)(lds + (bufoff) + ldsw + _i * 8192), 16, 0, 0); } while (0)
; #define PG8_LDA(dst, b, h) do { _Pragma("unroll") for (int m = 0; m < 4; ++m) _Pragma("unroll") for (int k = 0; k < 2; ++k) dst[m][k] = *(const LAS bf16x8*)(lds + PG8_SA(b, h) + aoff + m * 2048 + k * 1024); } while (0)
; #define PG8_LDB(dst, b, h) do { _Pragma("unroll") for (int n = 0; n < 2; ++n) _Pragma("unroll") for (int k = 0; k < 2; ++k) dst[n][k] = *(const LAS bf16x8*)(lds + PG8_SB(b, h) + boff + n * 2048 + k * 1024); } while (0)
; #define PG8_MMA(ai, bj, At, Bt) do { __builtin_amdgcn_s_setprio(1); _Pragma("unroll") for (int m = 0; m < 4; ++m) _Pragma("unroll") for (int n = 0; n < 2; ++n) _Pragma("unroll") for (int k = 0; k < 2; ++k) \
;         acc[ai][bj][m][n] = __builtin_amdgcn_mfma_f32_16x16x32_bf16(Bt[n][k], At[m][k], acc[ai][bj][m][n], 0, 0, 0); __builtin_amdgcn_s_setprio(0); } while (0)
; #define PG8_WAIT_V(n) asm volatile("s_waitcnt vmcnt(" #n ")" ::: "memory")
; #define PG8_WAIT_L(n) asm volatile("s_waitcnt lgkmcnt(" #n ")" ::: "memory")
; #define PG8_BAR __builtin_amdgcn_s_barrier()
; #define PG8_SCHED __builtin_amdgcn_sched_barrier(0)
; template <class Epi>
; DI void gemm_phase(int wv, LAS unsigned char* lds, LAS unsigned char* scr, const Sched& S, const Epi& E) {
;     ...
;         for (int t = 0; t < nt; t += 2) {
;             const bool last = (t == nt - 2);
;             const char* a1 = cA + (size_t)(t + 1) * kstep;
;             const char* a2 = last ? nA : cA + (size_t)(t + 2) * kstep; const char* b2 = last ? nB : cB + (size_t)(t + 2) * kstep;
;             const char* a3 = a2 + kstep; const char* b3 = b2 + kstep;
;             PG8_LDB(B0, 0, 0); PG8_LDB(B1, 0, 1); PG8_SCHED; PG8_LDA(At, 0, 0); PG8_STAGE(PG8_SA(1, 1), a1 + hstepA, voffA);
;             PG8_WAIT_V(8); PG8_WAIT_L(0); PG8_BAR; PG8_MMA(0, 0, At, B0); PG8_MMA(0, 1, At, B1); PG8_BAR; PG8_SCHED;
;             PG8_LDA(At, 0, 1); PG8_STAGE(PG8_SB(0, 0), b2, voffB); PG8_STAGE(PG8_SB(0, 1), b2 + hstepB, voffB); PG8_STAGE(PG8_SA(0, 0), a2, voffA);
;             PG8_WAIT_V(8); PG8_WAIT_L(0); PG8_BAR; PG8_MMA(1, 0, At, B0); PG8_MMA(1, 1, At, B1); PG8_BAR; PG8_SCHED;
.LBB0_189:
	s_add_u32 s26, s6, 0xfffc0080
	s_addc_u32 s27, s7, -1
	s_add_i32 s59, 0, 0x10000
	s_cmp_eq_u32 s55, 12
	s_cselect_b32 s29, s21, s27
	s_cselect_b32 s28, s40, s26
	v_add_u32_e32 v143, s59, v140
	s_cselect_b32 s27, s23, s54
	s_cselect_b32 s26, s22, s51
	s_add_i32 s62, 0, 0x14000
	ds_read_b128 v[144:147], v143
	ds_read_b128 v[148:151], v143 offset:1024
	ds_read_b128 v[152:155], v143 offset:2048
	ds_read_b128 v[156:159], v143 offset:3072
	v_add_u32_e32 v143, s62, v140
	ds_read_b128 v[160:163], v143
	ds_read_b128 v[164:167], v143 offset:1024
	ds_read_b128 v[168:171], v143 offset:2048
	ds_read_b128 v[172:175], v143 offset:3072
	v_lshl_add_u64 v[210:211], s[6:7], 0, v[138:139]
	s_add_i32 m0, s37, 0xc000
	ds_read_b128 v[176:179], v142
	ds_read_b128 v[180:183], v142 offset:1024
	ds_read_b128 v[184:187], v142 offset:2048
	ds_read_b128 v[188:191], v142 offset:3072
	ds_read_b128 v[194:197], v142 offset:4096
	ds_read_b128 v[198:201], v142 offset:5120
	ds_read_b128 v[202:205], v142 offset:6144
	ds_read_b128 v[206:209], v142 offset:7168
	global_load_lds_dwordx4 v[210:211], off
	v_lshl_add_u64 v[210:211], s[6:7], 0, v[136:137]
	s_add_i32 m0, s37, 0xe000
	s_nop 0
	global_load_lds_dwordx4 v[210:211], off
	s_waitcnt vmcnt(8)
	s_waitcnt lgkmcnt(0)
	s_barrier
	s_waitcnt lgkmcnt(0)
	v_mfma_f32_16x16x32_bf16 v[124:127], v[144:147], v[176:179], v[124:127]
	v_mfma_f32_16x16x32_bf16 v[120:123], v[152:155], v[176:179], v[120:123]
	v_mfma_f32_16x16x32_bf16 v[116:119], v[144:147], v[184:187], v[116:119]
	v_mfma_f32_16x16x32_bf16 v[112:115], v[152:155], v[184:187], v[112:115]
	v_mfma_f32_16x16x32_bf16 v[100:103], v[144:147], v[194:197], v[100:103]
	v_mfma_f32_16x16x32_bf16 v[96:99], v[152:155], v[194:197], v[96:99]
	v_mfma_f32_16x16x32_bf16 v[84:87], v[144:147], v[202:205], v[84:87]
	v_mfma_f32_16x16x32_bf16 v[80:83], v[152:155], v[202:205], v[80:83]
	v_mfma_f32_16x16x32_bf16 v[124:127], v[148:151], v[180:183], v[124:127]
	v_mfma_f32_16x16x32_bf16 v[120:123], v[156:159], v[180:183], v[120:123]
	v_mfma_f32_16x16x32_bf16 v[116:119], v[148:151], v[188:191], v[116:119]
	v_mfma_f32_16x16x32_bf16 v[112:115], v[156:159], v[188:191], v[112:115]
	v_mfma_f32_16x16x32_bf16 v[100:103], v[148:151], v[198:201], v[100:103]
	v_mfma_f32_16x16x32_bf16 v[96:99], v[156:159], v[198:201], v[96:99]
	v_mfma_f32_16x16x32_bf16 v[84:87], v[148:151], v[206:209], v[84:87]
	v_mfma_f32_16x16x32_bf16 v[80:83], v[156:159], v[206:209], v[80:83]
	v_mfma_f32_16x16x32_bf16 v[108:111], v[160:163], v[176:179], v[108:111]
	v_mfma_f32_16x16x32_bf16 v[104:107], v[168:171], v[176:179], v[104:107]
	v_mfma_f32_16x16x32_bf16 v[92:95], v[160:163], v[184:187], v[92:95]
	v_mfma_f32_16x16x32_bf16 v[88:91], v[168:171], v[184:187], v[88:91]
	v_mfma_f32_16x16x32_bf16 v[76:79], v[160:163], v[194:197], v[76:79]
	v_mfma_f32_16x16x32_bf16 v[72:75], v[168:171], v[194:197], v[72:75]
	v_mfma_f32_16x16x32_bf16 v[68:71], v[160:163], v[202:205], v[68:71]
	v_mfma_f32_16x16x32_bf16 v[64:67], v[168:171], v[202:205], v[64:67]
	v_mfma_f32_16x16x32_bf16 v[108:111], v[164:167], v[180:183], v[108:111]
	v_mfma_f32_16x16x32_bf16 v[104:107], v[172:175], v[180:183], v[104:107]
	v_mfma_f32_16x16x32_bf16 v[92:95], v[164:167], v[188:191], v[92:95]
	v_mfma_f32_16x16x32_bf16 v[88:91], v[172:175], v[188:191], v[88:91]
	v_mfma_f32_16x16x32_bf16 v[76:79], v[164:167], v[198:201], v[76:79]
	v_mfma_f32_16x16x32_bf16 v[72:75], v[172:175], v[198:201], v[72:75]
	v_mfma_f32_16x16x32_bf16 v[68:71], v[164:167], v[206:209], v[68:71]
	v_mfma_f32_16x16x32_bf16 v[64:67], v[172:175], v[206:209], v[64:67]
	s_barrier
	s_add_i32 s59, s59, s33
	v_lshl_add_u64 v[210:211], s[26:27], 0, v[192:193]
	s_mov_b32 m0, s59
	ds_read_b128 v[176:179], v142 offset:16384
	ds_read_b128 v[180:183], v142 offset:17408
	ds_read_b128 v[184:187], v142 offset:18432
	ds_read_b128 v[188:191], v142 offset:19456
	ds_read_b128 v[194:197], v142 offset:20480
	ds_read_b128 v[198:201], v142 offset:21504
	ds_read_b128 v[202:205], v142 offset:22528
	ds_read_b128 v[206:209], v142 offset:23552
	global_load_lds_dwordx4 v[210:211], off
	s_add_i32 m0, s59, 0x2000
	s_add_u32 s60, s26, 0x400000
	v_lshl_add_u64 v[212:213], s[26:27], 0, v[132:133]
	s_addc_u32 s61, s27, 0
	s_add_i32 s59, s62, s33
	global_load_lds_dwordx4 v[212:213], off
	v_lshl_add_u64 v[214:215], s[60:61], 0, v[192:193]
	s_mov_b32 m0, s59
	v_lshl_add_u64 v[216:217], s[28:29], 0, v[130:131]
	global_load_lds_dwordx4 v[214:215], off
	v_lshl_add_u64 v[214:215], s[60:61], 0, v[132:133]
	s_add_i32 m0, s59, 0x2000
	s_nop 0
	global_load_lds_dwordx4 v[214:215], off
	v_lshl_add_u64 v[214:215], s[28:29], 0, v[128:129]
	s_mov_b32 m0, s37
	s_nop 0
	global_load_lds_dwordx4 v[214:215], off
	s_mov_b32 m0, s38
	s_nop 0
	global_load_lds_dwordx4 v[216:217], off
	s_waitcnt vmcnt(8)
	s_waitcnt lgkmcnt(0)
	s_barrier
; #define PG8_STAGE(bufoff, gbase, voff) do { _Pragma("unroll") for (int _i = 0; _i < 2; ++_i) \
;         __builtin_amdgcn_global_load_lds((const unsigned*)((const char*)(gbase) + (voff)[_i]), (LAS unsigned*)(lds + (bufoff) + ldsw + _i * 8192), 16, 0, 0); } while (0)
; #define PG8_LDA(dst, b, h) do { _Pragma("unroll") for (int m = 0; m < 4; ++m) _Pragma("unroll") for (int k = 0; k < 2; ++k) dst[m][k] = *(const LAS bf16x8*)(lds + PG8_SA(b, h) + aoff + m * 2048 + k * 1024); } while (0)
; #define PG8_LDB(dst, b, h) do { _Pragma("unroll") for (int n = 0; n < 2; ++n) _Pragma("unroll") for (int k = 0; k < 2; ++k) dst[n][k] = *(const LAS bf16x8*)(lds + PG8_SB(b, h) + boff + n * 2048 + k * 1024); } while (0)
; #define PG8_MMA(ai, bj, At, Bt) do { __builtin_amdgcn_s_setprio(1); _Pragma("unroll") for (int m = 0; m < 4; ++m) _Pragma("unroll") for (int n = 0; n < 2; ++n) _Pragma("unroll") for (int k = 0; k < 2; ++k) \
;         acc[ai][bj][m][n] = __builtin_amdgcn_mfma_f32_16x16x32_bf16(Bt[n][k], At[m][k], acc[ai][bj][m][n], 0, 0, 0); __builtin_amdgcn_s_setprio(0); } while (0)
; #define PG8_WAIT_V(n) asm volatile("s_waitcnt vmcnt(" #n ")" ::: "memory")
; #define PG8_WAIT_L(n) asm volatile("s_waitcnt lgkmcnt(" #n ")" ::: "memory")
; #define PG8_BAR __builtin_amdgcn_s_barrier()
; #define PG8_SCHED __builtin_amdgcn_sched_barrier(0)
; template <class Epi>
; DI void gemm_phase(int wv, LAS unsigned char* lds, LAS unsigned char* scr, const Sched& S, const Epi& E) {
;     ...
;             PG8_WAIT_V(8); PG8_WAIT_L(0); PG8_BAR; PG8_MMA(0, 0, At, B0); PG8_MMA(0, 1, At, B1); PG8_BAR; PG8_SCHED;
;             PG8_LDA(At, 0, 1); PG8_STAGE(PG8_SB(0, 0), b2, voffB); PG8_STAGE(PG8_SB(0, 1), b2 + hstepB, voffB); PG8_STAGE(PG8_SA(0, 0), a2, voffA);
;             PG8_WAIT_V(8); PG8_WAIT_L(0); PG8_BAR; PG8_MMA(1, 0, At, B0); PG8_MMA(1, 1, At, B1); PG8_BAR; PG8_SCHED;
;             PG8_LDB(B0, 1, 0); PG8_LDB(B1, 1, 1); PG8_SCHED; PG8_LDA(At, 1, 0); PG8_STAGE(PG8_SA(0, 1), a2 + hstepA, voffA);
;             PG8_WAIT_V(8); PG8_WAIT_L(0); PG8_BAR; PG8_MMA(0, 0, At, B0); PG8_MMA(0, 1, At, B1); PG8_BAR; PG8_SCHED;
	s_waitcnt lgkmcnt(0)
	v_mfma_f32_16x16x32_bf16 v[60:63], v[144:147], v[176:179], v[60:63]
	v_mfma_f32_16x16x32_bf16 v[56:59], v[152:155], v[176:179], v[56:59]
	v_mfma_f32_16x16x32_bf16 v[52:55], v[144:147], v[184:187], v[52:55]
	v_mfma_f32_16x16x32_bf16 v[48:51], v[152:155], v[184:187], v[48:51]
	v_mfma_f32_16x16x32_bf16 v[36:39], v[144:147], v[194:197], v[36:39]
	v_mfma_f32_16x16x32_bf16 v[32:35], v[152:155], v[194:197], v[32:35]
	v_mfma_f32_16x16x32_bf16 v[20:23], v[144:147], v[202:205], v[20:23]
	v_mfma_f32_16x16x32_bf16 v[16:19], v[152:155], v[202:205], v[16:19]
	v_mfma_f32_16x16x32_bf16 v[60:63], v[148:151], v[180:183], v[60:63]
	v_mfma_f32_16x16x32_bf16 v[56:59], v[156:159], v[180:183], v[56:59]
	v_mfma_f32_16x16x32_bf16 v[52:55], v[148:151], v[188:191], v[52:55]
	v_mfma_f32_16x16x32_bf16 v[48:51], v[156:159], v[188:191], v[48:51]
	v_mfma_f32_16x16x32_bf16 v[36:39], v[148:151], v[198:201], v[36:39]
	v_mfma_f32_16x16x32_bf16 v[32:35], v[156:159], v[198:201], v[32:35]
	v_mfma_f32_16x16x32_bf16 v[20:23], v[148:151], v[206:209], v[20:23]
	v_mfma_f32_16x16x32_bf16 v[16:19], v[156:159], v[206:209], v[16:19]
	v_mfma_f32_16x16x32_bf16 v[44:47], v[160:163], v[176:179], v[44:47]
	v_mfma_f32_16x16x32_bf16 v[40:43], v[168:171], v[176:179], v[40:43]
	v_mfma_f32_16x16x32_bf16 v[28:31], v[160:163], v[184:187], v[28:31]
	v_mfma_f32_16x16x32_bf16 v[24:27], v[168:171], v[184:187], v[24:27]
	v_mfma_f32_16x16x32_bf16 v[12:15], v[160:163], v[194:197], v[12:15]
	v_mfma_f32_16x16x32_bf16 v[8:11], v[168:171], v[194:197], v[8:11]
	v_mfma_f32_16x16x32_bf16 v[4:7], v[160:163], v[202:205], v[4:7]
	v_mfma_f32_16x16x32_bf16 v[0:3], v[168:171], v[202:205], v[0:3]
	v_mfma_f32_16x16x32_bf16 v[44:47], v[164:167], v[180:183], v[44:47]
	v_mfma_f32_16x16x32_bf16 v[40:43], v[172:175], v[180:183], v[40:43]
	v_mfma_f32_16x16x32_bf16 v[28:31], v[164:167], v[188:191], v[28:31]
	v_mfma_f32_16x16x32_bf16 v[24:27], v[172:175], v[188:191], v[24:27]
	v_mfma_f32_16x16x32_bf16 v[12:15], v[164:167], v[198:201], v[12:15]
	v_mfma_f32_16x16x32_bf16 v[8:11], v[172:175], v[198:201], v[8:11]
	v_mfma_f32_16x16x32_bf16 v[4:7], v[164:167], v[206:209], v[4:7]
	v_mfma_f32_16x16x32_bf16 v[0:3], v[172:175], v[206:209], v[0:3]
	s_barrier
	s_add_i32 s59, 0, 0x18000
	v_add_u32_e32 v143, s59, v140
	s_add_i32 s60, 0, 0x1c000
	ds_read_b128 v[144:147], v143
	ds_read_b128 v[148:151], v143 offset:1024
	ds_read_b128 v[152:155], v143 offset:2048
	ds_read_b128 v[156:159], v143 offset:3072
	v_add_u32_e32 v143, s60, v140
	ds_read_b128 v[160:163], v143
	ds_read_b128 v[164:167], v143 offset:1024
	ds_read_b128 v[168:171], v143 offset:2048
	ds_read_b128 v[172:175], v143 offset:3072
	s_add_u32 s28, s28, 0x40000
	s_addc_u32 s29, s29, 0
	s_mov_b32 m0, s39
	v_lshl_add_u64 v[218:219], s[28:29], 0, v[128:129]
	ds_read_b128 v[176:179], v142 offset:32768
	ds_read_b128 v[180:183], v142 offset:33792
	ds_read_b128 v[184:187], v142 offset:34816
	ds_read_b128 v[188:191], v142 offset:35840
	ds_read_b128 v[194:197], v142 offset:36864
	ds_read_b128 v[198:201], v142 offset:37888
	ds_read_b128 v[202:205], v142 offset:38912
	ds_read_b128 v[206:209], v142 offset:39936
	global_load_lds_dwordx4 v[218:219], off
	v_lshl_add_u64 v[218:219], s[28:29], 0, v[130:131]
	s_mov_b32 m0, s42
	s_nop 0
	global_load_lds_dwordx4 v[218:219], off
	s_waitcnt vmcnt(8)
	s_waitcnt lgkmcnt(0)
	s_barrier
	s_waitcnt lgkmcnt(0)
	v_mfma_f32_16x16x32_bf16 v[124:127], v[144:147], v[176:179], v[124:127]
	v_mfma_f32_16x16x32_bf16 v[120:123], v[152:155], v[176:179], v[120:123]
	v_mfma_f32_16x16x32_bf16 v[116:119], v[144:147], v[184:187], v[116:119]
	v_mfma_f32_16x16x32_bf16 v[112:115], v[152:155], v[184:187], v[112:115]
	v_mfma_f32_16x16x32_bf16 v[100:103], v[144:147], v[194:197], v[100:103]
	v_mfma_f32_16x16x32_bf16 v[96:99], v[152:155], v[194:197], v[96:99]
	v_mfma_f32_16x16x32_bf16 v[84:87], v[144:147], v[202:205], v[84:87]
	v_mfma_f32_16x16x32_bf16 v[80:83], v[152:155], v[202:205], v[80:83]
	v_mfma_f32_16x16x32_bf16 v[124:127], v[148:151], v[180:183], v[124:127]
	v_mfma_f32_16x16x32_bf16 v[120:123], v[156:159], v[180:183], v[120:123]
	v_mfma_f32_16x16x32_bf16 v[116:119], v[148:151], v[188:191], v[116:119]
	v_mfma_f32_16x16x32_bf16 v[112:115], v[156:159], v[188:191], v[112:115]
	v_mfma_f32_16x16x32_bf16 v[100:103], v[148:151], v[198:201], v[100:103]
	v_mfma_f32_16x16x32_bf16 v[96:99], v[156:159], v[198:201], v[96:99]
	v_mfma_f32_16x16x32_bf16 v[84:87], v[148:151], v[206:209], v[84:87]
	v_mfma_f32_16x16x32_bf16 v[80:83], v[156:159], v[206:209], v[80:83]
	v_mfma_f32_16x16x32_bf16 v[108:111], v[160:163], v[176:179], v[108:111]
	v_mfma_f32_16x16x32_bf16 v[104:107], v[168:171], v[176:179], v[104:107]
	v_mfma_f32_16x16x32_bf16 v[92:95], v[160:163], v[184:187], v[92:95]
	v_mfma_f32_16x16x32_bf16 v[88:91], v[168:171], v[184:187], v[88:91]
	v_mfma_f32_16x16x32_bf16 v[76:79], v[160:163], v[194:197], v[76:79]
	v_mfma_f32_16x16x32_bf16 v[72:75], v[168:171], v[194:197], v[72:75]
	v_mfma_f32_16x16x32_bf16 v[68:71], v[160:163], v[202:205], v[68:71]
	v_mfma_f32_16x16x32_bf16 v[64:67], v[168:171], v[202:205], v[64:67]
	v_mfma_f32_16x16x32_bf16 v[108:111], v[164:167], v[180:183], v[108:111]
	v_mfma_f32_16x16x32_bf16 v[104:107], v[172:175], v[180:183], v[104:107]
	v_mfma_f32_16x16x32_bf16 v[92:95], v[164:167], v[188:191], v[92:95]
	v_mfma_f32_16x16x32_bf16 v[88:91], v[172:175], v[188:191], v[88:91]
	v_mfma_f32_16x16x32_bf16 v[76:79], v[164:167], v[198:201], v[76:79]
	v_mfma_f32_16x16x32_bf16 v[72:75], v[172:175], v[198:201], v[72:75]
	v_mfma_f32_16x16x32_bf16 v[68:71], v[164:167], v[206:209], v[68:71]
	v_mfma_f32_16x16x32_bf16 v[64:67], v[172:175], v[206:209], v[64:67]
	s_barrier
; #define PG8_STAGE(bufoff, gbase, voff) do { _Pragma("unroll") for (int _i = 0; _i < 2; ++_i) \
;         __builtin_amdgcn_global_load_lds((const unsigned*)((const char*)(gbase) + (voff)[_i]), (LAS unsigned*)(lds + (bufoff) + ldsw + _i * 8192), 16, 0, 0); } while (0)
; #define PG8_LDA(dst, b, h) do { _Pragma("unroll") for (int m = 0; m < 4; ++m) _Pragma("unroll") for (int k = 0; k < 2; ++k) dst[m][k] = *(const LAS bf16x8*)(lds + PG8_SA(b, h) + aoff + m * 2048 + k * 1024); } while (0)
; #define PG8_MMA(ai, bj, At, Bt) do { __builtin_amdgcn_s_setprio(1); _Pragma("unroll") for (int m = 0; m < 4; ++m) _Pragma("unroll") for (int n = 0; n < 2; ++n) _Pragma("unroll") for (int k = 0; k < 2; ++k) \
;         acc[ai][bj][m][n] = __builtin_amdgcn_mfma_f32_16x16x32_bf16(Bt[n][k], At[m][k], acc[ai][bj][m][n], 0, 0, 0); __builtin_amdgcn_s_setprio(0); } while (0)
; #define PG8_WAIT_V(n) asm volatile("s_waitcnt vmcnt(" #n ")" ::: "memory")
; #define PG8_WAIT_L(n) asm volatile("s_waitcnt lgkmcnt(" #n ")" ::: "memory")
; #define PG8_BAR __builtin_amdgcn_s_barrier()
; #define PG8_SCHED __builtin_amdgcn_sched_barrier(0)
; template <class Epi>
; DI void gemm_phase(int wv, LAS unsigned char* lds, LAS unsigned char* scr, const Sched& S, const Epi& E) {
;     ...
;             PG8_LDA(At, 1, 1); PG8_STAGE(PG8_SB(1, 0), b3, voffB); PG8_STAGE(PG8_SB(1, 1), b3 + hstepB, voffB); PG8_STAGE(PG8_SA(1, 0), a3, voffA);
;             PG8_WAIT_V(8); PG8_WAIT_L(0); PG8_BAR; PG8_MMA(1, 0, At, B0); PG8_MMA(1, 1, At, B1); PG8_BAR; PG8_SCHED;
;         }
;         if (wr == 0) PG8_BAR;
	s_add_i32 s28, s59, s33
	v_lshl_add_u64 v[210:211], v[210:211], 0, s[2:3]
	s_mov_b32 m0, s28
	ds_read_b128 v[176:179], v142 offset:49152
	ds_read_b128 v[180:183], v142 offset:50176
	ds_read_b128 v[184:187], v142 offset:51200
	ds_read_b128 v[188:191], v142 offset:52224
	ds_read_b128 v[194:197], v142 offset:53248
	ds_read_b128 v[198:201], v142 offset:54272
	ds_read_b128 v[202:205], v142 offset:55296
	ds_read_b128 v[206:209], v142 offset:56320
	global_load_lds_dwordx4 v[210:211], off
	s_add_i32 m0, s28, 0x2000
	s_add_u32 s26, s26, 0x400080
	v_lshl_add_u64 v[210:211], v[212:213], 0, s[2:3]
	s_addc_u32 s27, s27, 0
	s_add_i32 s28, s60, s33
	global_load_lds_dwordx4 v[210:211], off
	v_lshl_add_u64 v[210:211], s[26:27], 0, v[192:193]
	s_mov_b32 m0, s28
	s_nop 0
	global_load_lds_dwordx4 v[210:211], off
	v_lshl_add_u64 v[210:211], s[26:27], 0, v[132:133]
	s_add_i32 m0, s28, 0x2000
	s_nop 0
	global_load_lds_dwordx4 v[210:211], off
	v_lshl_add_u64 v[210:211], v[214:215], 0, s[2:3]
	s_mov_b32 m0, s43
	s_nop 0
	global_load_lds_dwordx4 v[210:211], off
	v_lshl_add_u64 v[210:211], v[216:217], 0, s[2:3]
	s_mov_b32 m0, s44
	s_nop 0
	global_load_lds_dwordx4 v[210:211], off
	s_waitcnt vmcnt(8)
	s_waitcnt lgkmcnt(0)
	s_barrier
	s_waitcnt lgkmcnt(0)
	v_mfma_f32_16x16x32_bf16 v[60:63], v[144:147], v[176:179], v[60:63]
	v_mfma_f32_16x16x32_bf16 v[56:59], v[152:155], v[176:179], v[56:59]
	v_mfma_f32_16x16x32_bf16 v[52:55], v[144:147], v[184:187], v[52:55]
	v_mfma_f32_16x16x32_bf16 v[48:51], v[152:155], v[184:187], v[48:51]
	v_mfma_f32_16x16x32_bf16 v[36:39], v[144:147], v[194:197], v[36:39]
	v_mfma_f32_16x16x32_bf16 v[32:35], v[152:155], v[194:197], v[32:35]
	v_mfma_f32_16x16x32_bf16 v[20:23], v[144:147], v[202:205], v[20:23]
	v_mfma_f32_16x16x32_bf16 v[16:19], v[152:155], v[202:205], v[16:19]
	v_mfma_f32_16x16x32_bf16 v[60:63], v[148:151], v[180:183], v[60:63]
	v_mfma_f32_16x16x32_bf16 v[56:59], v[156:159], v[180:183], v[56:59]
	v_mfma_f32_16x16x32_bf16 v[52:55], v[148:151], v[188:191], v[52:55]
	v_mfma_f32_16x16x32_bf16 v[48:51], v[156:159], v[188:191], v[48:51]
	v_mfma_f32_16x16x32_bf16 v[36:39], v[148:151], v[198:201], v[36:39]
	v_mfma_f32_16x16x32_bf16 v[32:35], v[156:159], v[198:201], v[32:35]
	v_mfma_f32_16x16x32_bf16 v[20:23], v[148:151], v[206:209], v[20:23]
	v_mfma_f32_16x16x32_bf16 v[16:19], v[156:159], v[206:209], v[16:19]
	v_mfma_f32_16x16x32_bf16 v[44:47], v[160:163], v[176:179], v[44:47]
	v_mfma_f32_16x16x32_bf16 v[40:43], v[168:171], v[176:179], v[40:43]
	v_mfma_f32_16x16x32_bf16 v[28:31], v[160:163], v[184:187], v[28:31]
	v_mfma_f32_16x16x32_bf16 v[24:27], v[168:171], v[184:187], v[24:27]
	v_mfma_f32_16x16x32_bf16 v[12:15], v[160:163], v[194:197], v[12:15]
	v_mfma_f32_16x16x32_bf16 v[8:11], v[168:171], v[194:197], v[8:11]
	v_mfma_f32_16x16x32_bf16 v[4:7], v[160:163], v[202:205], v[4:7]
	v_mfma_f32_16x16x32_bf16 v[0:3], v[168:171], v[202:205], v[0:3]
	v_mfma_f32_16x16x32_bf16 v[44:47], v[164:167], v[180:183], v[44:47]
	v_mfma_f32_16x16x32_bf16 v[40:43], v[172:175], v[180:183], v[40:43]
	v_mfma_f32_16x16x32_bf16 v[28:31], v[164:167], v[188:191], v[28:31]
	v_mfma_f32_16x16x32_bf16 v[24:27], v[172:175], v[188:191], v[24:27]
	v_mfma_f32_16x16x32_bf16 v[12:15], v[164:167], v[198:201], v[12:15]
	v_mfma_f32_16x16x32_bf16 v[8:11], v[172:175], v[198:201], v[8:11]
	v_mfma_f32_16x16x32_bf16 v[4:7], v[164:167], v[206:209], v[4:7]
	v_mfma_f32_16x16x32_bf16 v[0:3], v[172:175], v[206:209], v[0:3]
	s_barrier
	s_add_i32 s55, s55, 2
	s_add_u32 s51, s51, 0x100
	s_addc_u32 s54, s54, 0
	s_add_u32 s6, s6, 0x100
	s_addc_u32 s7, s7, 0
	s_cmp_gt_u32 s55, 13
	s_cbranch_scc0 .LBB0_189
	s_and_b64 vcc, exec, s[18:19]
	s_cbranch_vccz .LBB0_192
	s_barrier

; #define PG8_STAGE(bufoff, gbase, voff) do { _Pragma("unroll") for (int _i = 0; _i < 2; ++_i) \
;         __builtin_amdgcn_global_load_lds((const unsigned*)((const char*)(gbase) + (voff)[_i]), (LAS unsigned*)(lds + (bufoff) + ldsw + _i * 8192), 16, 0, 0); } while (0)
; #define PG8_LDA(dst, b, h) do { _Pragma("unroll") for (int m = 0; m < 4; ++m) _Pragma("unroll") for (int k = 0; k < 2; ++k) dst[m][k] = *(const LAS bf16x8*)(lds + PG8_SA(b, h) + aoff + m * 2048 + k * 1024); } while (0)
; #define PG8_LDB(dst, b, h) do { _Pragma("unroll") for (int n = 0; n < 2; ++n) _Pragma("unroll") for (int k = 0; k < 2; ++k) dst[n][k] = *(const LAS bf16x8*)(lds + PG8_SB(b, h) + boff + n * 2048 + k * 1024); } while (0)
; #define PG8_MMA(ai, bj, At, Bt) do { __builtin_amdgcn_s_setprio(1); _Pragma("unroll") for (int m = 0; m < 4; ++m) _Pragma("unroll") for (int n = 0; n < 2; ++n) _Pragma("unroll") for (int k = 0; k < 2; ++k) \
;         acc[ai][bj][m][n] = __builtin_amdgcn_mfma_f32_16x16x32_bf16(Bt[n][k], At[m][k], acc[ai][bj][m][n], 0, 0, 0); __builtin_amdgcn_s_setprio(0); } while (0)
; #define PG8_WAIT_V(n) asm volatile("s_waitcnt vmcnt(" #n ")" ::: "memory")
; #define PG8_WAIT_L(n) asm volatile("s_waitcnt lgkmcnt(" #n ")" ::: "memory")
; #define PG8_BAR __builtin_amdgcn_s_barrier()
; #define PG8_SCHED __builtin_amdgcn_sched_barrier(0)
; template <class Epi>
; DI void gemm_phase(int wv, LAS unsigned char* lds, LAS unsigned char* scr, const Sched& S, const Epi& E) {
;     ...
;             const bool last = (t == nt - 2);
;             const char* a1 = cA + (size_t)(t + 1) * kstep;
;             const char* a2 = last ? nA : cA + (size_t)(t + 2) * kstep; const char* b2 = last ? nB : cB + (size_t)(t + 2) * kstep;
;             const char* a3 = a2 + kstep; const char* b3 = b2 + kstep;
;             PG8_LDB(B0, 0, 0); PG8_LDB(B1, 0, 1); PG8_SCHED; PG8_LDA(At, 0, 0); PG8_STAGE(PG8_SA(1, 1), a1 + hstepA, voffA);
;             PG8_WAIT_V(8); PG8_WAIT_L(0); PG8_BAR; PG8_MMA(0, 0, At, B0); PG8_MMA(0, 1, At, B1); PG8_BAR; PG8_SCHED;
;             PG8_LDA(At, 0, 1); PG8_STAGE(PG8_SB(0, 0), b2, voffB); PG8_STAGE(PG8_SB(0, 1), b2 + hstepB, voffB); PG8_STAGE(PG8_SA(0, 0), a2, voffA);
.LBB0_256:
	s_add_u32 s21, s16, s13
	s_addc_u32 s23, s17, 0
	s_add_u32 s30, s21, 0x100
	s_addc_u32 s31, s23, 0
	s_and_b64 s[28:29], s[26:27], exec
	s_cselect_b32 s31, s9, s31
	s_cselect_b32 s30, s8, s30
	s_add_u32 s13, s18, s13
	s_addc_u32 s28, s19, 0
	s_add_u32 s13, s13, 0x100
	s_addc_u32 s28, s28, 0
	s_add_i32 s64, 0, 0x10000
	s_and_b64 s[26:27], s[26:27], exec
	s_cselect_b32 s35, s15, s28
	s_cselect_b32 s34, s14, s13
	s_add_i32 s27, 0, 0x14000
	s_add_u32 s38, s21, 0x40080
	s_addc_u32 s39, s23, 0
	s_add_i32 s63, s64, s45
	s_add_i32 m0, s46, 0xc000
	s_add_i32 s66, s46, 0xe000
	s_add_i32 s60, s63, 0x2000
	v_add_u32_e32 v138, s64, v140
	s_add_u32 s36, s34, 0x40000
	ds_read_b128 v[142:145], v138
	ds_read_b128 v[146:149], v138 offset:1024
	ds_read_b128 v[150:153], v138 offset:2048
	ds_read_b128 v[154:157], v138 offset:3072
	v_add_u32_e32 v138, s27, v140
	s_addc_u32 s37, s35, 0
	s_add_i32 s62, s27, s45
	ds_read_b128 v[158:161], v138
	ds_read_b128 v[162:165], v138 offset:1024
	ds_read_b128 v[166:169], v138 offset:2048
	ds_read_b128 v[170:173], v138 offset:3072
	s_add_i32 s61, s62, 0x2000
	s_add_i32 s59, 0, 0x18000
	s_add_i32 s23, 0, 0x1c000
	s_add_u32 s28, s30, 0x40000
	s_addc_u32 s29, s31, 0
	s_add_i32 s21, s59, s45
	s_add_i32 s13, s21, 0x2000
	s_add_u32 s26, s34, 0x40080
	s_addc_u32 s27, s35, 0
	s_add_i32 s65, s23, s45
	s_add_i32 s64, s65, 0x2000
	v_lshl_add_u64 v[138:139], s[38:39], 0, v[134:135]
	ds_read_b128 v[174:177], v141
	ds_read_b128 v[178:181], v141 offset:1024
	ds_read_b128 v[182:185], v141 offset:2048
	ds_read_b128 v[186:189], v141 offset:3072
	ds_read_b128 v[194:197], v141 offset:4096
	ds_read_b128 v[198:201], v141 offset:5120
	ds_read_b128 v[202:205], v141 offset:6144
	ds_read_b128 v[206:209], v141 offset:7168
	global_load_lds_dwordx4 v[138:139], off
	v_lshl_add_u64 v[138:139], s[38:39], 0, v[130:131]
	s_mov_b32 m0, s66
	s_nop 0
	global_load_lds_dwordx4 v[138:139], off
	s_waitcnt vmcnt(8)
	s_waitcnt lgkmcnt(0)
	s_barrier
	s_waitcnt lgkmcnt(0)
	v_mfma_f32_16x16x32_bf16 v[124:127], v[142:145], v[174:177], v[124:127]
	v_mfma_f32_16x16x32_bf16 v[120:123], v[150:153], v[174:177], v[120:123]
	v_mfma_f32_16x16x32_bf16 v[116:119], v[142:145], v[182:185], v[116:119]
	v_mfma_f32_16x16x32_bf16 v[108:111], v[150:153], v[182:185], v[108:111]
	v_mfma_f32_16x16x32_bf16 v[100:103], v[142:145], v[194:197], v[100:103]
	v_mfma_f32_16x16x32_bf16 v[92:95], v[150:153], v[194:197], v[92:95]
	v_mfma_f32_16x16x32_bf16 v[84:87], v[142:145], v[202:205], v[84:87]
	v_mfma_f32_16x16x32_bf16 v[76:79], v[150:153], v[202:205], v[76:79]
	v_mfma_f32_16x16x32_bf16 v[124:127], v[146:149], v[178:181], v[124:127]
	v_mfma_f32_16x16x32_bf16 v[120:123], v[154:157], v[178:181], v[120:123]
	v_mfma_f32_16x16x32_bf16 v[116:119], v[146:149], v[186:189], v[116:119]
	v_mfma_f32_16x16x32_bf16 v[108:111], v[154:157], v[186:189], v[108:111]
	v_mfma_f32_16x16x32_bf16 v[100:103], v[146:149], v[198:201], v[100:103]
	v_mfma_f32_16x16x32_bf16 v[92:95], v[154:157], v[198:201], v[92:95]
	v_mfma_f32_16x16x32_bf16 v[84:87], v[146:149], v[206:209], v[84:87]
	v_mfma_f32_16x16x32_bf16 v[76:79], v[154:157], v[206:209], v[76:79]
	v_mfma_f32_16x16x32_bf16 v[112:115], v[158:161], v[174:177], v[112:115]
	v_mfma_f32_16x16x32_bf16 v[104:107], v[166:169], v[174:177], v[104:107]
	v_mfma_f32_16x16x32_bf16 v[96:99], v[158:161], v[182:185], v[96:99]
	v_mfma_f32_16x16x32_bf16 v[88:91], v[166:169], v[182:185], v[88:91]
	v_mfma_f32_16x16x32_bf16 v[80:83], v[158:161], v[194:197], v[80:83]
	v_mfma_f32_16x16x32_bf16 v[72:75], v[166:169], v[194:197], v[72:75]
	v_mfma_f32_16x16x32_bf16 v[68:71], v[158:161], v[202:205], v[68:71]
	v_mfma_f32_16x16x32_bf16 v[64:67], v[166:169], v[202:205], v[64:67]
	v_mfma_f32_16x16x32_bf16 v[112:115], v[162:165], v[178:181], v[112:115]
	v_mfma_f32_16x16x32_bf16 v[104:107], v[170:173], v[178:181], v[104:107]
	v_mfma_f32_16x16x32_bf16 v[96:99], v[162:165], v[186:189], v[96:99]
	v_mfma_f32_16x16x32_bf16 v[88:91], v[170:173], v[186:189], v[88:91]
	v_mfma_f32_16x16x32_bf16 v[80:83], v[162:165], v[198:201], v[80:83]
	v_mfma_f32_16x16x32_bf16 v[72:75], v[170:173], v[198:201], v[72:75]
	v_mfma_f32_16x16x32_bf16 v[68:71], v[162:165], v[206:209], v[68:71]
	v_mfma_f32_16x16x32_bf16 v[64:67], v[170:173], v[206:209], v[64:67]
	s_barrier
	s_mov_b32 m0, s63
	v_lshl_add_u64 v[138:139], s[34:35], 0, v[132:133]
	ds_read_b128 v[174:177], v141 offset:16384
	ds_read_b128 v[178:181], v141 offset:17408
	ds_read_b128 v[182:185], v141 offset:18432
	ds_read_b128 v[186:189], v141 offset:19456
	ds_read_b128 v[194:197], v141 offset:20480
	ds_read_b128 v[198:201], v141 offset:21504
	ds_read_b128 v[202:205], v141 offset:22528
	ds_read_b128 v[206:209], v141 offset:23552
	global_load_lds_dwordx4 v[138:139], off
	v_lshl_add_u64 v[190:191], s[34:35], 0, v[128:129]
	s_mov_b32 m0, s60
	v_lshl_add_u64 v[210:211], s[36:37], 0, v[132:133]
	global_load_lds_dwordx4 v[190:191], off
	s_mov_b32 m0, s62
	v_lshl_add_u64 v[212:213], s[30:31], 0, v[130:131]
	global_load_lds_dwordx4 v[210:211], off
	v_lshl_add_u64 v[210:211], s[36:37], 0, v[128:129]
	s_mov_b32 m0, s61
	s_nop 0
	global_load_lds_dwordx4 v[210:211], off
	v_lshl_add_u64 v[210:211], s[30:31], 0, v[134:135]
	s_mov_b32 m0, s46
	s_nop 0
	global_load_lds_dwordx4 v[210:211], off
	s_mov_b32 m0, s47
	s_nop 0
	global_load_lds_dwordx4 v[212:213], off
	s_waitcnt vmcnt(8)
	s_waitcnt lgkmcnt(0)
	s_barrier
; #define PG8_STAGE(bufoff, gbase, voff) do { _Pragma("unroll") for (int _i = 0; _i < 2; ++_i) \
;         __builtin_amdgcn_global_load_lds((const unsigned*)((const char*)(gbase) + (voff)[_i]), (LAS unsigned*)(lds + (bufoff) + ldsw + _i * 8192), 16, 0, 0); } while (0)
; #define PG8_LDA(dst, b, h) do { _Pragma("unroll") for (int m = 0; m < 4; ++m) _Pragma("unroll") for (int k = 0; k < 2; ++k) dst[m][k] = *(const LAS bf16x8*)(lds + PG8_SA(b, h) + aoff + m * 2048 + k * 1024); } while (0)
; #define PG8_LDB(dst, b, h) do { _Pragma("unroll") for (int n = 0; n < 2; ++n) _Pragma("unroll") for (int k = 0; k < 2; ++k) dst[n][k] = *(const LAS bf16x8*)(lds + PG8_SB(b, h) + boff + n * 2048 + k * 1024); } while (0)
; #define PG8_MMA(ai, bj, At, Bt) do { __builtin_amdgcn_s_setprio(1); _Pragma("unroll") for (int m = 0; m < 4; ++m) _Pragma("unroll") for (int n = 0; n < 2; ++n) _Pragma("unroll") for (int k = 0; k < 2; ++k) \
;         acc[ai][bj][m][n] = __builtin_amdgcn_mfma_f32_16x16x32_bf16(Bt[n][k], At[m][k], acc[ai][bj][m][n], 0, 0, 0); __builtin_amdgcn_s_setprio(0); } while (0)
; #define PG8_WAIT_V(n) asm volatile("s_waitcnt vmcnt(" #n ")" ::: "memory")
; #define PG8_WAIT_L(n) asm volatile("s_waitcnt lgkmcnt(" #n ")" ::: "memory")
; #define PG8_BAR __builtin_amdgcn_s_barrier()
; #define PG8_SCHED __builtin_amdgcn_sched_barrier(0)
; template <class Epi>
; DI void gemm_phase(int wv, LAS unsigned char* lds, LAS unsigned char* scr, const Sched& S, const Epi& E) {
;     ...
;             PG8_WAIT_V(8); PG8_WAIT_L(0); PG8_BAR; PG8_MMA(1, 0, At, B0); PG8_MMA(1, 1, At, B1); PG8_BAR; PG8_SCHED;
;             PG8_LDB(B0, 1, 0); PG8_LDB(B1, 1, 1); PG8_SCHED; PG8_LDA(At, 1, 0); PG8_STAGE(PG8_SA(0, 1), a2 + hstepA, voffA);
;             PG8_WAIT_V(8); PG8_WAIT_L(0); PG8_BAR; PG8_MMA(0, 0, At, B0); PG8_MMA(0, 1, At, B1); PG8_BAR; PG8_SCHED;
	s_waitcnt lgkmcnt(0)
	v_mfma_f32_16x16x32_bf16 v[60:63], v[142:145], v[174:177], v[60:63]
	v_mfma_f32_16x16x32_bf16 v[56:59], v[150:153], v[174:177], v[56:59]
	v_mfma_f32_16x16x32_bf16 v[52:55], v[142:145], v[182:185], v[52:55]
	v_mfma_f32_16x16x32_bf16 v[44:47], v[150:153], v[182:185], v[44:47]
	v_mfma_f32_16x16x32_bf16 v[36:39], v[142:145], v[194:197], v[36:39]
	v_mfma_f32_16x16x32_bf16 v[28:31], v[150:153], v[194:197], v[28:31]
	v_mfma_f32_16x16x32_bf16 v[20:23], v[142:145], v[202:205], v[20:23]
	v_mfma_f32_16x16x32_bf16 v[12:15], v[150:153], v[202:205], v[12:15]
	v_mfma_f32_16x16x32_bf16 v[60:63], v[146:149], v[178:181], v[60:63]
	v_mfma_f32_16x16x32_bf16 v[56:59], v[154:157], v[178:181], v[56:59]
	v_mfma_f32_16x16x32_bf16 v[52:55], v[146:149], v[186:189], v[52:55]
	v_mfma_f32_16x16x32_bf16 v[44:47], v[154:157], v[186:189], v[44:47]
	v_mfma_f32_16x16x32_bf16 v[36:39], v[146:149], v[198:201], v[36:39]
	v_mfma_f32_16x16x32_bf16 v[28:31], v[154:157], v[198:201], v[28:31]
	v_mfma_f32_16x16x32_bf16 v[20:23], v[146:149], v[206:209], v[20:23]
	v_mfma_f32_16x16x32_bf16 v[12:15], v[154:157], v[206:209], v[12:15]
	v_mfma_f32_16x16x32_bf16 v[48:51], v[158:161], v[174:177], v[48:51]
	v_mfma_f32_16x16x32_bf16 v[40:43], v[166:169], v[174:177], v[40:43]
	v_mfma_f32_16x16x32_bf16 v[32:35], v[158:161], v[182:185], v[32:35]
	v_mfma_f32_16x16x32_bf16 v[24:27], v[166:169], v[182:185], v[24:27]
	v_mfma_f32_16x16x32_bf16 v[16:19], v[158:161], v[194:197], v[16:19]
	v_mfma_f32_16x16x32_bf16 v[8:11], v[166:169], v[194:197], v[8:11]
	v_mfma_f32_16x16x32_bf16 v[4:7], v[158:161], v[202:205], v[4:7]
	v_mfma_f32_16x16x32_bf16 v[0:3], v[166:169], v[202:205], v[0:3]
	v_mfma_f32_16x16x32_bf16 v[48:51], v[162:165], v[178:181], v[48:51]
	v_mfma_f32_16x16x32_bf16 v[40:43], v[170:173], v[178:181], v[40:43]
	v_mfma_f32_16x16x32_bf16 v[32:35], v[162:165], v[186:189], v[32:35]
	v_mfma_f32_16x16x32_bf16 v[24:27], v[170:173], v[186:189], v[24:27]
	v_mfma_f32_16x16x32_bf16 v[16:19], v[162:165], v[198:201], v[16:19]
	v_mfma_f32_16x16x32_bf16 v[8:11], v[170:173], v[198:201], v[8:11]
	v_mfma_f32_16x16x32_bf16 v[4:7], v[162:165], v[206:209], v[4:7]
	v_mfma_f32_16x16x32_bf16 v[0:3], v[170:173], v[206:209], v[0:3]
	s_barrier
	v_add_u32_e32 v154, s59, v140
	v_add_u32_e32 v170, s23, v140
	ds_read_b128 v[142:145], v154
	ds_read_b128 v[146:149], v154 offset:1024
	ds_read_b128 v[150:153], v154 offset:2048
	ds_read_b128 v[154:157], v154 offset:3072
	ds_read_b128 v[158:161], v170
	ds_read_b128 v[162:165], v170 offset:1024
	ds_read_b128 v[166:169], v170 offset:2048
	ds_read_b128 v[170:173], v170 offset:3072
	s_mov_b32 m0, s48
	v_lshl_add_u64 v[214:215], s[28:29], 0, v[134:135]
	ds_read_b128 v[174:177], v141 offset:32768
	ds_read_b128 v[178:181], v141 offset:33792
	ds_read_b128 v[182:185], v141 offset:34816
	ds_read_b128 v[186:189], v141 offset:35840
	ds_read_b128 v[194:197], v141 offset:36864
	ds_read_b128 v[198:201], v141 offset:37888
	ds_read_b128 v[202:205], v141 offset:38912
	ds_read_b128 v[206:209], v141 offset:39936
	global_load_lds_dwordx4 v[214:215], off
	v_lshl_add_u64 v[214:215], s[28:29], 0, v[130:131]
	s_mov_b32 m0, s49
	s_nop 0
	global_load_lds_dwordx4 v[214:215], off
	s_waitcnt vmcnt(8)
	s_waitcnt lgkmcnt(0)
	s_barrier
	s_waitcnt lgkmcnt(0)
	v_mfma_f32_16x16x32_bf16 v[124:127], v[142:145], v[174:177], v[124:127]
	v_mfma_f32_16x16x32_bf16 v[120:123], v[150:153], v[174:177], v[120:123]
	v_mfma_f32_16x16x32_bf16 v[116:119], v[142:145], v[182:185], v[116:119]
	v_mfma_f32_16x16x32_bf16 v[108:111], v[150:153], v[182:185], v[108:111]
	v_mfma_f32_16x16x32_bf16 v[100:103], v[142:145], v[194:197], v[100:103]
	v_mfma_f32_16x16x32_bf16 v[92:95], v[150:153], v[194:197], v[92:95]
	v_mfma_f32_16x16x32_bf16 v[84:87], v[142:145], v[202:205], v[84:87]
	v_mfma_f32_16x16x32_bf16 v[76:79], v[150:153], v[202:205], v[76:79]
	v_mfma_f32_16x16x32_bf16 v[124:127], v[146:149], v[178:181], v[124:127]
	v_mfma_f32_16x16x32_bf16 v[120:123], v[154:157], v[178:181], v[120:123]
	v_mfma_f32_16x16x32_bf16 v[116:119], v[146:149], v[186:189], v[116:119]
	v_mfma_f32_16x16x32_bf16 v[108:111], v[154:157], v[186:189], v[108:111]
	v_mfma_f32_16x16x32_bf16 v[100:103], v[146:149], v[198:201], v[100:103]
	v_mfma_f32_16x16x32_bf16 v[92:95], v[154:157], v[198:201], v[92:95]
	v_mfma_f32_16x16x32_bf16 v[84:87], v[146:149], v[206:209], v[84:87]
	v_mfma_f32_16x16x32_bf16 v[76:79], v[154:157], v[206:209], v[76:79]
	v_mfma_f32_16x16x32_bf16 v[112:115], v[158:161], v[174:177], v[112:115]
	v_mfma_f32_16x16x32_bf16 v[104:107], v[166:169], v[174:177], v[104:107]
	v_mfma_f32_16x16x32_bf16 v[96:99], v[158:161], v[182:185], v[96:99]
	v_mfma_f32_16x16x32_bf16 v[88:91], v[166:169], v[182:185], v[88:91]
	v_mfma_f32_16x16x32_bf16 v[80:83], v[158:161], v[194:197], v[80:83]
	v_mfma_f32_16x16x32_bf16 v[72:75], v[166:169], v[194:197], v[72:75]
	v_mfma_f32_16x16x32_bf16 v[68:71], v[158:161], v[202:205], v[68:71]
	v_mfma_f32_16x16x32_bf16 v[64:67], v[166:169], v[202:205], v[64:67]
	v_mfma_f32_16x16x32_bf16 v[112:115], v[162:165], v[178:181], v[112:115]
	v_mfma_f32_16x16x32_bf16 v[104:107], v[170:173], v[178:181], v[104:107]
	v_mfma_f32_16x16x32_bf16 v[96:99], v[162:165], v[186:189], v[96:99]
	v_mfma_f32_16x16x32_bf16 v[88:91], v[170:173], v[186:189], v[88:91]
	v_mfma_f32_16x16x32_bf16 v[80:83], v[162:165], v[198:201], v[80:83]
	v_mfma_f32_16x16x32_bf16 v[72:75], v[170:173], v[198:201], v[72:75]
	v_mfma_f32_16x16x32_bf16 v[68:71], v[162:165], v[206:209], v[68:71]
	v_mfma_f32_16x16x32_bf16 v[64:67], v[170:173], v[206:209], v[64:67]
	s_barrier
; #define PG8_STAGE(bufoff, gbase, voff) do { _Pragma("unroll") for (int _i = 0; _i < 2; ++_i) \
;         __builtin_amdgcn_global_load_lds((const unsigned*)((const char*)(gbase) + (voff)[_i]), (LAS unsigned*)(lds + (bufoff) + ldsw + _i * 8192), 16, 0, 0); } while (0)
; #define PG8_LDA(dst, b, h) do { _Pragma("unroll") for (int m = 0; m < 4; ++m) _Pragma("unroll") for (int k = 0; k < 2; ++k) dst[m][k] = *(const LAS bf16x8*)(lds + PG8_SA(b, h) + aoff + m * 2048 + k * 1024); } while (0)
; #define PG8_MMA(ai, bj, At, Bt) do { __builtin_amdgcn_s_setprio(1); _Pragma("unroll") for (int m = 0; m < 4; ++m) _Pragma("unroll") for (int n = 0; n < 2; ++n) _Pragma("unroll") for (int k = 0; k < 2; ++k) \
;         acc[ai][bj][m][n] = __builtin_amdgcn_mfma_f32_16x16x32_bf16(Bt[n][k], At[m][k], acc[ai][bj][m][n], 0, 0, 0); __builtin_amdgcn_s_setprio(0); } while (0)
; #define PG8_WAIT_V(n) asm volatile("s_waitcnt vmcnt(" #n ")" ::: "memory")
; #define PG8_WAIT_L(n) asm volatile("s_waitcnt lgkmcnt(" #n ")" ::: "memory")
; #define PG8_BAR __builtin_amdgcn_s_barrier()
; #define PG8_SCHED __builtin_amdgcn_sched_barrier(0)
; template <class Epi>
; DI void gemm_phase(int wv, LAS unsigned char* lds, LAS unsigned char* scr, const Sched& S, const Epi& E) {
;     ...
;             PG8_LDA(At, 1, 1); PG8_STAGE(PG8_SB(1, 0), b3, voffB); PG8_STAGE(PG8_SB(1, 1), b3 + hstepB, voffB); PG8_STAGE(PG8_SA(1, 0), a3, voffA);
;             PG8_WAIT_V(8); PG8_WAIT_L(0); PG8_BAR; PG8_MMA(1, 0, At, B0); PG8_MMA(1, 1, At, B1); PG8_BAR; PG8_SCHED;
;         }
;         if (wr == 0) PG8_BAR;
	s_mov_b32 m0, s21
	v_lshl_add_u64 v[138:139], v[138:139], 0, s[2:3]
	ds_read_b128 v[174:177], v141 offset:49152
	ds_read_b128 v[178:181], v141 offset:50176
	ds_read_b128 v[182:185], v141 offset:51200
	ds_read_b128 v[186:189], v141 offset:52224
	ds_read_b128 v[194:197], v141 offset:53248
	ds_read_b128 v[198:201], v141 offset:54272
	ds_read_b128 v[202:205], v141 offset:55296
	ds_read_b128 v[206:209], v141 offset:56320
	global_load_lds_dwordx4 v[138:139], off
	v_lshl_add_u64 v[138:139], v[190:191], 0, s[2:3]
	s_mov_b32 m0, s13
	s_nop 0
	global_load_lds_dwordx4 v[138:139], off
	v_lshl_add_u64 v[138:139], s[26:27], 0, v[132:133]
	s_mov_b32 m0, s65
	s_nop 0
	global_load_lds_dwordx4 v[138:139], off
	v_lshl_add_u64 v[138:139], s[26:27], 0, v[128:129]
	s_mov_b32 m0, s64
	s_nop 0
	global_load_lds_dwordx4 v[138:139], off
	v_lshl_add_u64 v[138:139], v[210:211], 0, s[2:3]
	s_mov_b32 m0, s52
	s_nop 0
	global_load_lds_dwordx4 v[138:139], off
	v_lshl_add_u64 v[138:139], v[212:213], 0, s[2:3]
	s_mov_b32 m0, s53
	s_nop 0
	global_load_lds_dwordx4 v[138:139], off
	s_waitcnt vmcnt(8)
	s_waitcnt lgkmcnt(0)
	s_barrier
	s_waitcnt lgkmcnt(0)
	v_mfma_f32_16x16x32_bf16 v[60:63], v[142:145], v[174:177], v[60:63]
	v_mfma_f32_16x16x32_bf16 v[56:59], v[150:153], v[174:177], v[56:59]
	v_mfma_f32_16x16x32_bf16 v[52:55], v[142:145], v[182:185], v[52:55]
	v_mfma_f32_16x16x32_bf16 v[44:47], v[150:153], v[182:185], v[44:47]
	v_mfma_f32_16x16x32_bf16 v[36:39], v[142:145], v[194:197], v[36:39]
	v_mfma_f32_16x16x32_bf16 v[28:31], v[150:153], v[194:197], v[28:31]
	v_mfma_f32_16x16x32_bf16 v[20:23], v[142:145], v[202:205], v[20:23]
	v_mfma_f32_16x16x32_bf16 v[12:15], v[150:153], v[202:205], v[12:15]
	v_mfma_f32_16x16x32_bf16 v[60:63], v[146:149], v[178:181], v[60:63]
	v_mfma_f32_16x16x32_bf16 v[56:59], v[154:157], v[178:181], v[56:59]
	v_mfma_f32_16x16x32_bf16 v[52:55], v[146:149], v[186:189], v[52:55]
	v_mfma_f32_16x16x32_bf16 v[44:47], v[154:157], v[186:189], v[44:47]
	v_mfma_f32_16x16x32_bf16 v[36:39], v[146:149], v[198:201], v[36:39]
	v_mfma_f32_16x16x32_bf16 v[28:31], v[154:157], v[198:201], v[28:31]
	v_mfma_f32_16x16x32_bf16 v[20:23], v[146:149], v[206:209], v[20:23]
	v_mfma_f32_16x16x32_bf16 v[12:15], v[154:157], v[206:209], v[12:15]
	v_mfma_f32_16x16x32_bf16 v[48:51], v[158:161], v[174:177], v[48:51]
	v_mfma_f32_16x16x32_bf16 v[40:43], v[166:169], v[174:177], v[40:43]
	v_mfma_f32_16x16x32_bf16 v[32:35], v[158:161], v[182:185], v[32:35]
	v_mfma_f32_16x16x32_bf16 v[24:27], v[166:169], v[182:185], v[24:27]
	v_mfma_f32_16x16x32_bf16 v[16:19], v[158:161], v[194:197], v[16:19]
	v_mfma_f32_16x16x32_bf16 v[8:11], v[166:169], v[194:197], v[8:11]
	v_mfma_f32_16x16x32_bf16 v[4:7], v[158:161], v[202:205], v[4:7]
	v_mfma_f32_16x16x32_bf16 v[0:3], v[166:169], v[202:205], v[0:3]
	v_mfma_f32_16x16x32_bf16 v[48:51], v[162:165], v[178:181], v[48:51]
	v_mfma_f32_16x16x32_bf16 v[40:43], v[170:173], v[178:181], v[40:43]
	v_mfma_f32_16x16x32_bf16 v[32:35], v[162:165], v[186:189], v[32:35]
	v_mfma_f32_16x16x32_bf16 v[24:27], v[170:173], v[186:189], v[24:27]
	v_mfma_f32_16x16x32_bf16 v[16:19], v[162:165], v[198:201], v[16:19]
	v_mfma_f32_16x16x32_bf16 v[8:11], v[170:173], v[198:201], v[8:11]
	v_mfma_f32_16x16x32_bf16 v[4:7], v[162:165], v[206:209], v[4:7]
	v_mfma_f32_16x16x32_bf16 v[0:3], v[170:173], v[206:209], v[0:3]
	s_barrier
	s_movk_i32 s13, 0x100
	s_andn2_b64 vcc, exec, s[24:25]
	s_mov_b64 s[26:27], -1
	s_mov_b64 s[24:25], 0
	s_cbranch_vccz .LBB0_256
	s_and_b64 vcc, exec, s[10:11]
	s_cbranch_vccz .LBB0_259
	s_barrier

; #define PG8_STAGE(bufoff, gbase, voff) do { _Pragma("unroll") for (int _i = 0; _i < 2; ++_i) \
;         __builtin_amdgcn_global_load_lds((const unsigned*)((const char*)(gbase) + (voff)[_i]), (LAS unsigned*)(lds + (bufoff) + ldsw + _i * 8192), 16, 0, 0); } while (0)
; #define PG8_LDA(dst, b, h) do { _Pragma("unroll") for (int m = 0; m < 4; ++m) _Pragma("unroll") for (int k = 0; k < 2; ++k) dst[m][k] = *(const LAS bf16x8*)(lds + PG8_SA(b, h) + aoff + m * 2048 + k * 1024); } while (0)
; #define PG8_LDB(dst, b, h) do { _Pragma("unroll") for (int n = 0; n < 2; ++n) _Pragma("unroll") for (int k = 0; k < 2; ++k) dst[n][k] = *(const LAS bf16x8*)(lds + PG8_SB(b, h) + boff + n * 2048 + k * 1024); } while (0)
; #define PG8_MMA(ai, bj, At, Bt) do { __builtin_amdgcn_s_setprio(1); _Pragma("unroll") for (int m = 0; m < 4; ++m) _Pragma("unroll") for (int n = 0; n < 2; ++n) _Pragma("unroll") for (int k = 0; k < 2; ++k) \
;         acc[ai][bj][m][n] = __builtin_amdgcn_mfma_f32_16x16x32_bf16(Bt[n][k], At[m][k], acc[ai][bj][m][n], 0, 0, 0); __builtin_amdgcn_s_setprio(0); } while (0)
; #define PG8_WAIT_V(n) asm volatile("s_waitcnt vmcnt(" #n ")" ::: "memory")
; #define PG8_WAIT_L(n) asm volatile("s_waitcnt lgkmcnt(" #n ")" ::: "memory")
; #define PG8_BAR __builtin_amdgcn_s_barrier()
; #define PG8_SCHED __builtin_amdgcn_sched_barrier(0)
; template <class Epi>
; DI void gemm_phase(int wv, LAS unsigned char* lds, LAS unsigned char* scr, const Sched& S, const Epi& E) {
;     ...
;             const bool last = (t == nt - 2);
;             const char* a1 = cA + (size_t)(t + 1) * kstep;
;             const char* a2 = last ? nA : cA + (size_t)(t + 2) * kstep; const char* b2 = last ? nB : cB + (size_t)(t + 2) * kstep;
;             const char* a3 = a2 + kstep; const char* b3 = b2 + kstep;
;             PG8_LDB(B0, 0, 0); PG8_LDB(B1, 0, 1); PG8_SCHED; PG8_LDA(At, 0, 0); PG8_STAGE(PG8_SA(1, 1), a1 + hstepA, voffA);
;             PG8_WAIT_V(8); PG8_WAIT_L(0); PG8_BAR; PG8_MMA(0, 0, At, B0); PG8_MMA(0, 1, At, B1); PG8_BAR; PG8_SCHED;
;             PG8_LDA(At, 0, 1); PG8_STAGE(PG8_SB(0, 0), b2, voffB); PG8_STAGE(PG8_SB(0, 1), b2 + hstepB, voffB); PG8_STAGE(PG8_SA(0, 0), a2, voffA);
.LBB0_277:
	s_add_u32 s21, s14, s13
	s_addc_u32 s34, s15, 0
	s_add_u32 s28, s21, 0x100
	s_addc_u32 s29, s34, 0
	s_and_b64 s[26:27], s[24:25], exec
	s_cselect_b32 s29, s9, s29
	s_cselect_b32 s28, s8, s28
	s_add_u32 s13, s16, s13
	s_addc_u32 s26, s17, 0
	s_add_u32 s13, s13, 0x100
	s_addc_u32 s26, s26, 0
	s_add_i32 s64, 0, 0x10000
	s_and_b64 s[24:25], s[24:25], exec
	s_cselect_b32 s31, s19, s26
	s_cselect_b32 s30, s18, s13
	s_add_i32 s25, 0, 0x14000
	s_add_u32 s36, s21, 0x40080
	s_addc_u32 s37, s34, 0
	s_add_i32 s63, s64, s43
	s_add_i32 m0, s44, 0xc000
	s_add_i32 s66, s44, 0xe000
	s_add_i32 s60, s63, 0x2000
	s_add_u32 s34, s30, 0x40000
	v_add_u32_e32 v152, s64, v138
	v_add_u32_e32 v168, s25, v138
	s_addc_u32 s35, s31, 0
	s_add_i32 s62, s25, s43
	ds_read_b128 v[140:143], v152
	ds_read_b128 v[144:147], v152 offset:1024
	ds_read_b128 v[148:151], v152 offset:2048
	ds_read_b128 v[152:155], v152 offset:3072
	ds_read_b128 v[156:159], v168
	ds_read_b128 v[160:163], v168 offset:1024
	ds_read_b128 v[164:167], v168 offset:2048
	ds_read_b128 v[168:171], v168 offset:3072
	s_add_i32 s61, s62, 0x2000
	s_add_i32 s59, 0, 0x18000
	s_add_i32 s55, 0, 0x1c000
	s_add_u32 s26, s28, 0x40000
	s_addc_u32 s27, s29, 0
	s_add_i32 s21, s59, s43
	s_add_i32 s13, s21, 0x2000
	s_add_u32 s24, s30, 0x40080
	s_addc_u32 s25, s31, 0
	s_add_i32 s65, s55, s43
	s_add_i32 s64, s65, 0x2000
	v_lshl_add_u64 v[206:207], s[36:37], 0, v[134:135]
	ds_read_b128 v[172:175], v139
	ds_read_b128 v[176:179], v139 offset:1024
	ds_read_b128 v[180:183], v139 offset:2048
	ds_read_b128 v[184:187], v139 offset:3072
	ds_read_b128 v[188:191], v139 offset:4096
	ds_read_b128 v[194:197], v139 offset:5120
	ds_read_b128 v[198:201], v139 offset:6144
	ds_read_b128 v[202:205], v139 offset:7168
	global_load_lds_dwordx4 v[206:207], off
	v_lshl_add_u64 v[206:207], s[36:37], 0, v[130:131]
	s_mov_b32 m0, s66
	s_nop 0
	global_load_lds_dwordx4 v[206:207], off
	s_waitcnt vmcnt(8)
	s_waitcnt lgkmcnt(0)
	s_barrier
	s_waitcnt lgkmcnt(0)
	v_mfma_f32_16x16x32_bf16 v[124:127], v[140:143], v[172:175], v[124:127]
	v_mfma_f32_16x16x32_bf16 v[120:123], v[148:151], v[172:175], v[120:123]
	v_mfma_f32_16x16x32_bf16 v[116:119], v[140:143], v[180:183], v[116:119]
	v_mfma_f32_16x16x32_bf16 v[112:115], v[148:151], v[180:183], v[112:115]
	v_mfma_f32_16x16x32_bf16 v[100:103], v[140:143], v[188:191], v[100:103]
	v_mfma_f32_16x16x32_bf16 v[96:99], v[148:151], v[188:191], v[96:99]
	v_mfma_f32_16x16x32_bf16 v[84:87], v[140:143], v[198:201], v[84:87]
	v_mfma_f32_16x16x32_bf16 v[80:83], v[148:151], v[198:201], v[80:83]
	v_mfma_f32_16x16x32_bf16 v[124:127], v[144:147], v[176:179], v[124:127]
	v_mfma_f32_16x16x32_bf16 v[120:123], v[152:155], v[176:179], v[120:123]
	v_mfma_f32_16x16x32_bf16 v[116:119], v[144:147], v[184:187], v[116:119]
	v_mfma_f32_16x16x32_bf16 v[112:115], v[152:155], v[184:187], v[112:115]
	v_mfma_f32_16x16x32_bf16 v[100:103], v[144:147], v[194:197], v[100:103]
	v_mfma_f32_16x16x32_bf16 v[96:99], v[152:155], v[194:197], v[96:99]
	v_mfma_f32_16x16x32_bf16 v[84:87], v[144:147], v[202:205], v[84:87]
	v_mfma_f32_16x16x32_bf16 v[80:83], v[152:155], v[202:205], v[80:83]
	v_mfma_f32_16x16x32_bf16 v[108:111], v[156:159], v[172:175], v[108:111]
	v_mfma_f32_16x16x32_bf16 v[104:107], v[164:167], v[172:175], v[104:107]
	v_mfma_f32_16x16x32_bf16 v[92:95], v[156:159], v[180:183], v[92:95]
	v_mfma_f32_16x16x32_bf16 v[88:91], v[164:167], v[180:183], v[88:91]
	v_mfma_f32_16x16x32_bf16 v[76:79], v[156:159], v[188:191], v[76:79]
	v_mfma_f32_16x16x32_bf16 v[72:75], v[164:167], v[188:191], v[72:75]
	v_mfma_f32_16x16x32_bf16 v[68:71], v[156:159], v[198:201], v[68:71]
	v_mfma_f32_16x16x32_bf16 v[64:67], v[164:167], v[198:201], v[64:67]
	v_mfma_f32_16x16x32_bf16 v[108:111], v[160:163], v[176:179], v[108:111]
	v_mfma_f32_16x16x32_bf16 v[104:107], v[168:171], v[176:179], v[104:107]
	v_mfma_f32_16x16x32_bf16 v[92:95], v[160:163], v[184:187], v[92:95]
	v_mfma_f32_16x16x32_bf16 v[88:91], v[168:171], v[184:187], v[88:91]
	v_mfma_f32_16x16x32_bf16 v[76:79], v[160:163], v[194:197], v[76:79]
	v_mfma_f32_16x16x32_bf16 v[72:75], v[168:171], v[194:197], v[72:75]
	v_mfma_f32_16x16x32_bf16 v[68:71], v[160:163], v[202:205], v[68:71]
	v_mfma_f32_16x16x32_bf16 v[64:67], v[168:171], v[202:205], v[64:67]
	s_barrier
	s_mov_b32 m0, s63
	v_lshl_add_u64 v[206:207], s[30:31], 0, v[132:133]
	ds_read_b128 v[172:175], v139 offset:16384
	ds_read_b128 v[176:179], v139 offset:17408
	ds_read_b128 v[180:183], v139 offset:18432
	ds_read_b128 v[184:187], v139 offset:19456
	ds_read_b128 v[188:191], v139 offset:20480
	ds_read_b128 v[194:197], v139 offset:21504
	ds_read_b128 v[198:201], v139 offset:22528
	ds_read_b128 v[202:205], v139 offset:23552
	global_load_lds_dwordx4 v[206:207], off
	v_lshl_add_u64 v[208:209], s[30:31], 0, v[128:129]
	s_mov_b32 m0, s60
	v_lshl_add_u64 v[210:211], s[34:35], 0, v[132:133]
	global_load_lds_dwordx4 v[208:209], off
	s_mov_b32 m0, s62
	v_lshl_add_u64 v[212:213], s[28:29], 0, v[130:131]
	global_load_lds_dwordx4 v[210:211], off
	v_lshl_add_u64 v[210:211], s[34:35], 0, v[128:129]
	s_mov_b32 m0, s61
	s_nop 0
	global_load_lds_dwordx4 v[210:211], off
	v_lshl_add_u64 v[210:211], s[28:29], 0, v[134:135]
	s_mov_b32 m0, s44
	s_nop 0
	global_load_lds_dwordx4 v[210:211], off
	s_mov_b32 m0, s45
	s_nop 0
	global_load_lds_dwordx4 v[212:213], off
	s_waitcnt vmcnt(8)
	s_waitcnt lgkmcnt(0)
	s_barrier
; #define PG8_STAGE(bufoff, gbase, voff) do { _Pragma("unroll") for (int _i = 0; _i < 2; ++_i) \
;         __builtin_amdgcn_global_load_lds((const unsigned*)((const char*)(gbase) + (voff)[_i]), (LAS unsigned*)(lds + (bufoff) + ldsw + _i * 8192), 16, 0, 0); } while (0)
; #define PG8_LDA(dst, b, h) do { _Pragma("unroll") for (int m = 0; m < 4; ++m) _Pragma("unroll") for (int k = 0; k < 2; ++k) dst[m][k] = *(const LAS bf16x8*)(lds + PG8_SA(b, h) + aoff + m * 2048 + k * 1024); } while (0)
; #define PG8_LDB(dst, b, h) do { _Pragma("unroll") for (int n = 0; n < 2; ++n) _Pragma("unroll") for (int k = 0; k < 2; ++k) dst[n][k] = *(const LAS bf16x8*)(lds + PG8_SB(b, h) + boff + n * 2048 + k * 1024); } while (0)
; #define PG8_MMA(ai, bj, At, Bt) do { __builtin_amdgcn_s_setprio(1); _Pragma("unroll") for (int m = 0; m < 4; ++m) _Pragma("unroll") for (int n = 0; n < 2; ++n) _Pragma("unroll") for (int k = 0; k < 2; ++k) \
;         acc[ai][bj][m][n] = __builtin_amdgcn_mfma_f32_16x16x32_bf16(Bt[n][k], At[m][k], acc[ai][bj][m][n], 0, 0, 0); __builtin_amdgcn_s_setprio(0); } while (0)
; #define PG8_WAIT_V(n) asm volatile("s_waitcnt vmcnt(" #n ")" ::: "memory")
; #define PG8_WAIT_L(n) asm volatile("s_waitcnt lgkmcnt(" #n ")" ::: "memory")
; #define PG8_BAR __builtin_amdgcn_s_barrier()
; #define PG8_SCHED __builtin_amdgcn_sched_barrier(0)
; template <class Epi>
; DI void gemm_phase(int wv, LAS unsigned char* lds, LAS unsigned char* scr, const Sched& S, const Epi& E) {
;     ...
;             PG8_WAIT_V(8); PG8_WAIT_L(0); PG8_BAR; PG8_MMA(1, 0, At, B0); PG8_MMA(1, 1, At, B1); PG8_BAR; PG8_SCHED;
;             PG8_LDB(B0, 1, 0); PG8_LDB(B1, 1, 1); PG8_SCHED; PG8_LDA(At, 1, 0); PG8_STAGE(PG8_SA(0, 1), a2 + hstepA, voffA);
;             PG8_WAIT_V(8); PG8_WAIT_L(0); PG8_BAR; PG8_MMA(0, 0, At, B0); PG8_MMA(0, 1, At, B1); PG8_BAR; PG8_SCHED;
	s_waitcnt lgkmcnt(0)
	v_mfma_f32_16x16x32_bf16 v[60:63], v[140:143], v[172:175], v[60:63]
	v_mfma_f32_16x16x32_bf16 v[56:59], v[148:151], v[172:175], v[56:59]
	v_mfma_f32_16x16x32_bf16 v[52:55], v[140:143], v[180:183], v[52:55]
	v_mfma_f32_16x16x32_bf16 v[48:51], v[148:151], v[180:183], v[48:51]
	v_mfma_f32_16x16x32_bf16 v[36:39], v[140:143], v[188:191], v[36:39]
	v_mfma_f32_16x16x32_bf16 v[32:35], v[148:151], v[188:191], v[32:35]
	v_mfma_f32_16x16x32_bf16 v[20:23], v[140:143], v[198:201], v[20:23]
	v_mfma_f32_16x16x32_bf16 v[16:19], v[148:151], v[198:201], v[16:19]
	v_mfma_f32_16x16x32_bf16 v[60:63], v[144:147], v[176:179], v[60:63]
	v_mfma_f32_16x16x32_bf16 v[56:59], v[152:155], v[176:179], v[56:59]
	v_mfma_f32_16x16x32_bf16 v[52:55], v[144:147], v[184:187], v[52:55]
	v_mfma_f32_16x16x32_bf16 v[48:51], v[152:155], v[184:187], v[48:51]
	v_mfma_f32_16x16x32_bf16 v[36:39], v[144:147], v[194:197], v[36:39]
	v_mfma_f32_16x16x32_bf16 v[32:35], v[152:155], v[194:197], v[32:35]
	v_mfma_f32_16x16x32_bf16 v[20:23], v[144:147], v[202:205], v[20:23]
	v_mfma_f32_16x16x32_bf16 v[16:19], v[152:155], v[202:205], v[16:19]
	v_mfma_f32_16x16x32_bf16 v[44:47], v[156:159], v[172:175], v[44:47]
	v_mfma_f32_16x16x32_bf16 v[40:43], v[164:167], v[172:175], v[40:43]
	v_mfma_f32_16x16x32_bf16 v[28:31], v[156:159], v[180:183], v[28:31]
	v_mfma_f32_16x16x32_bf16 v[24:27], v[164:167], v[180:183], v[24:27]
	v_mfma_f32_16x16x32_bf16 v[12:15], v[156:159], v[188:191], v[12:15]
	v_mfma_f32_16x16x32_bf16 v[8:11], v[164:167], v[188:191], v[8:11]
	v_mfma_f32_16x16x32_bf16 v[4:7], v[156:159], v[198:201], v[4:7]
	v_mfma_f32_16x16x32_bf16 v[0:3], v[164:167], v[198:201], v[0:3]
	v_mfma_f32_16x16x32_bf16 v[44:47], v[160:163], v[176:179], v[44:47]
	v_mfma_f32_16x16x32_bf16 v[40:43], v[168:171], v[176:179], v[40:43]
	v_mfma_f32_16x16x32_bf16 v[28:31], v[160:163], v[184:187], v[28:31]
	v_mfma_f32_16x16x32_bf16 v[24:27], v[168:171], v[184:187], v[24:27]
	v_mfma_f32_16x16x32_bf16 v[12:15], v[160:163], v[194:197], v[12:15]
	v_mfma_f32_16x16x32_bf16 v[8:11], v[168:171], v[194:197], v[8:11]
	v_mfma_f32_16x16x32_bf16 v[4:7], v[160:163], v[202:205], v[4:7]
	v_mfma_f32_16x16x32_bf16 v[0:3], v[168:171], v[202:205], v[0:3]
	s_barrier
	v_add_u32_e32 v152, s59, v138
	v_add_u32_e32 v168, s55, v138
	ds_read_b128 v[140:143], v152
	ds_read_b128 v[144:147], v152 offset:1024
	ds_read_b128 v[148:151], v152 offset:2048
	ds_read_b128 v[152:155], v152 offset:3072
	ds_read_b128 v[156:159], v168
	ds_read_b128 v[160:163], v168 offset:1024
	ds_read_b128 v[164:167], v168 offset:2048
	ds_read_b128 v[168:171], v168 offset:3072
	s_mov_b32 m0, s46
	v_lshl_add_u64 v[214:215], s[26:27], 0, v[134:135]
	ds_read_b128 v[172:175], v139 offset:32768
	ds_read_b128 v[176:179], v139 offset:33792
	ds_read_b128 v[180:183], v139 offset:34816
	ds_read_b128 v[184:187], v139 offset:35840
	ds_read_b128 v[188:191], v139 offset:36864
	ds_read_b128 v[194:197], v139 offset:37888
	ds_read_b128 v[198:201], v139 offset:38912
	ds_read_b128 v[202:205], v139 offset:39936
	global_load_lds_dwordx4 v[214:215], off
	v_lshl_add_u64 v[214:215], s[26:27], 0, v[130:131]
	s_mov_b32 m0, s47
	s_nop 0
	global_load_lds_dwordx4 v[214:215], off
	s_waitcnt vmcnt(8)
	s_waitcnt lgkmcnt(0)
	s_barrier
	s_waitcnt lgkmcnt(0)
	v_mfma_f32_16x16x32_bf16 v[124:127], v[140:143], v[172:175], v[124:127]
	v_mfma_f32_16x16x32_bf16 v[120:123], v[148:151], v[172:175], v[120:123]
	v_mfma_f32_16x16x32_bf16 v[116:119], v[140:143], v[180:183], v[116:119]
	v_mfma_f32_16x16x32_bf16 v[112:115], v[148:151], v[180:183], v[112:115]
	v_mfma_f32_16x16x32_bf16 v[100:103], v[140:143], v[188:191], v[100:103]
	v_mfma_f32_16x16x32_bf16 v[96:99], v[148:151], v[188:191], v[96:99]
	v_mfma_f32_16x16x32_bf16 v[84:87], v[140:143], v[198:201], v[84:87]
	v_mfma_f32_16x16x32_bf16 v[80:83], v[148:151], v[198:201], v[80:83]
	v_mfma_f32_16x16x32_bf16 v[124:127], v[144:147], v[176:179], v[124:127]
	v_mfma_f32_16x16x32_bf16 v[120:123], v[152:155], v[176:179], v[120:123]
	v_mfma_f32_16x16x32_bf16 v[116:119], v[144:147], v[184:187], v[116:119]
	v_mfma_f32_16x16x32_bf16 v[112:115], v[152:155], v[184:187], v[112:115]
	v_mfma_f32_16x16x32_bf16 v[100:103], v[144:147], v[194:197], v[100:103]
	v_mfma_f32_16x16x32_bf16 v[96:99], v[152:155], v[194:197], v[96:99]
	v_mfma_f32_16x16x32_bf16 v[84:87], v[144:147], v[202:205], v[84:87]
	v_mfma_f32_16x16x32_bf16 v[80:83], v[152:155], v[202:205], v[80:83]
	v_mfma_f32_16x16x32_bf16 v[108:111], v[156:159], v[172:175], v[108:111]
	v_mfma_f32_16x16x32_bf16 v[104:107], v[164:167], v[172:175], v[104:107]
	v_mfma_f32_16x16x32_bf16 v[92:95], v[156:159], v[180:183], v[92:95]
	v_mfma_f32_16x16x32_bf16 v[88:91], v[164:167], v[180:183], v[88:91]
	v_mfma_f32_16x16x32_bf16 v[76:79], v[156:159], v[188:191], v[76:79]
	v_mfma_f32_16x16x32_bf16 v[72:75], v[164:167], v[188:191], v[72:75]
	v_mfma_f32_16x16x32_bf16 v[68:71], v[156:159], v[198:201], v[68:71]
	v_mfma_f32_16x16x32_bf16 v[64:67], v[164:167], v[198:201], v[64:67]
	v_mfma_f32_16x16x32_bf16 v[108:111], v[160:163], v[176:179], v[108:111]
	v_mfma_f32_16x16x32_bf16 v[104:107], v[168:171], v[176:179], v[104:107]
	v_mfma_f32_16x16x32_bf16 v[92:95], v[160:163], v[184:187], v[92:95]
	v_mfma_f32_16x16x32_bf16 v[88:91], v[168:171], v[184:187], v[88:91]
	v_mfma_f32_16x16x32_bf16 v[76:79], v[160:163], v[194:197], v[76:79]
	v_mfma_f32_16x16x32_bf16 v[72:75], v[168:171], v[194:197], v[72:75]
	v_mfma_f32_16x16x32_bf16 v[68:71], v[160:163], v[202:205], v[68:71]
	v_mfma_f32_16x16x32_bf16 v[64:67], v[168:171], v[202:205], v[64:67]
	s_barrier
; #define PG8_STAGE(bufoff, gbase, voff) do { _Pragma("unroll") for (int _i = 0; _i < 2; ++_i) \
;         __builtin_amdgcn_global_load_lds((const unsigned*)((const char*)(gbase) + (voff)[_i]), (LAS unsigned*)(lds + (bufoff) + ldsw + _i * 8192), 16, 0, 0); } while (0)
; #define PG8_LDA(dst, b, h) do { _Pragma("unroll") for (int m = 0; m < 4; ++m) _Pragma("unroll") for (int k = 0; k < 2; ++k) dst[m][k] = *(const LAS bf16x8*)(lds + PG8_SA(b, h) + aoff + m * 2048 + k * 1024); } while (0)
; #define PG8_MMA(ai, bj, At, Bt) do { __builtin_amdgcn_s_setprio(1); _Pragma("unroll") for (int m = 0; m < 4; ++m) _Pragma("unroll") for (int n = 0; n < 2; ++n) _Pragma("unroll") for (int k = 0; k < 2; ++k) \
;         acc[ai][bj][m][n] = __builtin_amdgcn_mfma_f32_16x16x32_bf16(Bt[n][k], At[m][k], acc[ai][bj][m][n], 0, 0, 0); __builtin_amdgcn_s_setprio(0); } while (0)
; #define PG8_WAIT_V(n) asm volatile("s_waitcnt vmcnt(" #n ")" ::: "memory")
; #define PG8_WAIT_L(n) asm volatile("s_waitcnt lgkmcnt(" #n ")" ::: "memory")
; #define PG8_BAR __builtin_amdgcn_s_barrier()
; #define PG8_SCHED __builtin_amdgcn_sched_barrier(0)
; template <class Epi>
; DI void gemm_phase(int wv, LAS unsigned char* lds, LAS unsigned char* scr, const Sched& S, const Epi& E) {
;     ...
;             PG8_LDA(At, 1, 1); PG8_STAGE(PG8_SB(1, 0), b3, voffB); PG8_STAGE(PG8_SB(1, 1), b3 + hstepB, voffB); PG8_STAGE(PG8_SA(1, 0), a3, voffA);
;             PG8_WAIT_V(8); PG8_WAIT_L(0); PG8_BAR; PG8_MMA(1, 0, At, B0); PG8_MMA(1, 1, At, B1); PG8_BAR; PG8_SCHED;
;         }
;         if (wr == 0) PG8_BAR;
	s_mov_b32 m0, s21
	v_lshl_add_u64 v[206:207], v[206:207], 0, s[2:3]
	ds_read_b128 v[172:175], v139 offset:49152
	ds_read_b128 v[176:179], v139 offset:50176
	ds_read_b128 v[180:183], v139 offset:51200
	ds_read_b128 v[184:187], v139 offset:52224
	ds_read_b128 v[188:191], v139 offset:53248
	ds_read_b128 v[194:197], v139 offset:54272
	ds_read_b128 v[198:201], v139 offset:55296
	ds_read_b128 v[202:205], v139 offset:56320
	global_load_lds_dwordx4 v[206:207], off
	v_lshl_add_u64 v[206:207], v[208:209], 0, s[2:3]
	s_mov_b32 m0, s13
	s_nop 0
	global_load_lds_dwordx4 v[206:207], off
	v_lshl_add_u64 v[206:207], s[24:25], 0, v[132:133]
	s_mov_b32 m0, s65
	s_nop 0
	global_load_lds_dwordx4 v[206:207], off
	v_lshl_add_u64 v[206:207], s[24:25], 0, v[128:129]
	s_mov_b32 m0, s64
	s_nop 0
	global_load_lds_dwordx4 v[206:207], off
	v_lshl_add_u64 v[206:207], v[210:211], 0, s[2:3]
	s_mov_b32 m0, s50
	s_nop 0
	global_load_lds_dwordx4 v[206:207], off
	v_lshl_add_u64 v[206:207], v[212:213], 0, s[2:3]
	s_mov_b32 m0, s51
	s_nop 0
	global_load_lds_dwordx4 v[206:207], off
	s_waitcnt vmcnt(8)
	s_waitcnt lgkmcnt(0)
	s_barrier
	s_waitcnt lgkmcnt(0)
	v_mfma_f32_16x16x32_bf16 v[60:63], v[140:143], v[172:175], v[60:63]
	v_mfma_f32_16x16x32_bf16 v[56:59], v[148:151], v[172:175], v[56:59]
	v_mfma_f32_16x16x32_bf16 v[52:55], v[140:143], v[180:183], v[52:55]
	v_mfma_f32_16x16x32_bf16 v[48:51], v[148:151], v[180:183], v[48:51]
	v_mfma_f32_16x16x32_bf16 v[36:39], v[140:143], v[188:191], v[36:39]
	v_mfma_f32_16x16x32_bf16 v[32:35], v[148:151], v[188:191], v[32:35]
	v_mfma_f32_16x16x32_bf16 v[20:23], v[140:143], v[198:201], v[20:23]
	v_mfma_f32_16x16x32_bf16 v[16:19], v[148:151], v[198:201], v[16:19]
	v_mfma_f32_16x16x32_bf16 v[60:63], v[144:147], v[176:179], v[60:63]
	v_mfma_f32_16x16x32_bf16 v[56:59], v[152:155], v[176:179], v[56:59]
	v_mfma_f32_16x16x32_bf16 v[52:55], v[144:147], v[184:187], v[52:55]
	v_mfma_f32_16x16x32_bf16 v[48:51], v[152:155], v[184:187], v[48:51]
	v_mfma_f32_16x16x32_bf16 v[36:39], v[144:147], v[194:197], v[36:39]
	v_mfma_f32_16x16x32_bf16 v[32:35], v[152:155], v[194:197], v[32:35]
	v_mfma_f32_16x16x32_bf16 v[20:23], v[144:147], v[202:205], v[20:23]
	v_mfma_f32_16x16x32_bf16 v[16:19], v[152:155], v[202:205], v[16:19]
	v_mfma_f32_16x16x32_bf16 v[44:47], v[156:159], v[172:175], v[44:47]
	v_mfma_f32_16x16x32_bf16 v[40:43], v[164:167], v[172:175], v[40:43]
	v_mfma_f32_16x16x32_bf16 v[28:31], v[156:159], v[180:183], v[28:31]
	v_mfma_f32_16x16x32_bf16 v[24:27], v[164:167], v[180:183], v[24:27]
	v_mfma_f32_16x16x32_bf16 v[12:15], v[156:159], v[188:191], v[12:15]
	v_mfma_f32_16x16x32_bf16 v[8:11], v[164:167], v[188:191], v[8:11]
	v_mfma_f32_16x16x32_bf16 v[4:7], v[156:159], v[198:201], v[4:7]
	v_mfma_f32_16x16x32_bf16 v[0:3], v[164:167], v[198:201], v[0:3]
	v_mfma_f32_16x16x32_bf16 v[44:47], v[160:163], v[176:179], v[44:47]
	v_mfma_f32_16x16x32_bf16 v[40:43], v[168:171], v[176:179], v[40:43]
	v_mfma_f32_16x16x32_bf16 v[28:31], v[160:163], v[184:187], v[28:31]
	v_mfma_f32_16x16x32_bf16 v[24:27], v[168:171], v[184:187], v[24:27]
	v_mfma_f32_16x16x32_bf16 v[12:15], v[160:163], v[194:197], v[12:15]
	v_mfma_f32_16x16x32_bf16 v[8:11], v[168:171], v[194:197], v[8:11]
	v_mfma_f32_16x16x32_bf16 v[4:7], v[160:163], v[202:205], v[4:7]
	v_mfma_f32_16x16x32_bf16 v[0:3], v[168:171], v[202:205], v[0:3]
	s_barrier
	s_movk_i32 s13, 0x100
	s_andn2_b64 vcc, exec, s[22:23]
	s_mov_b64 s[24:25], -1
	s_mov_b64 s[22:23], 0
	s_cbranch_vccz .LBB0_277
	s_and_b64 vcc, exec, s[10:11]
	s_cbranch_vccz .LBB0_280
	s_barrier

; #define PG8_STAGE(bufoff, gbase, voff) do { _Pragma("unroll") for (int _i = 0; _i < 2; ++_i) \
;         __builtin_amdgcn_global_load_lds((const unsigned*)((const char*)(gbase) + (voff)[_i]), (LAS unsigned*)(lds + (bufoff) + ldsw + _i * 8192), 16, 0, 0); } while (0)
; #define PG8_LDA(dst, b, h) do { _Pragma("unroll") for (int m = 0; m < 4; ++m) _Pragma("unroll") for (int k = 0; k < 2; ++k) dst[m][k] = *(const LAS bf16x8*)(lds + PG8_SA(b, h) + aoff + m * 2048 + k * 1024); } while (0)
; #define PG8_LDB(dst, b, h) do { _Pragma("unroll") for (int n = 0; n < 2; ++n) _Pragma("unroll") for (int k = 0; k < 2; ++k) dst[n][k] = *(const LAS bf16x8*)(lds + PG8_SB(b, h) + boff + n * 2048 + k * 1024); } while (0)
; #define PG8_MMA(ai, bj, At, Bt) do { __builtin_amdgcn_s_setprio(1); _Pragma("unroll") for (int m = 0; m < 4; ++m) _Pragma("unroll") for (int n = 0; n < 2; ++n) _Pragma("unroll") for (int k = 0; k < 2; ++k) \
;         acc[ai][bj][m][n] = __builtin_amdgcn_mfma_f32_16x16x32_bf16(Bt[n][k], At[m][k], acc[ai][bj][m][n], 0, 0, 0); __builtin_amdgcn_s_setprio(0); } while (0)
; #define PG8_WAIT_V(n) asm volatile("s_waitcnt vmcnt(" #n ")" ::: "memory")
; #define PG8_WAIT_L(n) asm volatile("s_waitcnt lgkmcnt(" #n ")" ::: "memory")
; #define PG8_BAR __builtin_amdgcn_s_barrier()
; #define PG8_SCHED __builtin_amdgcn_sched_barrier(0)
; template <class Epi>
; DI void gemm_phase(int wv, LAS unsigned char* lds, LAS unsigned char* scr, const Sched& S, const Epi& E) {
;     ...
;             const bool last = (t == nt - 2);
;             const char* a1 = cA + (size_t)(t + 1) * kstep;
;             const char* a2 = last ? nA : cA + (size_t)(t + 2) * kstep; const char* b2 = last ? nB : cB + (size_t)(t + 2) * kstep;
;             const char* a3 = a2 + kstep; const char* b3 = b2 + kstep;
;             PG8_LDB(B0, 0, 0); PG8_LDB(B1, 0, 1); PG8_SCHED; PG8_LDA(At, 0, 0); PG8_STAGE(PG8_SA(1, 1), a1 + hstepA, voffA);
;             PG8_WAIT_V(8); PG8_WAIT_L(0); PG8_BAR; PG8_MMA(0, 0, At, B0); PG8_MMA(0, 1, At, B1); PG8_BAR; PG8_SCHED;
;             PG8_LDA(At, 0, 1); PG8_STAGE(PG8_SB(0, 0), b2, voffB); PG8_STAGE(PG8_SB(0, 1), b2 + hstepB, voffB); PG8_STAGE(PG8_SA(0, 0), a2, voffA);
.LBB0_463:
	s_add_u32 s24, s22, 0xfffc0080
	s_addc_u32 s25, s23, -1
	s_add_i32 s48, 0, 0x10000
	s_cmp_eq_u32 s47, 12
	s_cselect_b32 s27, s11, s25
	s_cselect_b32 s26, s15, s24
	v_add_u32_e32 v143, s48, v144
	s_cselect_b32 s25, s13, s46
	s_cselect_b32 s24, s21, s45
	s_add_i32 s50, 0, 0x14000
	ds_read_b128 v[146:149], v143
	ds_read_b128 v[150:153], v143 offset:1024
	ds_read_b128 v[154:157], v143 offset:2048
	ds_read_b128 v[158:161], v143 offset:3072
	v_add_u32_e32 v143, s50, v144
	ds_read_b128 v[162:165], v143
	ds_read_b128 v[166:169], v143 offset:1024
	ds_read_b128 v[170:173], v143 offset:2048
	ds_read_b128 v[174:177], v143 offset:3072
	v_lshl_add_u64 v[190:191], s[22:23], 0, v[140:141]
	s_add_i32 m0, s34, 0xc000
	ds_read_b128 v[178:181], v145
	ds_read_b128 v[182:185], v145 offset:1024
	ds_read_b128 v[186:189], v145 offset:2048
	ds_read_b128 v[194:197], v145 offset:3072
	ds_read_b128 v[198:201], v145 offset:4096
	ds_read_b128 v[202:205], v145 offset:5120
	ds_read_b128 v[206:209], v145 offset:6144
	ds_read_b128 v[210:213], v145 offset:7168
	global_load_lds_dwordx4 v[190:191], off
	v_lshl_add_u64 v[190:191], s[22:23], 0, v[138:139]
	s_add_i32 m0, s34, 0xe000
	s_nop 0
	global_load_lds_dwordx4 v[190:191], off
	s_waitcnt vmcnt(8)
	s_waitcnt lgkmcnt(0)
	s_barrier
	s_waitcnt lgkmcnt(0)
	v_mfma_f32_16x16x32_bf16 v[124:127], v[146:149], v[178:181], v[124:127]
	v_mfma_f32_16x16x32_bf16 v[120:123], v[154:157], v[178:181], v[120:123]
	v_mfma_f32_16x16x32_bf16 v[116:119], v[146:149], v[186:189], v[116:119]
	v_mfma_f32_16x16x32_bf16 v[112:115], v[154:157], v[186:189], v[112:115]
	v_mfma_f32_16x16x32_bf16 v[100:103], v[146:149], v[198:201], v[100:103]
	v_mfma_f32_16x16x32_bf16 v[96:99], v[154:157], v[198:201], v[96:99]
	v_mfma_f32_16x16x32_bf16 v[84:87], v[146:149], v[206:209], v[84:87]
	v_mfma_f32_16x16x32_bf16 v[80:83], v[154:157], v[206:209], v[80:83]
	v_mfma_f32_16x16x32_bf16 v[124:127], v[150:153], v[182:185], v[124:127]
	v_mfma_f32_16x16x32_bf16 v[120:123], v[158:161], v[182:185], v[120:123]
	v_mfma_f32_16x16x32_bf16 v[116:119], v[150:153], v[194:197], v[116:119]
	v_mfma_f32_16x16x32_bf16 v[112:115], v[158:161], v[194:197], v[112:115]
	v_mfma_f32_16x16x32_bf16 v[100:103], v[150:153], v[202:205], v[100:103]
	v_mfma_f32_16x16x32_bf16 v[96:99], v[158:161], v[202:205], v[96:99]
	v_mfma_f32_16x16x32_bf16 v[84:87], v[150:153], v[210:213], v[84:87]
	v_mfma_f32_16x16x32_bf16 v[80:83], v[158:161], v[210:213], v[80:83]
	v_mfma_f32_16x16x32_bf16 v[108:111], v[162:165], v[178:181], v[108:111]
	v_mfma_f32_16x16x32_bf16 v[104:107], v[170:173], v[178:181], v[104:107]
	v_mfma_f32_16x16x32_bf16 v[92:95], v[162:165], v[186:189], v[92:95]
	v_mfma_f32_16x16x32_bf16 v[88:91], v[170:173], v[186:189], v[88:91]
	v_mfma_f32_16x16x32_bf16 v[76:79], v[162:165], v[198:201], v[76:79]
	v_mfma_f32_16x16x32_bf16 v[72:75], v[170:173], v[198:201], v[72:75]
	v_mfma_f32_16x16x32_bf16 v[68:71], v[162:165], v[206:209], v[68:71]
	v_mfma_f32_16x16x32_bf16 v[64:67], v[170:173], v[206:209], v[64:67]
	v_mfma_f32_16x16x32_bf16 v[108:111], v[166:169], v[182:185], v[108:111]
	v_mfma_f32_16x16x32_bf16 v[104:107], v[174:177], v[182:185], v[104:107]
	v_mfma_f32_16x16x32_bf16 v[92:95], v[166:169], v[194:197], v[92:95]
	v_mfma_f32_16x16x32_bf16 v[88:91], v[174:177], v[194:197], v[88:91]
	v_mfma_f32_16x16x32_bf16 v[76:79], v[166:169], v[202:205], v[76:79]
	v_mfma_f32_16x16x32_bf16 v[72:75], v[174:177], v[202:205], v[72:75]
	v_mfma_f32_16x16x32_bf16 v[68:71], v[166:169], v[210:213], v[68:71]
	v_mfma_f32_16x16x32_bf16 v[64:67], v[174:177], v[210:213], v[64:67]
	s_barrier
	s_add_i32 s48, s48, s33
	v_lshl_add_u64 v[190:191], s[24:25], 0, v[132:133]
	s_mov_b32 m0, s48
	ds_read_b128 v[178:181], v145 offset:16384
	ds_read_b128 v[182:185], v145 offset:17408
	ds_read_b128 v[186:189], v145 offset:18432
	ds_read_b128 v[194:197], v145 offset:19456
	ds_read_b128 v[198:201], v145 offset:20480
	ds_read_b128 v[202:205], v145 offset:21504
	ds_read_b128 v[206:209], v145 offset:22528
	ds_read_b128 v[210:213], v145 offset:23552
	global_load_lds_dwordx4 v[190:191], off
	s_add_i32 m0, s48, 0x2000
	s_add_u32 s48, s24, 0x40000
	v_lshl_add_u64 v[214:215], s[24:25], 0, v[128:129]
	s_addc_u32 s49, s25, 0
	s_add_i32 s50, s50, s33
	global_load_lds_dwordx4 v[214:215], off
	v_lshl_add_u64 v[216:217], s[48:49], 0, v[132:133]
	s_mov_b32 m0, s50
	v_lshl_add_u64 v[218:219], s[26:27], 0, v[130:131]
	global_load_lds_dwordx4 v[216:217], off
	v_lshl_add_u64 v[216:217], s[48:49], 0, v[128:129]
	s_add_i32 m0, s50, 0x2000
	s_nop 0
	global_load_lds_dwordx4 v[216:217], off
	v_lshl_add_u64 v[216:217], s[26:27], 0, v[134:135]
	s_mov_b32 m0, s34
	s_nop 0
	global_load_lds_dwordx4 v[216:217], off
	s_mov_b32 m0, s35
	s_nop 0
	global_load_lds_dwordx4 v[218:219], off
	s_waitcnt vmcnt(8)
	s_waitcnt lgkmcnt(0)
	s_barrier
; #define PG8_STAGE(bufoff, gbase, voff) do { _Pragma("unroll") for (int _i = 0; _i < 2; ++_i) \
;         __builtin_amdgcn_global_load_lds((const unsigned*)((const char*)(gbase) + (voff)[_i]), (LAS unsigned*)(lds + (bufoff) + ldsw + _i * 8192), 16, 0, 0); } while (0)
; #define PG8_LDA(dst, b, h) do { _Pragma("unroll") for (int m = 0; m < 4; ++m) _Pragma("unroll") for (int k = 0; k < 2; ++k) dst[m][k] = *(const LAS bf16x8*)(lds + PG8_SA(b, h) + aoff + m * 2048 + k * 1024); } while (0)
; #define PG8_LDB(dst, b, h) do { _Pragma("unroll") for (int n = 0; n < 2; ++n) _Pragma("unroll") for (int k = 0; k < 2; ++k) dst[n][k] = *(const LAS bf16x8*)(lds + PG8_SB(b, h) + boff + n * 2048 + k * 1024); } while (0)
; #define PG8_MMA(ai, bj, At, Bt) do { __builtin_amdgcn_s_setprio(1); _Pragma("unroll") for (int m = 0; m < 4; ++m) _Pragma("unroll") for (int n = 0; n < 2; ++n) _Pragma("unroll") for (int k = 0; k < 2; ++k) \
;         acc[ai][bj][m][n] = __builtin_amdgcn_mfma_f32_16x16x32_bf16(Bt[n][k], At[m][k], acc[ai][bj][m][n], 0, 0, 0); __builtin_amdgcn_s_setprio(0); } while (0)
; #define PG8_WAIT_V(n) asm volatile("s_waitcnt vmcnt(" #n ")" ::: "memory")
; #define PG8_WAIT_L(n) asm volatile("s_waitcnt lgkmcnt(" #n ")" ::: "memory")
; #define PG8_BAR __builtin_amdgcn_s_barrier()
; #define PG8_SCHED __builtin_amdgcn_sched_barrier(0)
; template <class Epi>
; DI void gemm_phase(int wv, LAS unsigned char* lds, LAS unsigned char* scr, const Sched& S, const Epi& E) {
;     ...
;             PG8_WAIT_V(8); PG8_WAIT_L(0); PG8_BAR; PG8_MMA(1, 0, At, B0); PG8_MMA(1, 1, At, B1); PG8_BAR; PG8_SCHED;
;             PG8_LDB(B0, 1, 0); PG8_LDB(B1, 1, 1); PG8_SCHED; PG8_LDA(At, 1, 0); PG8_STAGE(PG8_SA(0, 1), a2 + hstepA, voffA);
;             PG8_WAIT_V(8); PG8_WAIT_L(0); PG8_BAR; PG8_MMA(0, 0, At, B0); PG8_MMA(0, 1, At, B1); PG8_BAR; PG8_SCHED;
	s_waitcnt lgkmcnt(0)
	v_mfma_f32_16x16x32_bf16 v[60:63], v[146:149], v[178:181], v[60:63]
	v_mfma_f32_16x16x32_bf16 v[56:59], v[154:157], v[178:181], v[56:59]
	v_mfma_f32_16x16x32_bf16 v[52:55], v[146:149], v[186:189], v[52:55]
	v_mfma_f32_16x16x32_bf16 v[48:51], v[154:157], v[186:189], v[48:51]
	v_mfma_f32_16x16x32_bf16 v[36:39], v[146:149], v[198:201], v[36:39]
	v_mfma_f32_16x16x32_bf16 v[32:35], v[154:157], v[198:201], v[32:35]
	v_mfma_f32_16x16x32_bf16 v[20:23], v[146:149], v[206:209], v[20:23]
	v_mfma_f32_16x16x32_bf16 v[16:19], v[154:157], v[206:209], v[16:19]
	v_mfma_f32_16x16x32_bf16 v[60:63], v[150:153], v[182:185], v[60:63]
	v_mfma_f32_16x16x32_bf16 v[56:59], v[158:161], v[182:185], v[56:59]
	v_mfma_f32_16x16x32_bf16 v[52:55], v[150:153], v[194:197], v[52:55]
	v_mfma_f32_16x16x32_bf16 v[48:51], v[158:161], v[194:197], v[48:51]
	v_mfma_f32_16x16x32_bf16 v[36:39], v[150:153], v[202:205], v[36:39]
	v_mfma_f32_16x16x32_bf16 v[32:35], v[158:161], v[202:205], v[32:35]
	v_mfma_f32_16x16x32_bf16 v[20:23], v[150:153], v[210:213], v[20:23]
	v_mfma_f32_16x16x32_bf16 v[16:19], v[158:161], v[210:213], v[16:19]
	v_mfma_f32_16x16x32_bf16 v[44:47], v[162:165], v[178:181], v[44:47]
	v_mfma_f32_16x16x32_bf16 v[40:43], v[170:173], v[178:181], v[40:43]
	v_mfma_f32_16x16x32_bf16 v[28:31], v[162:165], v[186:189], v[28:31]
	v_mfma_f32_16x16x32_bf16 v[24:27], v[170:173], v[186:189], v[24:27]
	v_mfma_f32_16x16x32_bf16 v[12:15], v[162:165], v[198:201], v[12:15]
	v_mfma_f32_16x16x32_bf16 v[8:11], v[170:173], v[198:201], v[8:11]
	v_mfma_f32_16x16x32_bf16 v[4:7], v[162:165], v[206:209], v[4:7]
	v_mfma_f32_16x16x32_bf16 v[0:3], v[170:173], v[206:209], v[0:3]
	v_mfma_f32_16x16x32_bf16 v[44:47], v[166:169], v[182:185], v[44:47]
	v_mfma_f32_16x16x32_bf16 v[40:43], v[174:177], v[182:185], v[40:43]
	v_mfma_f32_16x16x32_bf16 v[28:31], v[166:169], v[194:197], v[28:31]
	v_mfma_f32_16x16x32_bf16 v[24:27], v[174:177], v[194:197], v[24:27]
	v_mfma_f32_16x16x32_bf16 v[12:15], v[166:169], v[202:205], v[12:15]
	v_mfma_f32_16x16x32_bf16 v[8:11], v[174:177], v[202:205], v[8:11]
	v_mfma_f32_16x16x32_bf16 v[4:7], v[166:169], v[210:213], v[4:7]
	v_mfma_f32_16x16x32_bf16 v[0:3], v[174:177], v[210:213], v[0:3]
	s_barrier
	s_add_i32 s48, 0, 0x18000
	v_add_u32_e32 v143, s48, v144
	s_add_i32 s49, 0, 0x1c000
	ds_read_b128 v[146:149], v143
	ds_read_b128 v[150:153], v143 offset:1024
	ds_read_b128 v[154:157], v143 offset:2048
	ds_read_b128 v[158:161], v143 offset:3072
	v_add_u32_e32 v143, s49, v144
	ds_read_b128 v[162:165], v143
	ds_read_b128 v[166:169], v143 offset:1024
	ds_read_b128 v[170:173], v143 offset:2048
	ds_read_b128 v[174:177], v143 offset:3072
	s_add_u32 s26, s26, 0x40000
	s_addc_u32 s27, s27, 0
	s_mov_b32 m0, s36
	v_lshl_add_u64 v[220:221], s[26:27], 0, v[134:135]
	ds_read_b128 v[178:181], v145 offset:32768
	ds_read_b128 v[182:185], v145 offset:33792
	ds_read_b128 v[186:189], v145 offset:34816
	ds_read_b128 v[194:197], v145 offset:35840
	ds_read_b128 v[198:201], v145 offset:36864
	ds_read_b128 v[202:205], v145 offset:37888
	ds_read_b128 v[206:209], v145 offset:38912
	ds_read_b128 v[210:213], v145 offset:39936
	global_load_lds_dwordx4 v[220:221], off
	v_lshl_add_u64 v[220:221], s[26:27], 0, v[130:131]
	s_mov_b32 m0, s37
	s_nop 0
	global_load_lds_dwordx4 v[220:221], off
	s_waitcnt vmcnt(8)
	s_waitcnt lgkmcnt(0)
	s_barrier
	s_waitcnt lgkmcnt(0)
	v_mfma_f32_16x16x32_bf16 v[124:127], v[146:149], v[178:181], v[124:127]
	v_mfma_f32_16x16x32_bf16 v[120:123], v[154:157], v[178:181], v[120:123]
	v_mfma_f32_16x16x32_bf16 v[116:119], v[146:149], v[186:189], v[116:119]
	v_mfma_f32_16x16x32_bf16 v[112:115], v[154:157], v[186:189], v[112:115]
	v_mfma_f32_16x16x32_bf16 v[100:103], v[146:149], v[198:201], v[100:103]
	v_mfma_f32_16x16x32_bf16 v[96:99], v[154:157], v[198:201], v[96:99]
	v_mfma_f32_16x16x32_bf16 v[84:87], v[146:149], v[206:209], v[84:87]
	v_mfma_f32_16x16x32_bf16 v[80:83], v[154:157], v[206:209], v[80:83]
	v_mfma_f32_16x16x32_bf16 v[124:127], v[150:153], v[182:185], v[124:127]
	v_mfma_f32_16x16x32_bf16 v[120:123], v[158:161], v[182:185], v[120:123]
	v_mfma_f32_16x16x32_bf16 v[116:119], v[150:153], v[194:197], v[116:119]
	v_mfma_f32_16x16x32_bf16 v[112:115], v[158:161], v[194:197], v[112:115]
	v_mfma_f32_16x16x32_bf16 v[100:103], v[150:153], v[202:205], v[100:103]
	v_mfma_f32_16x16x32_bf16 v[96:99], v[158:161], v[202:205], v[96:99]
	v_mfma_f32_16x16x32_bf16 v[84:87], v[150:153], v[210:213], v[84:87]
	v_mfma_f32_16x16x32_bf16 v[80:83], v[158:161], v[210:213], v[80:83]
	v_mfma_f32_16x16x32_bf16 v[108:111], v[162:165], v[178:181], v[108:111]
	v_mfma_f32_16x16x32_bf16 v[104:107], v[170:173], v[178:181], v[104:107]
	v_mfma_f32_16x16x32_bf16 v[92:95], v[162:165], v[186:189], v[92:95]
	v_mfma_f32_16x16x32_bf16 v[88:91], v[170:173], v[186:189], v[88:91]
	v_mfma_f32_16x16x32_bf16 v[76:79], v[162:165], v[198:201], v[76:79]
	v_mfma_f32_16x16x32_bf16 v[72:75], v[170:173], v[198:201], v[72:75]
	v_mfma_f32_16x16x32_bf16 v[68:71], v[162:165], v[206:209], v[68:71]
	v_mfma_f32_16x16x32_bf16 v[64:67], v[170:173], v[206:209], v[64:67]
	v_mfma_f32_16x16x32_bf16 v[108:111], v[166:169], v[182:185], v[108:111]
	v_mfma_f32_16x16x32_bf16 v[104:107], v[174:177], v[182:185], v[104:107]
	v_mfma_f32_16x16x32_bf16 v[92:95], v[166:169], v[194:197], v[92:95]
	v_mfma_f32_16x16x32_bf16 v[88:91], v[174:177], v[194:197], v[88:91]
	v_mfma_f32_16x16x32_bf16 v[76:79], v[166:169], v[202:205], v[76:79]
	v_mfma_f32_16x16x32_bf16 v[72:75], v[174:177], v[202:205], v[72:75]
	v_mfma_f32_16x16x32_bf16 v[68:71], v[166:169], v[210:213], v[68:71]
	v_mfma_f32_16x16x32_bf16 v[64:67], v[174:177], v[210:213], v[64:67]
	s_barrier
; #define PG8_STAGE(bufoff, gbase, voff) do { _Pragma("unroll") for (int _i = 0; _i < 2; ++_i) \
;         __builtin_amdgcn_global_load_lds((const unsigned*)((const char*)(gbase) + (voff)[_i]), (LAS unsigned*)(lds + (bufoff) + ldsw + _i * 8192), 16, 0, 0); } while (0)
; #define PG8_LDA(dst, b, h) do { _Pragma("unroll") for (int m = 0; m < 4; ++m) _Pragma("unroll") for (int k = 0; k < 2; ++k) dst[m][k] = *(const LAS bf16x8*)(lds + PG8_SA(b, h) + aoff + m * 2048 + k * 1024); } while (0)
; #define PG8_MMA(ai, bj, At, Bt) do { __builtin_amdgcn_s_setprio(1); _Pragma("unroll") for (int m = 0; m < 4; ++m) _Pragma("unroll") for (int n = 0; n < 2; ++n) _Pragma("unroll") for (int k = 0; k < 2; ++k) \
;         acc[ai][bj][m][n] = __builtin_amdgcn_mfma_f32_16x16x32_bf16(Bt[n][k], At[m][k], acc[ai][bj][m][n], 0, 0, 0); __builtin_amdgcn_s_setprio(0); } while (0)
; #define PG8_WAIT_V(n) asm volatile("s_waitcnt vmcnt(" #n ")" ::: "memory")
; #define PG8_WAIT_L(n) asm volatile("s_waitcnt lgkmcnt(" #n ")" ::: "memory")
; #define PG8_BAR __builtin_amdgcn_s_barrier()
; #define PG8_SCHED __builtin_amdgcn_sched_barrier(0)
; template <class Epi>
; DI void gemm_phase(int wv, LAS unsigned char* lds, LAS unsigned char* scr, const Sched& S, const Epi& E) {
;     ...
;             PG8_LDA(At, 1, 1); PG8_STAGE(PG8_SB(1, 0), b3, voffB); PG8_STAGE(PG8_SB(1, 1), b3 + hstepB, voffB); PG8_STAGE(PG8_SA(1, 0), a3, voffA);
;             PG8_WAIT_V(8); PG8_WAIT_L(0); PG8_BAR; PG8_MMA(1, 0, At, B0); PG8_MMA(1, 1, At, B1); PG8_BAR; PG8_SCHED;
;         }
;         if (wr == 0) PG8_BAR;
	s_add_i32 s26, s48, s33
	v_lshl_add_u64 v[190:191], v[190:191], 0, s[2:3]
	s_mov_b32 m0, s26
	ds_read_b128 v[178:181], v145 offset:49152
	ds_read_b128 v[182:185], v145 offset:50176
	ds_read_b128 v[186:189], v145 offset:51200
	ds_read_b128 v[194:197], v145 offset:52224
	ds_read_b128 v[198:201], v145 offset:53248
	ds_read_b128 v[202:205], v145 offset:54272
	ds_read_b128 v[206:209], v145 offset:55296
	ds_read_b128 v[210:213], v145 offset:56320
	global_load_lds_dwordx4 v[190:191], off
	s_add_i32 m0, s26, 0x2000
	s_add_u32 s24, s24, 0x40080
	v_lshl_add_u64 v[190:191], v[214:215], 0, s[2:3]
	s_addc_u32 s25, s25, 0
	s_add_i32 s26, s49, s33
	global_load_lds_dwordx4 v[190:191], off
	v_lshl_add_u64 v[190:191], s[24:25], 0, v[132:133]
	s_mov_b32 m0, s26
	s_nop 0
	global_load_lds_dwordx4 v[190:191], off
	v_lshl_add_u64 v[190:191], s[24:25], 0, v[128:129]
	s_add_i32 m0, s26, 0x2000
	s_nop 0
	global_load_lds_dwordx4 v[190:191], off
	v_lshl_add_u64 v[190:191], v[216:217], 0, s[2:3]
	s_mov_b32 m0, s42
	s_nop 0
	global_load_lds_dwordx4 v[190:191], off
	v_lshl_add_u64 v[190:191], v[218:219], 0, s[2:3]
	s_mov_b32 m0, s43
	s_nop 0
	global_load_lds_dwordx4 v[190:191], off
	s_waitcnt vmcnt(8)
	s_waitcnt lgkmcnt(0)
	s_barrier
	s_waitcnt lgkmcnt(0)
	v_mfma_f32_16x16x32_bf16 v[60:63], v[146:149], v[178:181], v[60:63]
	v_mfma_f32_16x16x32_bf16 v[56:59], v[154:157], v[178:181], v[56:59]
	v_mfma_f32_16x16x32_bf16 v[52:55], v[146:149], v[186:189], v[52:55]
	v_mfma_f32_16x16x32_bf16 v[48:51], v[154:157], v[186:189], v[48:51]
	v_mfma_f32_16x16x32_bf16 v[36:39], v[146:149], v[198:201], v[36:39]
	v_mfma_f32_16x16x32_bf16 v[32:35], v[154:157], v[198:201], v[32:35]
	v_mfma_f32_16x16x32_bf16 v[20:23], v[146:149], v[206:209], v[20:23]
	v_mfma_f32_16x16x32_bf16 v[16:19], v[154:157], v[206:209], v[16:19]
	v_mfma_f32_16x16x32_bf16 v[60:63], v[150:153], v[182:185], v[60:63]
	v_mfma_f32_16x16x32_bf16 v[56:59], v[158:161], v[182:185], v[56:59]
	v_mfma_f32_16x16x32_bf16 v[52:55], v[150:153], v[194:197], v[52:55]
	v_mfma_f32_16x16x32_bf16 v[48:51], v[158:161], v[194:197], v[48:51]
	v_mfma_f32_16x16x32_bf16 v[36:39], v[150:153], v[202:205], v[36:39]
	v_mfma_f32_16x16x32_bf16 v[32:35], v[158:161], v[202:205], v[32:35]
	v_mfma_f32_16x16x32_bf16 v[20:23], v[150:153], v[210:213], v[20:23]
	v_mfma_f32_16x16x32_bf16 v[16:19], v[158:161], v[210:213], v[16:19]
	v_mfma_f32_16x16x32_bf16 v[44:47], v[162:165], v[178:181], v[44:47]
	v_mfma_f32_16x16x32_bf16 v[40:43], v[170:173], v[178:181], v[40:43]
	v_mfma_f32_16x16x32_bf16 v[28:31], v[162:165], v[186:189], v[28:31]
	v_mfma_f32_16x16x32_bf16 v[24:27], v[170:173], v[186:189], v[24:27]
	v_mfma_f32_16x16x32_bf16 v[12:15], v[162:165], v[198:201], v[12:15]
	v_mfma_f32_16x16x32_bf16 v[8:11], v[170:173], v[198:201], v[8:11]
	v_mfma_f32_16x16x32_bf16 v[4:7], v[162:165], v[206:209], v[4:7]
	v_mfma_f32_16x16x32_bf16 v[0:3], v[170:173], v[206:209], v[0:3]
	v_mfma_f32_16x16x32_bf16 v[44:47], v[166:169], v[182:185], v[44:47]
	v_mfma_f32_16x16x32_bf16 v[40:43], v[174:177], v[182:185], v[40:43]
	v_mfma_f32_16x16x32_bf16 v[28:31], v[166:169], v[194:197], v[28:31]
	v_mfma_f32_16x16x32_bf16 v[24:27], v[174:177], v[194:197], v[24:27]
	v_mfma_f32_16x16x32_bf16 v[12:15], v[166:169], v[202:205], v[12:15]
	v_mfma_f32_16x16x32_bf16 v[8:11], v[174:177], v[202:205], v[8:11]
	v_mfma_f32_16x16x32_bf16 v[4:7], v[166:169], v[210:213], v[4:7]
	v_mfma_f32_16x16x32_bf16 v[0:3], v[174:177], v[210:213], v[0:3]
	s_barrier
	s_add_i32 s47, s47, 2
	s_add_u32 s45, s45, 0x100
	s_addc_u32 s46, s46, 0
	s_add_u32 s22, s22, 0x100
	s_addc_u32 s23, s23, 0
	s_cmp_gt_u32 s47, 13
	s_cbranch_scc0 .LBB0_463
	s_and_b64 vcc, exec, s[8:9]
	s_cbranch_vccz .LBB0_466
	s_barrier

; #define PG8_STAGE(bufoff, gbase, voff) do { _Pragma("unroll") for (int _i = 0; _i < 2; ++_i) \
;         __builtin_amdgcn_global_load_lds((const unsigned*)((const char*)(gbase) + (voff)[_i]), (LAS unsigned*)(lds + (bufoff) + ldsw + _i * 8192), 16, 0, 0); } while (0)
; #define PG8_LDA(dst, b, h) do { _Pragma("unroll") for (int m = 0; m < 4; ++m) _Pragma("unroll") for (int k = 0; k < 2; ++k) dst[m][k] = *(const LAS bf16x8*)(lds + PG8_SA(b, h) + aoff + m * 2048 + k * 1024); } while (0)
; #define PG8_LDB(dst, b, h) do { _Pragma("unroll") for (int n = 0; n < 2; ++n) _Pragma("unroll") for (int k = 0; k < 2; ++k) dst[n][k] = *(const LAS bf16x8*)(lds + PG8_SB(b, h) + boff + n * 2048 + k * 1024); } while (0)
; #define PG8_MMA(ai, bj, At, Bt) do { __builtin_amdgcn_s_setprio(1); _Pragma("unroll") for (int m = 0; m < 4; ++m) _Pragma("unroll") for (int n = 0; n < 2; ++n) _Pragma("unroll") for (int k = 0; k < 2; ++k) \
;         acc[ai][bj][m][n] = __builtin_amdgcn_mfma_f32_16x16x32_bf16(Bt[n][k], At[m][k], acc[ai][bj][m][n], 0, 0, 0); __builtin_amdgcn_s_setprio(0); } while (0)
; #define PG8_WAIT_V(n) asm volatile("s_waitcnt vmcnt(" #n ")" ::: "memory")
; #define PG8_WAIT_L(n) asm volatile("s_waitcnt lgkmcnt(" #n ")" ::: "memory")
; #define PG8_BAR __builtin_amdgcn_s_barrier()
; #define PG8_SCHED __builtin_amdgcn_sched_barrier(0)
; template <class Epi>
; DI void gemm_phase(int wv, LAS unsigned char* lds, LAS unsigned char* scr, const Sched& S, const Epi& E) {
;     ...
;             const bool last = (t == nt - 2);
;             const char* a1 = cA + (size_t)(t + 1) * kstep;
;             const char* a2 = last ? nA : cA + (size_t)(t + 2) * kstep; const char* b2 = last ? nB : cB + (size_t)(t + 2) * kstep;
;             const char* a3 = a2 + kstep; const char* b3 = b2 + kstep;
;             PG8_LDB(B0, 0, 0); PG8_LDB(B1, 0, 1); PG8_SCHED; PG8_LDA(At, 0, 0); PG8_STAGE(PG8_SA(1, 1), a1 + hstepA, voffA);
;             PG8_WAIT_V(8); PG8_WAIT_L(0); PG8_BAR; PG8_MMA(0, 0, At, B0); PG8_MMA(0, 1, At, B1); PG8_BAR; PG8_SCHED;
;             PG8_LDA(At, 0, 1); PG8_STAGE(PG8_SB(0, 0), b2, voffB); PG8_STAGE(PG8_SB(0, 1), b2 + hstepB, voffB); PG8_STAGE(PG8_SA(0, 0), a2, voffA);
.LBB0_588:
	s_add_u32 s28, s12, 0xfffc0080
	s_addc_u32 s29, s13, -1
	s_add_i32 s49, 0, 0x10000
	s_cmp_eq_u32 s33, 12
	s_cselect_b32 s31, s17, s29
	s_cselect_b32 s30, s19, s28
	v_add_u32_e32 v143, s49, v146
	s_cselect_b32 s29, s21, s27
	s_cselect_b32 s28, s20, s25
	s_add_i32 s52, 0, 0x14000
	ds_read_b128 v[168:171], v143
	ds_read_b128 v[172:175], v143 offset:1024
	ds_read_b128 v[176:179], v143 offset:2048
	ds_read_b128 v[180:183], v143 offset:3072
	v_add_u32_e32 v143, s52, v146
	ds_read_b128 v[184:187], v143
	ds_read_b128 v[188:191], v143 offset:1024
	ds_read_b128 v[194:197], v143 offset:2048
	ds_read_b128 v[198:201], v143 offset:3072
	v_lshl_add_u64 v[144:145], s[12:13], 0, v[140:141]
	s_add_i32 m0, s39, 0xc000
	ds_read_b128 v[202:205], v166
	ds_read_b128 v[206:209], v166 offset:1024
	ds_read_b128 v[210:213], v166 offset:2048
	ds_read_b128 v[214:217], v166 offset:3072
	ds_read_b128 v[218:221], v166 offset:4096
	ds_read_b128 v[222:225], v166 offset:5120
	ds_read_b128 v[226:229], v166 offset:6144
	ds_read_b128 v[230:233], v166 offset:7168
	global_load_lds_dwordx4 v[144:145], off
	v_lshl_add_u64 v[144:145], s[12:13], 0, v[138:139]
	s_add_i32 m0, s39, 0xe000
	s_nop 0
	global_load_lds_dwordx4 v[144:145], off
	s_waitcnt vmcnt(8)
	s_waitcnt lgkmcnt(0)
	s_barrier
	s_waitcnt lgkmcnt(0)
	v_mfma_f32_16x16x32_bf16 v[124:127], v[168:171], v[202:205], v[124:127]
	v_mfma_f32_16x16x32_bf16 v[120:123], v[176:179], v[202:205], v[120:123]
	v_mfma_f32_16x16x32_bf16 v[108:111], v[168:171], v[210:213], v[108:111]
	v_mfma_f32_16x16x32_bf16 v[104:107], v[176:179], v[210:213], v[104:107]
	v_mfma_f32_16x16x32_bf16 v[92:95], v[168:171], v[218:221], v[92:95]
	v_mfma_f32_16x16x32_bf16 v[88:91], v[176:179], v[218:221], v[88:91]
	v_mfma_f32_16x16x32_bf16 v[76:79], v[168:171], v[226:229], v[76:79]
	v_mfma_f32_16x16x32_bf16 v[72:75], v[176:179], v[226:229], v[72:75]
	v_mfma_f32_16x16x32_bf16 v[124:127], v[172:175], v[206:209], v[124:127]
	v_mfma_f32_16x16x32_bf16 v[120:123], v[180:183], v[206:209], v[120:123]
	v_mfma_f32_16x16x32_bf16 v[108:111], v[172:175], v[214:217], v[108:111]
	v_mfma_f32_16x16x32_bf16 v[104:107], v[180:183], v[214:217], v[104:107]
	v_mfma_f32_16x16x32_bf16 v[92:95], v[172:175], v[222:225], v[92:95]
	v_mfma_f32_16x16x32_bf16 v[88:91], v[180:183], v[222:225], v[88:91]
	v_mfma_f32_16x16x32_bf16 v[76:79], v[172:175], v[230:233], v[76:79]
	v_mfma_f32_16x16x32_bf16 v[72:75], v[180:183], v[230:233], v[72:75]
	v_mfma_f32_16x16x32_bf16 v[116:119], v[184:187], v[202:205], v[116:119]
	v_mfma_f32_16x16x32_bf16 v[112:115], v[194:197], v[202:205], v[112:115]
	v_mfma_f32_16x16x32_bf16 v[100:103], v[184:187], v[210:213], v[100:103]
	v_mfma_f32_16x16x32_bf16 v[96:99], v[194:197], v[210:213], v[96:99]
	v_mfma_f32_16x16x32_bf16 v[84:87], v[184:187], v[218:221], v[84:87]
	v_mfma_f32_16x16x32_bf16 v[80:83], v[194:197], v[218:221], v[80:83]
	v_mfma_f32_16x16x32_bf16 v[68:71], v[184:187], v[226:229], v[68:71]
	v_mfma_f32_16x16x32_bf16 v[64:67], v[194:197], v[226:229], v[64:67]
	v_mfma_f32_16x16x32_bf16 v[116:119], v[188:191], v[206:209], v[116:119]
	v_mfma_f32_16x16x32_bf16 v[112:115], v[198:201], v[206:209], v[112:115]
	v_mfma_f32_16x16x32_bf16 v[100:103], v[188:191], v[214:217], v[100:103]
	v_mfma_f32_16x16x32_bf16 v[96:99], v[198:201], v[214:217], v[96:99]
	v_mfma_f32_16x16x32_bf16 v[84:87], v[188:191], v[222:225], v[84:87]
	v_mfma_f32_16x16x32_bf16 v[80:83], v[198:201], v[222:225], v[80:83]
	v_mfma_f32_16x16x32_bf16 v[68:71], v[188:191], v[230:233], v[68:71]
	v_mfma_f32_16x16x32_bf16 v[64:67], v[198:201], v[230:233], v[64:67]
	s_barrier
	s_add_i32 s49, s49, s38
	v_lshl_add_u64 v[144:145], s[28:29], 0, v[130:131]
	s_mov_b32 m0, s49
	ds_read_b128 v[202:205], v166 offset:16384
	ds_read_b128 v[206:209], v166 offset:17408
	ds_read_b128 v[210:213], v166 offset:18432
	ds_read_b128 v[214:217], v166 offset:19456
	ds_read_b128 v[218:221], v166 offset:20480
	ds_read_b128 v[222:225], v166 offset:21504
	ds_read_b128 v[226:229], v166 offset:22528
	ds_read_b128 v[230:233], v166 offset:23552
	global_load_lds_dwordx4 v[144:145], off
	s_add_i32 m0, s49, 0x2000
	s_add_u32 s50, s28, 0x40000
	v_lshl_add_u64 v[234:235], s[28:29], 0, v[134:135]
	s_addc_u32 s51, s29, 0
	s_add_i32 s49, s52, s38
	global_load_lds_dwordx4 v[234:235], off
	v_lshl_add_u64 v[236:237], s[50:51], 0, v[130:131]
	s_mov_b32 m0, s49
	v_lshl_add_u64 v[238:239], s[30:31], 0, v[132:133]
	global_load_lds_dwordx4 v[236:237], off
	v_lshl_add_u64 v[236:237], s[50:51], 0, v[134:135]
	s_add_i32 m0, s49, 0x2000
	s_nop 0
	global_load_lds_dwordx4 v[236:237], off
	v_lshl_add_u64 v[236:237], s[30:31], 0, v[128:129]
	s_mov_b32 m0, s39
	s_nop 0
	global_load_lds_dwordx4 v[236:237], off
	s_mov_b32 m0, s42
	s_nop 0
	global_load_lds_dwordx4 v[238:239], off
	s_waitcnt vmcnt(8)
	s_waitcnt lgkmcnt(0)
	s_barrier
; #define PG8_STAGE(bufoff, gbase, voff) do { _Pragma("unroll") for (int _i = 0; _i < 2; ++_i) \
;         __builtin_amdgcn_global_load_lds((const unsigned*)((const char*)(gbase) + (voff)[_i]), (LAS unsigned*)(lds + (bufoff) + ldsw + _i * 8192), 16, 0, 0); } while (0)
; #define PG8_LDA(dst, b, h) do { _Pragma("unroll") for (int m = 0; m < 4; ++m) _Pragma("unroll") for (int k = 0; k < 2; ++k) dst[m][k] = *(const LAS bf16x8*)(lds + PG8_SA(b, h) + aoff + m * 2048 + k * 1024); } while (0)
; #define PG8_LDB(dst, b, h) do { _Pragma("unroll") for (int n = 0; n < 2; ++n) _Pragma("unroll") for (int k = 0; k < 2; ++k) dst[n][k] = *(const LAS bf16x8*)(lds + PG8_SB(b, h) + boff + n * 2048 + k * 1024); } while (0)
; #define PG8_MMA(ai, bj, At, Bt) do { __builtin_amdgcn_s_setprio(1); _Pragma("unroll") for (int m = 0; m < 4; ++m) _Pragma("unroll") for (int n = 0; n < 2; ++n) _Pragma("unroll") for (int k = 0; k < 2; ++k) \
;         acc[ai][bj][m][n] = __builtin_amdgcn_mfma_f32_16x16x32_bf16(Bt[n][k], At[m][k], acc[ai][bj][m][n], 0, 0, 0); __builtin_amdgcn_s_setprio(0); } while (0)
; #define PG8_WAIT_V(n) asm volatile("s_waitcnt vmcnt(" #n ")" ::: "memory")
; #define PG8_WAIT_L(n) asm volatile("s_waitcnt lgkmcnt(" #n ")" ::: "memory")
; #define PG8_BAR __builtin_amdgcn_s_barrier()
; #define PG8_SCHED __builtin_amdgcn_sched_barrier(0)
; template <class Epi>
; DI void gemm_phase(int wv, LAS unsigned char* lds, LAS unsigned char* scr, const Sched& S, const Epi& E) {
;     ...
;             PG8_WAIT_V(8); PG8_WAIT_L(0); PG8_BAR; PG8_MMA(1, 0, At, B0); PG8_MMA(1, 1, At, B1); PG8_BAR; PG8_SCHED;
;             PG8_LDB(B0, 1, 0); PG8_LDB(B1, 1, 1); PG8_SCHED; PG8_LDA(At, 1, 0); PG8_STAGE(PG8_SA(0, 1), a2 + hstepA, voffA);
;             PG8_WAIT_V(8); PG8_WAIT_L(0); PG8_BAR; PG8_MMA(0, 0, At, B0); PG8_MMA(0, 1, At, B1); PG8_BAR; PG8_SCHED;
	s_waitcnt lgkmcnt(0)
	v_mfma_f32_16x16x32_bf16 v[60:63], v[168:171], v[202:205], v[60:63]
	v_mfma_f32_16x16x32_bf16 v[56:59], v[176:179], v[202:205], v[56:59]
	v_mfma_f32_16x16x32_bf16 v[44:47], v[168:171], v[210:213], v[44:47]
	v_mfma_f32_16x16x32_bf16 v[40:43], v[176:179], v[210:213], v[40:43]
	v_mfma_f32_16x16x32_bf16 v[28:31], v[168:171], v[218:221], v[28:31]
	v_mfma_f32_16x16x32_bf16 v[24:27], v[176:179], v[218:221], v[24:27]
	v_mfma_f32_16x16x32_bf16 v[12:15], v[168:171], v[226:229], v[12:15]
	v_mfma_f32_16x16x32_bf16 v[8:11], v[176:179], v[226:229], v[8:11]
	v_mfma_f32_16x16x32_bf16 v[60:63], v[172:175], v[206:209], v[60:63]
	v_mfma_f32_16x16x32_bf16 v[56:59], v[180:183], v[206:209], v[56:59]
	v_mfma_f32_16x16x32_bf16 v[44:47], v[172:175], v[214:217], v[44:47]
	v_mfma_f32_16x16x32_bf16 v[40:43], v[180:183], v[214:217], v[40:43]
	v_mfma_f32_16x16x32_bf16 v[28:31], v[172:175], v[222:225], v[28:31]
	v_mfma_f32_16x16x32_bf16 v[24:27], v[180:183], v[222:225], v[24:27]
	v_mfma_f32_16x16x32_bf16 v[12:15], v[172:175], v[230:233], v[12:15]
	v_mfma_f32_16x16x32_bf16 v[8:11], v[180:183], v[230:233], v[8:11]
	v_mfma_f32_16x16x32_bf16 v[52:55], v[184:187], v[202:205], v[52:55]
	v_mfma_f32_16x16x32_bf16 v[48:51], v[194:197], v[202:205], v[48:51]
	v_mfma_f32_16x16x32_bf16 v[36:39], v[184:187], v[210:213], v[36:39]
	v_mfma_f32_16x16x32_bf16 v[32:35], v[194:197], v[210:213], v[32:35]
	v_mfma_f32_16x16x32_bf16 v[20:23], v[184:187], v[218:221], v[20:23]
	v_mfma_f32_16x16x32_bf16 v[16:19], v[194:197], v[218:221], v[16:19]
	v_mfma_f32_16x16x32_bf16 v[4:7], v[184:187], v[226:229], v[4:7]
	v_mfma_f32_16x16x32_bf16 v[0:3], v[194:197], v[226:229], v[0:3]
	v_mfma_f32_16x16x32_bf16 v[52:55], v[188:191], v[206:209], v[52:55]
	v_mfma_f32_16x16x32_bf16 v[48:51], v[198:201], v[206:209], v[48:51]
	v_mfma_f32_16x16x32_bf16 v[36:39], v[188:191], v[214:217], v[36:39]
	v_mfma_f32_16x16x32_bf16 v[32:35], v[198:201], v[214:217], v[32:35]
	v_mfma_f32_16x16x32_bf16 v[20:23], v[188:191], v[222:225], v[20:23]
	v_mfma_f32_16x16x32_bf16 v[16:19], v[198:201], v[222:225], v[16:19]
	v_mfma_f32_16x16x32_bf16 v[4:7], v[188:191], v[230:233], v[4:7]
	v_mfma_f32_16x16x32_bf16 v[0:3], v[198:201], v[230:233], v[0:3]
	s_barrier
	s_add_i32 s49, 0, 0x18000
	v_add_u32_e32 v143, s49, v146
	s_add_i32 s50, 0, 0x1c000
	ds_read_b128 v[168:171], v143
	ds_read_b128 v[172:175], v143 offset:1024
	ds_read_b128 v[176:179], v143 offset:2048
	ds_read_b128 v[180:183], v143 offset:3072
	v_add_u32_e32 v143, s50, v146
	ds_read_b128 v[184:187], v143
	ds_read_b128 v[188:191], v143 offset:1024
	ds_read_b128 v[194:197], v143 offset:2048
	ds_read_b128 v[198:201], v143 offset:3072
	s_add_u32 s30, s30, 0x40000
	s_addc_u32 s31, s31, 0
	s_mov_b32 m0, s43
	v_lshl_add_u64 v[240:241], s[30:31], 0, v[128:129]
	ds_read_b128 v[202:205], v166 offset:32768
	ds_read_b128 v[206:209], v166 offset:33792
	ds_read_b128 v[210:213], v166 offset:34816
	ds_read_b128 v[214:217], v166 offset:35840
	ds_read_b128 v[218:221], v166 offset:36864
	ds_read_b128 v[222:225], v166 offset:37888
	ds_read_b128 v[226:229], v166 offset:38912
	ds_read_b128 v[230:233], v166 offset:39936
	global_load_lds_dwordx4 v[240:241], off
	v_lshl_add_u64 v[240:241], s[30:31], 0, v[132:133]
	s_mov_b32 m0, s44
	s_nop 0
	global_load_lds_dwordx4 v[240:241], off
	s_waitcnt vmcnt(8)
	s_waitcnt lgkmcnt(0)
	s_barrier
	s_waitcnt lgkmcnt(0)
	v_mfma_f32_16x16x32_bf16 v[124:127], v[168:171], v[202:205], v[124:127]
	v_mfma_f32_16x16x32_bf16 v[120:123], v[176:179], v[202:205], v[120:123]
	v_mfma_f32_16x16x32_bf16 v[108:111], v[168:171], v[210:213], v[108:111]
	v_mfma_f32_16x16x32_bf16 v[104:107], v[176:179], v[210:213], v[104:107]
	v_mfma_f32_16x16x32_bf16 v[92:95], v[168:171], v[218:221], v[92:95]
	v_mfma_f32_16x16x32_bf16 v[88:91], v[176:179], v[218:221], v[88:91]
	v_mfma_f32_16x16x32_bf16 v[76:79], v[168:171], v[226:229], v[76:79]
	v_mfma_f32_16x16x32_bf16 v[72:75], v[176:179], v[226:229], v[72:75]
	v_mfma_f32_16x16x32_bf16 v[124:127], v[172:175], v[206:209], v[124:127]
	v_mfma_f32_16x16x32_bf16 v[120:123], v[180:183], v[206:209], v[120:123]
	v_mfma_f32_16x16x32_bf16 v[108:111], v[172:175], v[214:217], v[108:111]
	v_mfma_f32_16x16x32_bf16 v[104:107], v[180:183], v[214:217], v[104:107]
	v_mfma_f32_16x16x32_bf16 v[92:95], v[172:175], v[222:225], v[92:95]
	v_mfma_f32_16x16x32_bf16 v[88:91], v[180:183], v[222:225], v[88:91]
	v_mfma_f32_16x16x32_bf16 v[76:79], v[172:175], v[230:233], v[76:79]
	v_mfma_f32_16x16x32_bf16 v[72:75], v[180:183], v[230:233], v[72:75]
	v_mfma_f32_16x16x32_bf16 v[116:119], v[184:187], v[202:205], v[116:119]
	v_mfma_f32_16x16x32_bf16 v[112:115], v[194:197], v[202:205], v[112:115]
	v_mfma_f32_16x16x32_bf16 v[100:103], v[184:187], v[210:213], v[100:103]
	v_mfma_f32_16x16x32_bf16 v[96:99], v[194:197], v[210:213], v[96:99]
	v_mfma_f32_16x16x32_bf16 v[84:87], v[184:187], v[218:221], v[84:87]
	v_mfma_f32_16x16x32_bf16 v[80:83], v[194:197], v[218:221], v[80:83]
	v_mfma_f32_16x16x32_bf16 v[68:71], v[184:187], v[226:229], v[68:71]
	v_mfma_f32_16x16x32_bf16 v[64:67], v[194:197], v[226:229], v[64:67]
	v_mfma_f32_16x16x32_bf16 v[116:119], v[188:191], v[206:209], v[116:119]
	v_mfma_f32_16x16x32_bf16 v[112:115], v[198:201], v[206:209], v[112:115]
	v_mfma_f32_16x16x32_bf16 v[100:103], v[188:191], v[214:217], v[100:103]
	v_mfma_f32_16x16x32_bf16 v[96:99], v[198:201], v[214:217], v[96:99]
	v_mfma_f32_16x16x32_bf16 v[84:87], v[188:191], v[222:225], v[84:87]
	v_mfma_f32_16x16x32_bf16 v[80:83], v[198:201], v[222:225], v[80:83]
	v_mfma_f32_16x16x32_bf16 v[68:71], v[188:191], v[230:233], v[68:71]
	v_mfma_f32_16x16x32_bf16 v[64:67], v[198:201], v[230:233], v[64:67]
	s_barrier
; #define PG8_STAGE(bufoff, gbase, voff) do { _Pragma("unroll") for (int _i = 0; _i < 2; ++_i) \
;         __builtin_amdgcn_global_load_lds((const unsigned*)((const char*)(gbase) + (voff)[_i]), (LAS unsigned*)(lds + (bufoff) + ldsw + _i * 8192), 16, 0, 0); } while (0)
; #define PG8_LDA(dst, b, h) do { _Pragma("unroll") for (int m = 0; m < 4; ++m) _Pragma("unroll") for (int k = 0; k < 2; ++k) dst[m][k] = *(const LAS bf16x8*)(lds + PG8_SA(b, h) + aoff + m * 2048 + k * 1024); } while (0)
; #define PG8_MMA(ai, bj, At, Bt) do { __builtin_amdgcn_s_setprio(1); _Pragma("unroll") for (int m = 0; m < 4; ++m) _Pragma("unroll") for (int n = 0; n < 2; ++n) _Pragma("unroll") for (int k = 0; k < 2; ++k) \
;         acc[ai][bj][m][n] = __builtin_amdgcn_mfma_f32_16x16x32_bf16(Bt[n][k], At[m][k], acc[ai][bj][m][n], 0, 0, 0); __builtin_amdgcn_s_setprio(0); } while (0)
; #define PG8_WAIT_V(n) asm volatile("s_waitcnt vmcnt(" #n ")" ::: "memory")
; #define PG8_WAIT_L(n) asm volatile("s_waitcnt lgkmcnt(" #n ")" ::: "memory")
; #define PG8_BAR __builtin_amdgcn_s_barrier()
; #define PG8_SCHED __builtin_amdgcn_sched_barrier(0)
; template <class Epi>
; DI void gemm_phase(int wv, LAS unsigned char* lds, LAS unsigned char* scr, const Sched& S, const Epi& E) {
;     ...
;             PG8_LDA(At, 1, 1); PG8_STAGE(PG8_SB(1, 0), b3, voffB); PG8_STAGE(PG8_SB(1, 1), b3 + hstepB, voffB); PG8_STAGE(PG8_SA(1, 0), a3, voffA);
;             PG8_WAIT_V(8); PG8_WAIT_L(0); PG8_BAR; PG8_MMA(1, 0, At, B0); PG8_MMA(1, 1, At, B1); PG8_BAR; PG8_SCHED;
;         }
;         if (wr == 0) PG8_BAR;
	s_add_i32 s30, s49, s38
	v_lshl_add_u64 v[144:145], v[144:145], 0, s[2:3]
	s_mov_b32 m0, s30
	ds_read_b128 v[202:205], v166 offset:49152
	ds_read_b128 v[206:209], v166 offset:50176
	ds_read_b128 v[210:213], v166 offset:51200
	ds_read_b128 v[214:217], v166 offset:52224
	ds_read_b128 v[218:221], v166 offset:53248
	ds_read_b128 v[222:225], v166 offset:54272
	ds_read_b128 v[226:229], v166 offset:55296
	ds_read_b128 v[230:233], v166 offset:56320
	global_load_lds_dwordx4 v[144:145], off
	s_add_i32 m0, s30, 0x2000
	s_add_u32 s28, s28, 0x40080
	v_lshl_add_u64 v[144:145], v[234:235], 0, s[2:3]
	s_addc_u32 s29, s29, 0
	s_add_i32 s30, s50, s38
	global_load_lds_dwordx4 v[144:145], off
	v_lshl_add_u64 v[144:145], s[28:29], 0, v[130:131]
	s_mov_b32 m0, s30
	s_nop 0
	global_load_lds_dwordx4 v[144:145], off
	v_lshl_add_u64 v[144:145], s[28:29], 0, v[134:135]
	s_add_i32 m0, s30, 0x2000
	s_nop 0
	global_load_lds_dwordx4 v[144:145], off
	v_lshl_add_u64 v[144:145], v[236:237], 0, s[2:3]
	s_mov_b32 m0, s45
	s_nop 0
	global_load_lds_dwordx4 v[144:145], off
	v_lshl_add_u64 v[144:145], v[238:239], 0, s[2:3]
	s_mov_b32 m0, s46
	s_nop 0
	global_load_lds_dwordx4 v[144:145], off
	s_waitcnt vmcnt(8)
	s_waitcnt lgkmcnt(0)
	s_barrier
	s_waitcnt lgkmcnt(0)
	v_mfma_f32_16x16x32_bf16 v[60:63], v[168:171], v[202:205], v[60:63]
	v_mfma_f32_16x16x32_bf16 v[56:59], v[176:179], v[202:205], v[56:59]
	v_mfma_f32_16x16x32_bf16 v[44:47], v[168:171], v[210:213], v[44:47]
	v_mfma_f32_16x16x32_bf16 v[40:43], v[176:179], v[210:213], v[40:43]
	v_mfma_f32_16x16x32_bf16 v[28:31], v[168:171], v[218:221], v[28:31]
	v_mfma_f32_16x16x32_bf16 v[24:27], v[176:179], v[218:221], v[24:27]
	v_mfma_f32_16x16x32_bf16 v[12:15], v[168:171], v[226:229], v[12:15]
	v_mfma_f32_16x16x32_bf16 v[8:11], v[176:179], v[226:229], v[8:11]
	v_mfma_f32_16x16x32_bf16 v[60:63], v[172:175], v[206:209], v[60:63]
	v_mfma_f32_16x16x32_bf16 v[56:59], v[180:183], v[206:209], v[56:59]
	v_mfma_f32_16x16x32_bf16 v[44:47], v[172:175], v[214:217], v[44:47]
	v_mfma_f32_16x16x32_bf16 v[40:43], v[180:183], v[214:217], v[40:43]
	v_mfma_f32_16x16x32_bf16 v[28:31], v[172:175], v[222:225], v[28:31]
	v_mfma_f32_16x16x32_bf16 v[24:27], v[180:183], v[222:225], v[24:27]
	v_mfma_f32_16x16x32_bf16 v[12:15], v[172:175], v[230:233], v[12:15]
	v_mfma_f32_16x16x32_bf16 v[8:11], v[180:183], v[230:233], v[8:11]
	v_mfma_f32_16x16x32_bf16 v[52:55], v[184:187], v[202:205], v[52:55]
	v_mfma_f32_16x16x32_bf16 v[48:51], v[194:197], v[202:205], v[48:51]
	v_mfma_f32_16x16x32_bf16 v[36:39], v[184:187], v[210:213], v[36:39]
	v_mfma_f32_16x16x32_bf16 v[32:35], v[194:197], v[210:213], v[32:35]
	v_mfma_f32_16x16x32_bf16 v[20:23], v[184:187], v[218:221], v[20:23]
	v_mfma_f32_16x16x32_bf16 v[16:19], v[194:197], v[218:221], v[16:19]
	v_mfma_f32_16x16x32_bf16 v[4:7], v[184:187], v[226:229], v[4:7]
	v_mfma_f32_16x16x32_bf16 v[0:3], v[194:197], v[226:229], v[0:3]
	v_mfma_f32_16x16x32_bf16 v[52:55], v[188:191], v[206:209], v[52:55]
	v_mfma_f32_16x16x32_bf16 v[48:51], v[198:201], v[206:209], v[48:51]
	v_mfma_f32_16x16x32_bf16 v[36:39], v[188:191], v[214:217], v[36:39]
	v_mfma_f32_16x16x32_bf16 v[32:35], v[198:201], v[214:217], v[32:35]
	v_mfma_f32_16x16x32_bf16 v[20:23], v[188:191], v[222:225], v[20:23]
	v_mfma_f32_16x16x32_bf16 v[16:19], v[198:201], v[222:225], v[16:19]
	v_mfma_f32_16x16x32_bf16 v[4:7], v[188:191], v[230:233], v[4:7]
	v_mfma_f32_16x16x32_bf16 v[0:3], v[198:201], v[230:233], v[0:3]
	s_barrier
	s_add_i32 s33, s33, 2
	s_add_u32 s25, s25, 0x100
	s_addc_u32 s27, s27, 0
	s_add_u32 s12, s12, 0x100
	s_addc_u32 s13, s13, 0
	s_cmp_gt_u32 s33, 13
	s_cbranch_scc0 .LBB0_588
	s_and_b64 vcc, exec, s[14:15]
	s_cbranch_vccz .LBB0_591
	s_barrier

; #define PG8_STAGE(bufoff, gbase, voff) do { _Pragma("unroll") for (int _i = 0; _i < 2; ++_i) \
;         __builtin_amdgcn_global_load_lds((const unsigned*)((const char*)(gbase) + (voff)[_i]), (LAS unsigned*)(lds + (bufoff) + ldsw + _i * 8192), 16, 0, 0); } while (0)
; #define PG8_LDA(dst, b, h) do { _Pragma("unroll") for (int m = 0; m < 4; ++m) _Pragma("unroll") for (int k = 0; k < 2; ++k) dst[m][k] = *(const LAS bf16x8*)(lds + PG8_SA(b, h) + aoff + m * 2048 + k * 1024); } while (0)
; #define PG8_LDB(dst, b, h) do { _Pragma("unroll") for (int n = 0; n < 2; ++n) _Pragma("unroll") for (int k = 0; k < 2; ++k) dst[n][k] = *(const LAS bf16x8*)(lds + PG8_SB(b, h) + boff + n * 2048 + k * 1024); } while (0)
; #define PG8_MMA(ai, bj, At, Bt) do { __builtin_amdgcn_s_setprio(1); _Pragma("unroll") for (int m = 0; m < 4; ++m) _Pragma("unroll") for (int n = 0; n < 2; ++n) _Pragma("unroll") for (int k = 0; k < 2; ++k) \
;         acc[ai][bj][m][n] = __builtin_amdgcn_mfma_f32_16x16x32_bf16(Bt[n][k], At[m][k], acc[ai][bj][m][n], 0, 0, 0); __builtin_amdgcn_s_setprio(0); } while (0)
; #define PG8_WAIT_V(n) asm volatile("s_waitcnt vmcnt(" #n ")" ::: "memory")
; #define PG8_WAIT_L(n) asm volatile("s_waitcnt lgkmcnt(" #n ")" ::: "memory")
; #define PG8_BAR __builtin_amdgcn_s_barrier()
; #define PG8_SCHED __builtin_amdgcn_sched_barrier(0)
; template <class Epi>
; DI void gemm_phase(int wv, LAS unsigned char* lds, LAS unsigned char* scr, const Sched& S, const Epi& E) {
;     ...
;             const bool last = (t == nt - 2);
;             const char* a1 = cA + (size_t)(t + 1) * kstep;
;             const char* a2 = last ? nA : cA + (size_t)(t + 2) * kstep; const char* b2 = last ? nB : cB + (size_t)(t + 2) * kstep;
;             const char* a3 = a2 + kstep; const char* b3 = b2 + kstep;
;             PG8_LDB(B0, 0, 0); PG8_LDB(B1, 0, 1); PG8_SCHED; PG8_LDA(At, 0, 0); PG8_STAGE(PG8_SA(1, 1), a1 + hstepA, voffA);
;             PG8_WAIT_V(8); PG8_WAIT_L(0); PG8_BAR; PG8_MMA(0, 0, At, B0); PG8_MMA(0, 1, At, B1); PG8_BAR; PG8_SCHED;
;             PG8_LDA(At, 0, 1); PG8_STAGE(PG8_SB(0, 0), b2, voffB); PG8_STAGE(PG8_SB(0, 1), b2 + hstepB, voffB); PG8_STAGE(PG8_SA(0, 0), a2, voffA);
.LBB0_684:
	s_add_u32 s24, s8, 0xfffc0080
	s_addc_u32 s25, s9, -1
	s_add_i32 s46, 0, 0x10000
	s_cmp_eq_u32 s45, 12
	s_cselect_b32 s27, s11, s25
	s_cselect_b32 s26, s15, s24
	v_add_u32_e32 v143, s46, v144
	s_cselect_b32 s25, s21, s19
	s_cselect_b32 s24, s20, s17
	s_add_i32 s48, 0, 0x14000
	ds_read_b128 v[146:149], v143
	ds_read_b128 v[150:153], v143 offset:1024
	ds_read_b128 v[154:157], v143 offset:2048
	ds_read_b128 v[158:161], v143 offset:3072
	v_add_u32_e32 v143, s48, v144
	ds_read_b128 v[162:165], v143
	ds_read_b128 v[166:169], v143 offset:1024
	ds_read_b128 v[170:173], v143 offset:2048
	ds_read_b128 v[174:177], v143 offset:3072
	v_lshl_add_u64 v[190:191], s[8:9], 0, v[140:141]
	s_add_i32 m0, s34, 0xc000
	ds_read_b128 v[178:181], v145
	ds_read_b128 v[182:185], v145 offset:1024
	ds_read_b128 v[186:189], v145 offset:2048
	ds_read_b128 v[194:197], v145 offset:3072
	ds_read_b128 v[198:201], v145 offset:4096
	ds_read_b128 v[202:205], v145 offset:5120
	ds_read_b128 v[206:209], v145 offset:6144
	ds_read_b128 v[210:213], v145 offset:7168
	global_load_lds_dwordx4 v[190:191], off
	v_lshl_add_u64 v[190:191], s[8:9], 0, v[138:139]
	s_add_i32 m0, s34, 0xe000
	s_nop 0
	global_load_lds_dwordx4 v[190:191], off
	s_waitcnt vmcnt(8)
	s_waitcnt lgkmcnt(0)
	s_barrier
	s_waitcnt lgkmcnt(0)
	v_mfma_f32_16x16x32_bf16 v[124:127], v[146:149], v[178:181], v[124:127]
	v_mfma_f32_16x16x32_bf16 v[120:123], v[154:157], v[178:181], v[120:123]
	v_mfma_f32_16x16x32_bf16 v[116:119], v[146:149], v[186:189], v[116:119]
	v_mfma_f32_16x16x32_bf16 v[112:115], v[154:157], v[186:189], v[112:115]
	v_mfma_f32_16x16x32_bf16 v[100:103], v[146:149], v[198:201], v[100:103]
	v_mfma_f32_16x16x32_bf16 v[96:99], v[154:157], v[198:201], v[96:99]
	v_mfma_f32_16x16x32_bf16 v[84:87], v[146:149], v[206:209], v[84:87]
	v_mfma_f32_16x16x32_bf16 v[80:83], v[154:157], v[206:209], v[80:83]
	v_mfma_f32_16x16x32_bf16 v[124:127], v[150:153], v[182:185], v[124:127]
	v_mfma_f32_16x16x32_bf16 v[120:123], v[158:161], v[182:185], v[120:123]
	v_mfma_f32_16x16x32_bf16 v[116:119], v[150:153], v[194:197], v[116:119]
	v_mfma_f32_16x16x32_bf16 v[112:115], v[158:161], v[194:197], v[112:115]
	v_mfma_f32_16x16x32_bf16 v[100:103], v[150:153], v[202:205], v[100:103]
	v_mfma_f32_16x16x32_bf16 v[96:99], v[158:161], v[202:205], v[96:99]
	v_mfma_f32_16x16x32_bf16 v[84:87], v[150:153], v[210:213], v[84:87]
	v_mfma_f32_16x16x32_bf16 v[80:83], v[158:161], v[210:213], v[80:83]
	v_mfma_f32_16x16x32_bf16 v[108:111], v[162:165], v[178:181], v[108:111]
	v_mfma_f32_16x16x32_bf16 v[104:107], v[170:173], v[178:181], v[104:107]
	v_mfma_f32_16x16x32_bf16 v[92:95], v[162:165], v[186:189], v[92:95]
	v_mfma_f32_16x16x32_bf16 v[88:91], v[170:173], v[186:189], v[88:91]
	v_mfma_f32_16x16x32_bf16 v[76:79], v[162:165], v[198:201], v[76:79]
	v_mfma_f32_16x16x32_bf16 v[72:75], v[170:173], v[198:201], v[72:75]
	v_mfma_f32_16x16x32_bf16 v[68:71], v[162:165], v[206:209], v[68:71]
	v_mfma_f32_16x16x32_bf16 v[64:67], v[170:173], v[206:209], v[64:67]
	v_mfma_f32_16x16x32_bf16 v[108:111], v[166:169], v[182:185], v[108:111]
	v_mfma_f32_16x16x32_bf16 v[104:107], v[174:177], v[182:185], v[104:107]
	v_mfma_f32_16x16x32_bf16 v[92:95], v[166:169], v[194:197], v[92:95]
	v_mfma_f32_16x16x32_bf16 v[88:91], v[174:177], v[194:197], v[88:91]
	v_mfma_f32_16x16x32_bf16 v[76:79], v[166:169], v[202:205], v[76:79]
	v_mfma_f32_16x16x32_bf16 v[72:75], v[174:177], v[202:205], v[72:75]
	v_mfma_f32_16x16x32_bf16 v[68:71], v[166:169], v[210:213], v[68:71]
	v_mfma_f32_16x16x32_bf16 v[64:67], v[174:177], v[210:213], v[64:67]
	s_barrier
	s_add_i32 s46, s46, s33
	v_lshl_add_u64 v[190:191], s[24:25], 0, v[132:133]
	s_mov_b32 m0, s46
	ds_read_b128 v[178:181], v145 offset:16384
	ds_read_b128 v[182:185], v145 offset:17408
	ds_read_b128 v[186:189], v145 offset:18432
	ds_read_b128 v[194:197], v145 offset:19456
	ds_read_b128 v[198:201], v145 offset:20480
	ds_read_b128 v[202:205], v145 offset:21504
	ds_read_b128 v[206:209], v145 offset:22528
	ds_read_b128 v[210:213], v145 offset:23552
	global_load_lds_dwordx4 v[190:191], off
	s_add_i32 m0, s46, 0x2000
	s_add_u32 s46, s24, 0x40000
	v_lshl_add_u64 v[214:215], s[24:25], 0, v[128:129]
	s_addc_u32 s47, s25, 0
	s_add_i32 s48, s48, s33
	global_load_lds_dwordx4 v[214:215], off
	v_lshl_add_u64 v[216:217], s[46:47], 0, v[132:133]
	s_mov_b32 m0, s48
	v_lshl_add_u64 v[218:219], s[26:27], 0, v[130:131]
	global_load_lds_dwordx4 v[216:217], off
	v_lshl_add_u64 v[216:217], s[46:47], 0, v[128:129]
	s_add_i32 m0, s48, 0x2000
	s_nop 0
	global_load_lds_dwordx4 v[216:217], off
	v_lshl_add_u64 v[216:217], s[26:27], 0, v[134:135]
	s_mov_b32 m0, s34
	s_nop 0
	global_load_lds_dwordx4 v[216:217], off
	s_mov_b32 m0, s35
	s_nop 0
	global_load_lds_dwordx4 v[218:219], off
	s_waitcnt vmcnt(8)
	s_waitcnt lgkmcnt(0)
	s_barrier
; #define PG8_STAGE(bufoff, gbase, voff) do { _Pragma("unroll") for (int _i = 0; _i < 2; ++_i) \
;         __builtin_amdgcn_global_load_lds((const unsigned*)((const char*)(gbase) + (voff)[_i]), (LAS unsigned*)(lds + (bufoff) + ldsw + _i * 8192), 16, 0, 0); } while (0)
; #define PG8_LDA(dst, b, h) do { _Pragma("unroll") for (int m = 0; m < 4; ++m) _Pragma("unroll") for (int k = 0; k < 2; ++k) dst[m][k] = *(const LAS bf16x8*)(lds + PG8_SA(b, h) + aoff + m * 2048 + k * 1024); } while (0)
; #define PG8_LDB(dst, b, h) do { _Pragma("unroll") for (int n = 0; n < 2; ++n) _Pragma("unroll") for (int k = 0; k < 2; ++k) dst[n][k] = *(const LAS bf16x8*)(lds + PG8_SB(b, h) + boff + n * 2048 + k * 1024); } while (0)
; #define PG8_MMA(ai, bj, At, Bt) do { __builtin_amdgcn_s_setprio(1); _Pragma("unroll") for (int m = 0; m < 4; ++m) _Pragma("unroll") for (int n = 0; n < 2; ++n) _Pragma("unroll") for (int k = 0; k < 2; ++k) \
;         acc[ai][bj][m][n] = __builtin_amdgcn_mfma_f32_16x16x32_bf16(Bt[n][k], At[m][k], acc[ai][bj][m][n], 0, 0, 0); __builtin_amdgcn_s_setprio(0); } while (0)
; #define PG8_WAIT_V(n) asm volatile("s_waitcnt vmcnt(" #n ")" ::: "memory")
; #define PG8_WAIT_L(n) asm volatile("s_waitcnt lgkmcnt(" #n ")" ::: "memory")
; #define PG8_BAR __builtin_amdgcn_s_barrier()
; #define PG8_SCHED __builtin_amdgcn_sched_barrier(0)
; template <class Epi>
; DI void gemm_phase(int wv, LAS unsigned char* lds, LAS unsigned char* scr, const Sched& S, const Epi& E) {
;     ...
;             PG8_WAIT_V(8); PG8_WAIT_L(0); PG8_BAR; PG8_MMA(1, 0, At, B0); PG8_MMA(1, 1, At, B1); PG8_BAR; PG8_SCHED;
;             PG8_LDB(B0, 1, 0); PG8_LDB(B1, 1, 1); PG8_SCHED; PG8_LDA(At, 1, 0); PG8_STAGE(PG8_SA(0, 1), a2 + hstepA, voffA);
;             PG8_WAIT_V(8); PG8_WAIT_L(0); PG8_BAR; PG8_MMA(0, 0, At, B0); PG8_MMA(0, 1, At, B1); PG8_BAR; PG8_SCHED;
	s_waitcnt lgkmcnt(0)
	v_mfma_f32_16x16x32_bf16 v[60:63], v[146:149], v[178:181], v[60:63]
	v_mfma_f32_16x16x32_bf16 v[56:59], v[154:157], v[178:181], v[56:59]
	v_mfma_f32_16x16x32_bf16 v[52:55], v[146:149], v[186:189], v[52:55]
	v_mfma_f32_16x16x32_bf16 v[48:51], v[154:157], v[186:189], v[48:51]
	v_mfma_f32_16x16x32_bf16 v[36:39], v[146:149], v[198:201], v[36:39]
	v_mfma_f32_16x16x32_bf16 v[32:35], v[154:157], v[198:201], v[32:35]
	v_mfma_f32_16x16x32_bf16 v[20:23], v[146:149], v[206:209], v[20:23]
	v_mfma_f32_16x16x32_bf16 v[16:19], v[154:157], v[206:209], v[16:19]
	v_mfma_f32_16x16x32_bf16 v[60:63], v[150:153], v[182:185], v[60:63]
	v_mfma_f32_16x16x32_bf16 v[56:59], v[158:161], v[182:185], v[56:59]
	v_mfma_f32_16x16x32_bf16 v[52:55], v[150:153], v[194:197], v[52:55]
	v_mfma_f32_16x16x32_bf16 v[48:51], v[158:161], v[194:197], v[48:51]
	v_mfma_f32_16x16x32_bf16 v[36:39], v[150:153], v[202:205], v[36:39]
	v_mfma_f32_16x16x32_bf16 v[32:35], v[158:161], v[202:205], v[32:35]
	v_mfma_f32_16x16x32_bf16 v[20:23], v[150:153], v[210:213], v[20:23]
	v_mfma_f32_16x16x32_bf16 v[16:19], v[158:161], v[210:213], v[16:19]
	v_mfma_f32_16x16x32_bf16 v[44:47], v[162:165], v[178:181], v[44:47]
	v_mfma_f32_16x16x32_bf16 v[40:43], v[170:173], v[178:181], v[40:43]
	v_mfma_f32_16x16x32_bf16 v[28:31], v[162:165], v[186:189], v[28:31]
	v_mfma_f32_16x16x32_bf16 v[24:27], v[170:173], v[186:189], v[24:27]
	v_mfma_f32_16x16x32_bf16 v[12:15], v[162:165], v[198:201], v[12:15]
	v_mfma_f32_16x16x32_bf16 v[8:11], v[170:173], v[198:201], v[8:11]
	v_mfma_f32_16x16x32_bf16 v[4:7], v[162:165], v[206:209], v[4:7]
	v_mfma_f32_16x16x32_bf16 v[0:3], v[170:173], v[206:209], v[0:3]
	v_mfma_f32_16x16x32_bf16 v[44:47], v[166:169], v[182:185], v[44:47]
	v_mfma_f32_16x16x32_bf16 v[40:43], v[174:177], v[182:185], v[40:43]
	v_mfma_f32_16x16x32_bf16 v[28:31], v[166:169], v[194:197], v[28:31]
	v_mfma_f32_16x16x32_bf16 v[24:27], v[174:177], v[194:197], v[24:27]
	v_mfma_f32_16x16x32_bf16 v[12:15], v[166:169], v[202:205], v[12:15]
	v_mfma_f32_16x16x32_bf16 v[8:11], v[174:177], v[202:205], v[8:11]
	v_mfma_f32_16x16x32_bf16 v[4:7], v[166:169], v[210:213], v[4:7]
	v_mfma_f32_16x16x32_bf16 v[0:3], v[174:177], v[210:213], v[0:3]
	s_barrier
	s_add_i32 s46, 0, 0x18000
	v_add_u32_e32 v143, s46, v144
	s_add_i32 s47, 0, 0x1c000
	ds_read_b128 v[146:149], v143
	ds_read_b128 v[150:153], v143 offset:1024
	ds_read_b128 v[154:157], v143 offset:2048
	ds_read_b128 v[158:161], v143 offset:3072
	v_add_u32_e32 v143, s47, v144
	ds_read_b128 v[162:165], v143
	ds_read_b128 v[166:169], v143 offset:1024
	ds_read_b128 v[170:173], v143 offset:2048
	ds_read_b128 v[174:177], v143 offset:3072
	s_add_u32 s26, s26, 0x40000
	s_addc_u32 s27, s27, 0
	s_mov_b32 m0, s36
	v_lshl_add_u64 v[220:221], s[26:27], 0, v[134:135]
	ds_read_b128 v[178:181], v145 offset:32768
	ds_read_b128 v[182:185], v145 offset:33792
	ds_read_b128 v[186:189], v145 offset:34816
	ds_read_b128 v[194:197], v145 offset:35840
	ds_read_b128 v[198:201], v145 offset:36864
	ds_read_b128 v[202:205], v145 offset:37888
	ds_read_b128 v[206:209], v145 offset:38912
	ds_read_b128 v[210:213], v145 offset:39936
	global_load_lds_dwordx4 v[220:221], off
	v_lshl_add_u64 v[220:221], s[26:27], 0, v[130:131]
	s_mov_b32 m0, s37
	s_nop 0
	global_load_lds_dwordx4 v[220:221], off
	s_waitcnt vmcnt(8)
	s_waitcnt lgkmcnt(0)
	s_barrier
	s_waitcnt lgkmcnt(0)
	v_mfma_f32_16x16x32_bf16 v[124:127], v[146:149], v[178:181], v[124:127]
	v_mfma_f32_16x16x32_bf16 v[120:123], v[154:157], v[178:181], v[120:123]
	v_mfma_f32_16x16x32_bf16 v[116:119], v[146:149], v[186:189], v[116:119]
	v_mfma_f32_16x16x32_bf16 v[112:115], v[154:157], v[186:189], v[112:115]
	v_mfma_f32_16x16x32_bf16 v[100:103], v[146:149], v[198:201], v[100:103]
	v_mfma_f32_16x16x32_bf16 v[96:99], v[154:157], v[198:201], v[96:99]
	v_mfma_f32_16x16x32_bf16 v[84:87], v[146:149], v[206:209], v[84:87]
	v_mfma_f32_16x16x32_bf16 v[80:83], v[154:157], v[206:209], v[80:83]
	v_mfma_f32_16x16x32_bf16 v[124:127], v[150:153], v[182:185], v[124:127]
	v_mfma_f32_16x16x32_bf16 v[120:123], v[158:161], v[182:185], v[120:123]
	v_mfma_f32_16x16x32_bf16 v[116:119], v[150:153], v[194:197], v[116:119]
	v_mfma_f32_16x16x32_bf16 v[112:115], v[158:161], v[194:197], v[112:115]
	v_mfma_f32_16x16x32_bf16 v[100:103], v[150:153], v[202:205], v[100:103]
	v_mfma_f32_16x16x32_bf16 v[96:99], v[158:161], v[202:205], v[96:99]
	v_mfma_f32_16x16x32_bf16 v[84:87], v[150:153], v[210:213], v[84:87]
	v_mfma_f32_16x16x32_bf16 v[80:83], v[158:161], v[210:213], v[80:83]
	v_mfma_f32_16x16x32_bf16 v[108:111], v[162:165], v[178:181], v[108:111]
	v_mfma_f32_16x16x32_bf16 v[104:107], v[170:173], v[178:181], v[104:107]
	v_mfma_f32_16x16x32_bf16 v[92:95], v[162:165], v[186:189], v[92:95]
	v_mfma_f32_16x16x32_bf16 v[88:91], v[170:173], v[186:189], v[88:91]
	v_mfma_f32_16x16x32_bf16 v[76:79], v[162:165], v[198:201], v[76:79]
	v_mfma_f32_16x16x32_bf16 v[72:75], v[170:173], v[198:201], v[72:75]
	v_mfma_f32_16x16x32_bf16 v[68:71], v[162:165], v[206:209], v[68:71]
	v_mfma_f32_16x16x32_bf16 v[64:67], v[170:173], v[206:209], v[64:67]
	v_mfma_f32_16x16x32_bf16 v[108:111], v[166:169], v[182:185], v[108:111]
	v_mfma_f32_16x16x32_bf16 v[104:107], v[174:177], v[182:185], v[104:107]
	v_mfma_f32_16x16x32_bf16 v[92:95], v[166:169], v[194:197], v[92:95]
	v_mfma_f32_16x16x32_bf16 v[88:91], v[174:177], v[194:197], v[88:91]
	v_mfma_f32_16x16x32_bf16 v[76:79], v[166:169], v[202:205], v[76:79]
	v_mfma_f32_16x16x32_bf16 v[72:75], v[174:177], v[202:205], v[72:75]
	v_mfma_f32_16x16x32_bf16 v[68:71], v[166:169], v[210:213], v[68:71]
	v_mfma_f32_16x16x32_bf16 v[64:67], v[174:177], v[210:213], v[64:67]
	s_barrier
; #define PG8_STAGE(bufoff, gbase, voff) do { _Pragma("unroll") for (int _i = 0; _i < 2; ++_i) \
;         __builtin_amdgcn_global_load_lds((const unsigned*)((const char*)(gbase) + (voff)[_i]), (LAS unsigned*)(lds + (bufoff) + ldsw + _i * 8192), 16, 0, 0); } while (0)
; #define PG8_LDA(dst, b, h) do { _Pragma("unroll") for (int m = 0; m < 4; ++m) _Pragma("unroll") for (int k = 0; k < 2; ++k) dst[m][k] = *(const LAS bf16x8*)(lds + PG8_SA(b, h) + aoff + m * 2048 + k * 1024); } while (0)
; #define PG8_MMA(ai, bj, At, Bt) do { __builtin_amdgcn_s_setprio(1); _Pragma("unroll") for (int m = 0; m < 4; ++m) _Pragma("unroll") for (int n = 0; n < 2; ++n) _Pragma("unroll") for (int k = 0; k < 2; ++k) \
;         acc[ai][bj][m][n] = __builtin_amdgcn_mfma_f32_16x16x32_bf16(Bt[n][k], At[m][k], acc[ai][bj][m][n], 0, 0, 0); __builtin_amdgcn_s_setprio(0); } while (0)
; #define PG8_WAIT_V(n) asm volatile("s_waitcnt vmcnt(" #n ")" ::: "memory")
; #define PG8_WAIT_L(n) asm volatile("s_waitcnt lgkmcnt(" #n ")" ::: "memory")
; #define PG8_BAR __builtin_amdgcn_s_barrier()
; #define PG8_SCHED __builtin_amdgcn_sched_barrier(0)
; template <class Epi>
; DI void gemm_phase(int wv, LAS unsigned char* lds, LAS unsigned char* scr, const Sched& S, const Epi& E) {
;     ...
;             PG8_LDA(At, 1, 1); PG8_STAGE(PG8_SB(1, 0), b3, voffB); PG8_STAGE(PG8_SB(1, 1), b3 + hstepB, voffB); PG8_STAGE(PG8_SA(1, 0), a3, voffA);
;             PG8_WAIT_V(8); PG8_WAIT_L(0); PG8_BAR; PG8_MMA(1, 0, At, B0); PG8_MMA(1, 1, At, B1); PG8_BAR; PG8_SCHED;
;         }
;         if (wr == 0) PG8_BAR;
	s_add_i32 s26, s46, s33
	v_lshl_add_u64 v[190:191], v[190:191], 0, s[2:3]
	s_mov_b32 m0, s26
	ds_read_b128 v[178:181], v145 offset:49152
	ds_read_b128 v[182:185], v145 offset:50176
	ds_read_b128 v[186:189], v145 offset:51200
	ds_read_b128 v[194:197], v145 offset:52224
	ds_read_b128 v[198:201], v145 offset:53248
	ds_read_b128 v[202:205], v145 offset:54272
	ds_read_b128 v[206:209], v145 offset:55296
	ds_read_b128 v[210:213], v145 offset:56320
	global_load_lds_dwordx4 v[190:191], off
	s_add_i32 m0, s26, 0x2000
	s_add_u32 s24, s24, 0x40080
	v_lshl_add_u64 v[190:191], v[214:215], 0, s[2:3]
	s_addc_u32 s25, s25, 0
	s_add_i32 s26, s47, s33
	global_load_lds_dwordx4 v[190:191], off
	v_lshl_add_u64 v[190:191], s[24:25], 0, v[132:133]
	s_mov_b32 m0, s26
	s_nop 0
	global_load_lds_dwordx4 v[190:191], off
	v_lshl_add_u64 v[190:191], s[24:25], 0, v[128:129]
	s_add_i32 m0, s26, 0x2000
	s_nop 0
	global_load_lds_dwordx4 v[190:191], off
	v_lshl_add_u64 v[190:191], v[216:217], 0, s[2:3]
	s_mov_b32 m0, s42
	s_nop 0
	global_load_lds_dwordx4 v[190:191], off
	v_lshl_add_u64 v[190:191], v[218:219], 0, s[2:3]
	s_mov_b32 m0, s43
	s_nop 0
	global_load_lds_dwordx4 v[190:191], off
	s_waitcnt vmcnt(8)
	s_waitcnt lgkmcnt(0)
	s_barrier
	s_waitcnt lgkmcnt(0)
	v_mfma_f32_16x16x32_bf16 v[60:63], v[146:149], v[178:181], v[60:63]
	v_mfma_f32_16x16x32_bf16 v[56:59], v[154:157], v[178:181], v[56:59]
	v_mfma_f32_16x16x32_bf16 v[52:55], v[146:149], v[186:189], v[52:55]
	v_mfma_f32_16x16x32_bf16 v[48:51], v[154:157], v[186:189], v[48:51]
	v_mfma_f32_16x16x32_bf16 v[36:39], v[146:149], v[198:201], v[36:39]
	v_mfma_f32_16x16x32_bf16 v[32:35], v[154:157], v[198:201], v[32:35]
	v_mfma_f32_16x16x32_bf16 v[20:23], v[146:149], v[206:209], v[20:23]
	v_mfma_f32_16x16x32_bf16 v[16:19], v[154:157], v[206:209], v[16:19]
	v_mfma_f32_16x16x32_bf16 v[60:63], v[150:153], v[182:185], v[60:63]
	v_mfma_f32_16x16x32_bf16 v[56:59], v[158:161], v[182:185], v[56:59]
	v_mfma_f32_16x16x32_bf16 v[52:55], v[150:153], v[194:197], v[52:55]
	v_mfma_f32_16x16x32_bf16 v[48:51], v[158:161], v[194:197], v[48:51]
	v_mfma_f32_16x16x32_bf16 v[36:39], v[150:153], v[202:205], v[36:39]
	v_mfma_f32_16x16x32_bf16 v[32:35], v[158:161], v[202:205], v[32:35]
	v_mfma_f32_16x16x32_bf16 v[20:23], v[150:153], v[210:213], v[20:23]
	v_mfma_f32_16x16x32_bf16 v[16:19], v[158:161], v[210:213], v[16:19]
	v_mfma_f32_16x16x32_bf16 v[44:47], v[162:165], v[178:181], v[44:47]
	v_mfma_f32_16x16x32_bf16 v[40:43], v[170:173], v[178:181], v[40:43]
	v_mfma_f32_16x16x32_bf16 v[28:31], v[162:165], v[186:189], v[28:31]
	v_mfma_f32_16x16x32_bf16 v[24:27], v[170:173], v[186:189], v[24:27]
	v_mfma_f32_16x16x32_bf16 v[12:15], v[162:165], v[198:201], v[12:15]
	v_mfma_f32_16x16x32_bf16 v[8:11], v[170:173], v[198:201], v[8:11]
	v_mfma_f32_16x16x32_bf16 v[4:7], v[162:165], v[206:209], v[4:7]
	v_mfma_f32_16x16x32_bf16 v[0:3], v[170:173], v[206:209], v[0:3]
	v_mfma_f32_16x16x32_bf16 v[44:47], v[166:169], v[182:185], v[44:47]
	v_mfma_f32_16x16x32_bf16 v[40:43], v[174:177], v[182:185], v[40:43]
	v_mfma_f32_16x16x32_bf16 v[28:31], v[166:169], v[194:197], v[28:31]
	v_mfma_f32_16x16x32_bf16 v[24:27], v[174:177], v[194:197], v[24:27]
	v_mfma_f32_16x16x32_bf16 v[12:15], v[166:169], v[202:205], v[12:15]
	v_mfma_f32_16x16x32_bf16 v[8:11], v[174:177], v[202:205], v[8:11]
	v_mfma_f32_16x16x32_bf16 v[4:7], v[166:169], v[210:213], v[4:7]
	v_mfma_f32_16x16x32_bf16 v[0:3], v[174:177], v[210:213], v[0:3]
	s_barrier
	s_add_i32 s45, s45, 2
	s_add_u32 s17, s17, 0x100
	s_addc_u32 s19, s19, 0
	s_add_u32 s8, s8, 0x100
	s_addc_u32 s9, s9, 0
	s_cmp_gt_u32 s45, 13
	s_cbranch_scc0 .LBB0_684
	s_and_b64 vcc, exec, s[12:13]
	s_cbranch_vccz .LBB0_687
	s_barrier

; #define PG8_STAGE(bufoff, gbase, voff) do { _Pragma("unroll") for (int _i = 0; _i < 2; ++_i) \
;         __builtin_amdgcn_global_load_lds((const unsigned*)((const char*)(gbase) + (voff)[_i]), (LAS unsigned*)(lds + (bufoff) + ldsw + _i * 8192), 16, 0, 0); } while (0)
; #define PG8_LDA(dst, b, h) do { _Pragma("unroll") for (int m = 0; m < 4; ++m) _Pragma("unroll") for (int k = 0; k < 2; ++k) dst[m][k] = *(const LAS bf16x8*)(lds + PG8_SA(b, h) + aoff + m * 2048 + k * 1024); } while (0)
; #define PG8_LDB(dst, b, h) do { _Pragma("unroll") for (int n = 0; n < 2; ++n) _Pragma("unroll") for (int k = 0; k < 2; ++k) dst[n][k] = *(const LAS bf16x8*)(lds + PG8_SB(b, h) + boff + n * 2048 + k * 1024); } while (0)
; #define PG8_MMA(ai, bj, At, Bt) do { __builtin_amdgcn_s_setprio(1); _Pragma("unroll") for (int m = 0; m < 4; ++m) _Pragma("unroll") for (int n = 0; n < 2; ++n) _Pragma("unroll") for (int k = 0; k < 2; ++k) \
;         acc[ai][bj][m][n] = __builtin_amdgcn_mfma_f32_16x16x32_bf16(Bt[n][k], At[m][k], acc[ai][bj][m][n], 0, 0, 0); __builtin_amdgcn_s_setprio(0); } while (0)
; #define PG8_WAIT_V(n) asm volatile("s_waitcnt vmcnt(" #n ")" ::: "memory")
; #define PG8_WAIT_L(n) asm volatile("s_waitcnt lgkmcnt(" #n ")" ::: "memory")
; #define PG8_BAR __builtin_amdgcn_s_barrier()
; #define PG8_SCHED __builtin_amdgcn_sched_barrier(0)
; template <class Epi>
; DI void gemm_phase(int wv, LAS unsigned char* lds, LAS unsigned char* scr, const Sched& S, const Epi& E) {
;     ...
;             const bool last = (t == nt - 2);
;             const char* a1 = cA + (size_t)(t + 1) * kstep;
;             const char* a2 = last ? nA : cA + (size_t)(t + 2) * kstep; const char* b2 = last ? nB : cB + (size_t)(t + 2) * kstep;
;             const char* a3 = a2 + kstep; const char* b3 = b2 + kstep;
;             PG8_LDB(B0, 0, 0); PG8_LDB(B1, 0, 1); PG8_SCHED; PG8_LDA(At, 0, 0); PG8_STAGE(PG8_SA(1, 1), a1 + hstepA, voffA);
;             PG8_WAIT_V(8); PG8_WAIT_L(0); PG8_BAR; PG8_MMA(0, 0, At, B0); PG8_MMA(0, 1, At, B1); PG8_BAR; PG8_SCHED;
;             PG8_LDA(At, 0, 1); PG8_STAGE(PG8_SB(0, 0), b2, voffB); PG8_STAGE(PG8_SB(0, 1), b2 + hstepB, voffB); PG8_STAGE(PG8_SA(0, 0), a2, voffA);
.LBB0_811:
	s_add_u32 s54, s28, 0xfffc0080
	s_addc_u32 s55, s29, -1
	s_add_i32 s61, 0, 0x10000
	s_cmp_eq_u32 s60, 12
	s_cselect_b32 s57, s49, s55
	s_cselect_b32 s56, s48, s54
	s_cselect_b32 s55, s47, s59
	s_cselect_b32 s54, s53, s58
	s_add_i32 s76, 0, 0x14000
	v_add_u32_e32 v140, s61, v199
	v_add_u32_e32 v156, s76, v199
	ds_read_b128 v[128:131], v140
	ds_read_b128 v[132:135], v140 offset:1024
	ds_read_b128 v[136:139], v140 offset:2048
	ds_read_b128 v[140:143], v140 offset:3072
	ds_read_b128 v[144:147], v156
	ds_read_b128 v[148:151], v156 offset:1024
	ds_read_b128 v[152:155], v156 offset:2048
	ds_read_b128 v[156:159], v156 offset:3072
	v_lshl_add_u64 v[204:205], s[28:29], 0, v[178:179]
	s_add_i32 m0, s66, 0xc000
	ds_read_b128 v[160:163], v220
	ds_read_b128 v[164:167], v220 offset:1024
	ds_read_b128 v[180:183], v220 offset:2048
	ds_read_b128 v[184:187], v220 offset:3072
	ds_read_b128 v[188:191], v220 offset:4096
	ds_read_b128 v[194:197], v220 offset:5120
	ds_read_b128 v[200:203], v220 offset:6144
	ds_read_b128 v[222:225], v220 offset:7168
	global_load_lds_dwordx4 v[204:205], off
	v_lshl_add_u64 v[204:205], s[28:29], 0, v[176:177]
	s_add_i32 m0, s66, 0xe000
	s_nop 0
	global_load_lds_dwordx4 v[204:205], off
	s_waitcnt vmcnt(8)
	s_waitcnt lgkmcnt(0)
	s_barrier
	s_waitcnt lgkmcnt(0)
	v_mfma_f32_16x16x32_bf16 v[124:127], v[128:131], v[160:163], v[124:127]
	v_mfma_f32_16x16x32_bf16 v[92:95], v[136:139], v[160:163], v[92:95]
	v_mfma_f32_16x16x32_bf16 v[116:119], v[128:131], v[180:183], v[116:119]
	v_mfma_f32_16x16x32_bf16 v[84:87], v[136:139], v[180:183], v[84:87]
	v_mfma_f32_16x16x32_bf16 v[108:111], v[128:131], v[188:191], v[108:111]
	v_mfma_f32_16x16x32_bf16 v[76:79], v[136:139], v[188:191], v[76:79]
	v_mfma_f32_16x16x32_bf16 v[100:103], v[128:131], v[200:203], v[100:103]
	v_mfma_f32_16x16x32_bf16 v[68:71], v[136:139], v[200:203], v[68:71]
	v_mfma_f32_16x16x32_bf16 v[124:127], v[132:135], v[164:167], v[124:127]
	v_mfma_f32_16x16x32_bf16 v[92:95], v[140:143], v[164:167], v[92:95]
	v_mfma_f32_16x16x32_bf16 v[116:119], v[132:135], v[184:187], v[116:119]
	v_mfma_f32_16x16x32_bf16 v[84:87], v[140:143], v[184:187], v[84:87]
	v_mfma_f32_16x16x32_bf16 v[108:111], v[132:135], v[194:197], v[108:111]
	v_mfma_f32_16x16x32_bf16 v[76:79], v[140:143], v[194:197], v[76:79]
	v_mfma_f32_16x16x32_bf16 v[100:103], v[132:135], v[222:225], v[100:103]
	v_mfma_f32_16x16x32_bf16 v[68:71], v[140:143], v[222:225], v[68:71]
	v_mfma_f32_16x16x32_bf16 v[120:123], v[144:147], v[160:163], v[120:123]
	v_mfma_f32_16x16x32_bf16 v[88:91], v[152:155], v[160:163], v[88:91]
	v_mfma_f32_16x16x32_bf16 v[112:115], v[144:147], v[180:183], v[112:115]
	v_mfma_f32_16x16x32_bf16 v[80:83], v[152:155], v[180:183], v[80:83]
	v_mfma_f32_16x16x32_bf16 v[104:107], v[144:147], v[188:191], v[104:107]
	v_mfma_f32_16x16x32_bf16 v[72:75], v[152:155], v[188:191], v[72:75]
	v_mfma_f32_16x16x32_bf16 v[96:99], v[144:147], v[200:203], v[96:99]
	v_mfma_f32_16x16x32_bf16 v[64:67], v[152:155], v[200:203], v[64:67]
	v_mfma_f32_16x16x32_bf16 v[120:123], v[148:151], v[164:167], v[120:123]
	v_mfma_f32_16x16x32_bf16 v[88:91], v[156:159], v[164:167], v[88:91]
	v_mfma_f32_16x16x32_bf16 v[112:115], v[148:151], v[184:187], v[112:115]
	v_mfma_f32_16x16x32_bf16 v[80:83], v[156:159], v[184:187], v[80:83]
	v_mfma_f32_16x16x32_bf16 v[104:107], v[148:151], v[194:197], v[104:107]
	v_mfma_f32_16x16x32_bf16 v[72:75], v[156:159], v[194:197], v[72:75]
	v_mfma_f32_16x16x32_bf16 v[96:99], v[148:151], v[222:225], v[96:99]
	v_mfma_f32_16x16x32_bf16 v[64:67], v[156:159], v[222:225], v[64:67]
	s_barrier
	s_add_i32 s61, s61, s65
	v_lshl_add_u64 v[204:205], s[54:55], 0, v[170:171]
	s_mov_b32 m0, s61
	ds_read_b128 v[160:163], v220 offset:16384
	ds_read_b128 v[164:167], v220 offset:17408
	ds_read_b128 v[180:183], v220 offset:18432
	ds_read_b128 v[184:187], v220 offset:19456
	ds_read_b128 v[188:191], v220 offset:20480
	ds_read_b128 v[194:197], v220 offset:21504
	ds_read_b128 v[200:203], v220 offset:22528
	ds_read_b128 v[222:225], v220 offset:23552
	global_load_lds_dwordx4 v[204:205], off
	s_add_i32 m0, s61, 0x2000
	s_add_u32 s74, s54, 0x40000
	v_lshl_add_u64 v[226:227], s[54:55], 0, v[174:175]
	s_addc_u32 s75, s55, 0
	s_add_i32 s61, s76, s65
	global_load_lds_dwordx4 v[226:227], off
	v_lshl_add_u64 v[228:229], s[74:75], 0, v[170:171]
	s_mov_b32 m0, s61
	v_lshl_add_u64 v[230:231], s[56:57], 0, v[172:173]
	global_load_lds_dwordx4 v[228:229], off
	v_lshl_add_u64 v[228:229], s[74:75], 0, v[174:175]
	s_add_i32 m0, s61, 0x2000
	s_nop 0
	global_load_lds_dwordx4 v[228:229], off
	v_lshl_add_u64 v[228:229], s[56:57], 0, v[168:169]
	s_mov_b32 m0, s66
	s_nop 0
	global_load_lds_dwordx4 v[228:229], off
	s_mov_b32 m0, s67
	s_nop 0
	global_load_lds_dwordx4 v[230:231], off
	s_waitcnt vmcnt(8)
	s_waitcnt lgkmcnt(0)
	s_barrier
; #define PG8_STAGE(bufoff, gbase, voff) do { _Pragma("unroll") for (int _i = 0; _i < 2; ++_i) \
;         __builtin_amdgcn_global_load_lds((const unsigned*)((const char*)(gbase) + (voff)[_i]), (LAS unsigned*)(lds + (bufoff) + ldsw + _i * 8192), 16, 0, 0); } while (0)
; #define PG8_LDA(dst, b, h) do { _Pragma("unroll") for (int m = 0; m < 4; ++m) _Pragma("unroll") for (int k = 0; k < 2; ++k) dst[m][k] = *(const LAS bf16x8*)(lds + PG8_SA(b, h) + aoff + m * 2048 + k * 1024); } while (0)
; #define PG8_LDB(dst, b, h) do { _Pragma("unroll") for (int n = 0; n < 2; ++n) _Pragma("unroll") for (int k = 0; k < 2; ++k) dst[n][k] = *(const LAS bf16x8*)(lds + PG8_SB(b, h) + boff + n * 2048 + k * 1024); } while (0)
; #define PG8_MMA(ai, bj, At, Bt) do { __builtin_amdgcn_s_setprio(1); _Pragma("unroll") for (int m = 0; m < 4; ++m) _Pragma("unroll") for (int n = 0; n < 2; ++n) _Pragma("unroll") for (int k = 0; k < 2; ++k) \
;         acc[ai][bj][m][n] = __builtin_amdgcn_mfma_f32_16x16x32_bf16(Bt[n][k], At[m][k], acc[ai][bj][m][n], 0, 0, 0); __builtin_amdgcn_s_setprio(0); } while (0)
; #define PG8_WAIT_V(n) asm volatile("s_waitcnt vmcnt(" #n ")" ::: "memory")
; #define PG8_WAIT_L(n) asm volatile("s_waitcnt lgkmcnt(" #n ")" ::: "memory")
; #define PG8_BAR __builtin_amdgcn_s_barrier()
; #define PG8_SCHED __builtin_amdgcn_sched_barrier(0)
; template <class Epi>
; DI void gemm_phase(int wv, LAS unsigned char* lds, LAS unsigned char* scr, const Sched& S, const Epi& E) {
;     ...
;             PG8_WAIT_V(8); PG8_WAIT_L(0); PG8_BAR; PG8_MMA(1, 0, At, B0); PG8_MMA(1, 1, At, B1); PG8_BAR; PG8_SCHED;
;             PG8_LDB(B0, 1, 0); PG8_LDB(B1, 1, 1); PG8_SCHED; PG8_LDA(At, 1, 0); PG8_STAGE(PG8_SA(0, 1), a2 + hstepA, voffA);
;             PG8_WAIT_V(8); PG8_WAIT_L(0); PG8_BAR; PG8_MMA(0, 0, At, B0); PG8_MMA(0, 1, At, B1); PG8_BAR; PG8_SCHED;
	s_waitcnt lgkmcnt(0)
	v_mfma_f32_16x16x32_bf16 v[60:63], v[128:131], v[160:163], v[60:63]
	v_mfma_f32_16x16x32_bf16 v[28:31], v[136:139], v[160:163], v[28:31]
	v_mfma_f32_16x16x32_bf16 v[52:55], v[128:131], v[180:183], v[52:55]
	v_mfma_f32_16x16x32_bf16 v[20:23], v[136:139], v[180:183], v[20:23]
	v_mfma_f32_16x16x32_bf16 v[44:47], v[128:131], v[188:191], v[44:47]
	v_mfma_f32_16x16x32_bf16 v[12:15], v[136:139], v[188:191], v[12:15]
	v_mfma_f32_16x16x32_bf16 v[36:39], v[128:131], v[200:203], v[36:39]
	v_mfma_f32_16x16x32_bf16 v[4:7], v[136:139], v[200:203], v[4:7]
	v_mfma_f32_16x16x32_bf16 v[60:63], v[132:135], v[164:167], v[60:63]
	v_mfma_f32_16x16x32_bf16 v[28:31], v[140:143], v[164:167], v[28:31]
	v_mfma_f32_16x16x32_bf16 v[52:55], v[132:135], v[184:187], v[52:55]
	v_mfma_f32_16x16x32_bf16 v[20:23], v[140:143], v[184:187], v[20:23]
	v_mfma_f32_16x16x32_bf16 v[44:47], v[132:135], v[194:197], v[44:47]
	v_mfma_f32_16x16x32_bf16 v[12:15], v[140:143], v[194:197], v[12:15]
	v_mfma_f32_16x16x32_bf16 v[36:39], v[132:135], v[222:225], v[36:39]
	v_mfma_f32_16x16x32_bf16 v[4:7], v[140:143], v[222:225], v[4:7]
	v_mfma_f32_16x16x32_bf16 v[56:59], v[144:147], v[160:163], v[56:59]
	v_mfma_f32_16x16x32_bf16 v[24:27], v[152:155], v[160:163], v[24:27]
	v_mfma_f32_16x16x32_bf16 v[48:51], v[144:147], v[180:183], v[48:51]
	v_mfma_f32_16x16x32_bf16 v[16:19], v[152:155], v[180:183], v[16:19]
	v_mfma_f32_16x16x32_bf16 v[40:43], v[144:147], v[188:191], v[40:43]
	v_mfma_f32_16x16x32_bf16 v[8:11], v[152:155], v[188:191], v[8:11]
	v_mfma_f32_16x16x32_bf16 v[32:35], v[144:147], v[200:203], v[32:35]
	v_mfma_f32_16x16x32_bf16 v[0:3], v[152:155], v[200:203], v[0:3]
	v_mfma_f32_16x16x32_bf16 v[56:59], v[148:151], v[164:167], v[56:59]
	v_mfma_f32_16x16x32_bf16 v[24:27], v[156:159], v[164:167], v[24:27]
	v_mfma_f32_16x16x32_bf16 v[48:51], v[148:151], v[184:187], v[48:51]
	v_mfma_f32_16x16x32_bf16 v[16:19], v[156:159], v[184:187], v[16:19]
	v_mfma_f32_16x16x32_bf16 v[40:43], v[148:151], v[194:197], v[40:43]
	v_mfma_f32_16x16x32_bf16 v[8:11], v[156:159], v[194:197], v[8:11]
	v_mfma_f32_16x16x32_bf16 v[32:35], v[148:151], v[222:225], v[32:35]
	v_mfma_f32_16x16x32_bf16 v[0:3], v[156:159], v[222:225], v[0:3]
	s_barrier
	s_add_i32 s61, 0, 0x18000
	s_add_i32 s74, 0, 0x1c000
	v_add_u32_e32 v140, s61, v199
	v_add_u32_e32 v156, s74, v199
	ds_read_b128 v[128:131], v140
	ds_read_b128 v[132:135], v140 offset:1024
	ds_read_b128 v[136:139], v140 offset:2048
	ds_read_b128 v[140:143], v140 offset:3072
	ds_read_b128 v[144:147], v156
	ds_read_b128 v[148:151], v156 offset:1024
	ds_read_b128 v[152:155], v156 offset:2048
	ds_read_b128 v[156:159], v156 offset:3072
	s_add_u32 s56, s56, 0x40000
	s_addc_u32 s57, s57, 0
	s_mov_b32 m0, s68
	v_lshl_add_u64 v[232:233], s[56:57], 0, v[168:169]
	ds_read_b128 v[160:163], v220 offset:32768
	ds_read_b128 v[164:167], v220 offset:33792
	ds_read_b128 v[180:183], v220 offset:34816
	ds_read_b128 v[184:187], v220 offset:35840
	ds_read_b128 v[188:191], v220 offset:36864
	ds_read_b128 v[194:197], v220 offset:37888
	ds_read_b128 v[200:203], v220 offset:38912
	ds_read_b128 v[222:225], v220 offset:39936
	global_load_lds_dwordx4 v[232:233], off
	v_lshl_add_u64 v[232:233], s[56:57], 0, v[172:173]
	s_mov_b32 m0, s69
	s_nop 0
	global_load_lds_dwordx4 v[232:233], off
	s_waitcnt vmcnt(8)
	s_waitcnt lgkmcnt(0)
	s_barrier
	s_waitcnt lgkmcnt(0)
	v_mfma_f32_16x16x32_bf16 v[124:127], v[128:131], v[160:163], v[124:127]
	v_mfma_f32_16x16x32_bf16 v[92:95], v[136:139], v[160:163], v[92:95]
	v_mfma_f32_16x16x32_bf16 v[116:119], v[128:131], v[180:183], v[116:119]
	v_mfma_f32_16x16x32_bf16 v[84:87], v[136:139], v[180:183], v[84:87]
	v_mfma_f32_16x16x32_bf16 v[108:111], v[128:131], v[188:191], v[108:111]
	v_mfma_f32_16x16x32_bf16 v[76:79], v[136:139], v[188:191], v[76:79]
	v_mfma_f32_16x16x32_bf16 v[100:103], v[128:131], v[200:203], v[100:103]
	v_mfma_f32_16x16x32_bf16 v[68:71], v[136:139], v[200:203], v[68:71]
	v_mfma_f32_16x16x32_bf16 v[124:127], v[132:135], v[164:167], v[124:127]
	v_mfma_f32_16x16x32_bf16 v[92:95], v[140:143], v[164:167], v[92:95]
	v_mfma_f32_16x16x32_bf16 v[116:119], v[132:135], v[184:187], v[116:119]
	v_mfma_f32_16x16x32_bf16 v[84:87], v[140:143], v[184:187], v[84:87]
	v_mfma_f32_16x16x32_bf16 v[108:111], v[132:135], v[194:197], v[108:111]
	v_mfma_f32_16x16x32_bf16 v[76:79], v[140:143], v[194:197], v[76:79]
	v_mfma_f32_16x16x32_bf16 v[100:103], v[132:135], v[222:225], v[100:103]
	v_mfma_f32_16x16x32_bf16 v[68:71], v[140:143], v[222:225], v[68:71]
	v_mfma_f32_16x16x32_bf16 v[120:123], v[144:147], v[160:163], v[120:123]
	v_mfma_f32_16x16x32_bf16 v[88:91], v[152:155], v[160:163], v[88:91]
	v_mfma_f32_16x16x32_bf16 v[112:115], v[144:147], v[180:183], v[112:115]
	v_mfma_f32_16x16x32_bf16 v[80:83], v[152:155], v[180:183], v[80:83]
	v_mfma_f32_16x16x32_bf16 v[104:107], v[144:147], v[188:191], v[104:107]
	v_mfma_f32_16x16x32_bf16 v[72:75], v[152:155], v[188:191], v[72:75]
	v_mfma_f32_16x16x32_bf16 v[96:99], v[144:147], v[200:203], v[96:99]
	v_mfma_f32_16x16x32_bf16 v[64:67], v[152:155], v[200:203], v[64:67]
	v_mfma_f32_16x16x32_bf16 v[120:123], v[148:151], v[164:167], v[120:123]
	v_mfma_f32_16x16x32_bf16 v[88:91], v[156:159], v[164:167], v[88:91]
	v_mfma_f32_16x16x32_bf16 v[112:115], v[148:151], v[184:187], v[112:115]
	v_mfma_f32_16x16x32_bf16 v[80:83], v[156:159], v[184:187], v[80:83]
	v_mfma_f32_16x16x32_bf16 v[104:107], v[148:151], v[194:197], v[104:107]
	v_mfma_f32_16x16x32_bf16 v[72:75], v[156:159], v[194:197], v[72:75]
	v_mfma_f32_16x16x32_bf16 v[96:99], v[148:151], v[222:225], v[96:99]
	v_mfma_f32_16x16x32_bf16 v[64:67], v[156:159], v[222:225], v[64:67]
	s_barrier
; #define PG8_STAGE(bufoff, gbase, voff) do { _Pragma("unroll") for (int _i = 0; _i < 2; ++_i) \
;         __builtin_amdgcn_global_load_lds((const unsigned*)((const char*)(gbase) + (voff)[_i]), (LAS unsigned*)(lds + (bufoff) + ldsw + _i * 8192), 16, 0, 0); } while (0)
; #define PG8_LDA(dst, b, h) do { _Pragma("unroll") for (int m = 0; m < 4; ++m) _Pragma("unroll") for (int k = 0; k < 2; ++k) dst[m][k] = *(const LAS bf16x8*)(lds + PG8_SA(b, h) + aoff + m * 2048 + k * 1024); } while (0)
; #define PG8_MMA(ai, bj, At, Bt) do { __builtin_amdgcn_s_setprio(1); _Pragma("unroll") for (int m = 0; m < 4; ++m) _Pragma("unroll") for (int n = 0; n < 2; ++n) _Pragma("unroll") for (int k = 0; k < 2; ++k) \
;         acc[ai][bj][m][n] = __builtin_amdgcn_mfma_f32_16x16x32_bf16(Bt[n][k], At[m][k], acc[ai][bj][m][n], 0, 0, 0); __builtin_amdgcn_s_setprio(0); } while (0)
; #define PG8_WAIT_V(n) asm volatile("s_waitcnt vmcnt(" #n ")" ::: "memory")
; #define PG8_WAIT_L(n) asm volatile("s_waitcnt lgkmcnt(" #n ")" ::: "memory")
; #define PG8_BAR __builtin_amdgcn_s_barrier()
; #define PG8_SCHED __builtin_amdgcn_sched_barrier(0)
; template <class Epi>
; DI void gemm_phase(int wv, LAS unsigned char* lds, LAS unsigned char* scr, const Sched& S, const Epi& E) {
;     ...
;             PG8_LDA(At, 1, 1); PG8_STAGE(PG8_SB(1, 0), b3, voffB); PG8_STAGE(PG8_SB(1, 1), b3 + hstepB, voffB); PG8_STAGE(PG8_SA(1, 0), a3, voffA);
;             PG8_WAIT_V(8); PG8_WAIT_L(0); PG8_BAR; PG8_MMA(1, 0, At, B0); PG8_MMA(1, 1, At, B1); PG8_BAR; PG8_SCHED;
;         }
;         if (wr == 0) PG8_BAR;
	s_add_i32 s56, s61, s65
	v_lshl_add_u64 v[204:205], v[204:205], 0, s[2:3]
	s_mov_b32 m0, s56
	ds_read_b128 v[160:163], v220 offset:49152
	ds_read_b128 v[164:167], v220 offset:50176
	ds_read_b128 v[180:183], v220 offset:51200
	ds_read_b128 v[184:187], v220 offset:52224
	ds_read_b128 v[188:191], v220 offset:53248
	ds_read_b128 v[194:197], v220 offset:54272
	ds_read_b128 v[200:203], v220 offset:55296
	ds_read_b128 v[222:225], v220 offset:56320
	global_load_lds_dwordx4 v[204:205], off
	s_add_i32 m0, s56, 0x2000
	s_add_u32 s54, s54, 0x40080
	v_lshl_add_u64 v[204:205], v[226:227], 0, s[2:3]
	s_addc_u32 s55, s55, 0
	s_add_i32 s56, s74, s65
	global_load_lds_dwordx4 v[204:205], off
	v_lshl_add_u64 v[204:205], s[54:55], 0, v[170:171]
	s_mov_b32 m0, s56
	s_nop 0
	global_load_lds_dwordx4 v[204:205], off
	v_lshl_add_u64 v[204:205], s[54:55], 0, v[174:175]
	s_add_i32 m0, s56, 0x2000
	s_nop 0
	global_load_lds_dwordx4 v[204:205], off
	v_lshl_add_u64 v[204:205], v[228:229], 0, s[2:3]
	s_mov_b32 m0, s70
	s_nop 0
	global_load_lds_dwordx4 v[204:205], off
	v_lshl_add_u64 v[204:205], v[230:231], 0, s[2:3]
	s_mov_b32 m0, s71
	s_nop 0
	global_load_lds_dwordx4 v[204:205], off
	s_waitcnt vmcnt(8)
	s_waitcnt lgkmcnt(0)
	s_barrier
	s_waitcnt lgkmcnt(0)
	v_mfma_f32_16x16x32_bf16 v[60:63], v[128:131], v[160:163], v[60:63]
	v_mfma_f32_16x16x32_bf16 v[28:31], v[136:139], v[160:163], v[28:31]
	v_mfma_f32_16x16x32_bf16 v[52:55], v[128:131], v[180:183], v[52:55]
	v_mfma_f32_16x16x32_bf16 v[20:23], v[136:139], v[180:183], v[20:23]
	v_mfma_f32_16x16x32_bf16 v[44:47], v[128:131], v[188:191], v[44:47]
	v_mfma_f32_16x16x32_bf16 v[12:15], v[136:139], v[188:191], v[12:15]
	v_mfma_f32_16x16x32_bf16 v[36:39], v[128:131], v[200:203], v[36:39]
	v_mfma_f32_16x16x32_bf16 v[4:7], v[136:139], v[200:203], v[4:7]
	v_mfma_f32_16x16x32_bf16 v[60:63], v[132:135], v[164:167], v[60:63]
	v_mfma_f32_16x16x32_bf16 v[28:31], v[140:143], v[164:167], v[28:31]
	v_mfma_f32_16x16x32_bf16 v[52:55], v[132:135], v[184:187], v[52:55]
	v_mfma_f32_16x16x32_bf16 v[20:23], v[140:143], v[184:187], v[20:23]
	v_mfma_f32_16x16x32_bf16 v[44:47], v[132:135], v[194:197], v[44:47]
	v_mfma_f32_16x16x32_bf16 v[12:15], v[140:143], v[194:197], v[12:15]
	v_mfma_f32_16x16x32_bf16 v[36:39], v[132:135], v[222:225], v[36:39]
	v_mfma_f32_16x16x32_bf16 v[4:7], v[140:143], v[222:225], v[4:7]
	v_mfma_f32_16x16x32_bf16 v[56:59], v[144:147], v[160:163], v[56:59]
	v_mfma_f32_16x16x32_bf16 v[24:27], v[152:155], v[160:163], v[24:27]
	v_mfma_f32_16x16x32_bf16 v[48:51], v[144:147], v[180:183], v[48:51]
	v_mfma_f32_16x16x32_bf16 v[16:19], v[152:155], v[180:183], v[16:19]
	v_mfma_f32_16x16x32_bf16 v[40:43], v[144:147], v[188:191], v[40:43]
	v_mfma_f32_16x16x32_bf16 v[8:11], v[152:155], v[188:191], v[8:11]
	v_mfma_f32_16x16x32_bf16 v[32:35], v[144:147], v[200:203], v[32:35]
	v_mfma_f32_16x16x32_bf16 v[0:3], v[152:155], v[200:203], v[0:3]
	v_mfma_f32_16x16x32_bf16 v[56:59], v[148:151], v[164:167], v[56:59]
	v_mfma_f32_16x16x32_bf16 v[24:27], v[156:159], v[164:167], v[24:27]
	v_mfma_f32_16x16x32_bf16 v[48:51], v[148:151], v[184:187], v[48:51]
	v_mfma_f32_16x16x32_bf16 v[16:19], v[156:159], v[184:187], v[16:19]
	v_mfma_f32_16x16x32_bf16 v[40:43], v[148:151], v[194:197], v[40:43]
	v_mfma_f32_16x16x32_bf16 v[8:11], v[156:159], v[194:197], v[8:11]
	v_mfma_f32_16x16x32_bf16 v[32:35], v[148:151], v[222:225], v[32:35]
	v_mfma_f32_16x16x32_bf16 v[0:3], v[156:159], v[222:225], v[0:3]
	s_barrier
	s_add_i32 s60, s60, 2
	s_add_u32 s58, s58, 0x100
	s_addc_u32 s59, s59, 0
	s_add_u32 s28, s28, 0x100
	s_addc_u32 s29, s29, 0
	s_cmp_gt_u32 s60, 13
	s_cbranch_scc0 .LBB0_811
	s_and_b64 vcc, exec, s[42:43]
	s_cbranch_vccz .LBB0_814
	s_barrier

; #define PG8_STAGE(bufoff, gbase, voff) do { _Pragma("unroll") for (int _i = 0; _i < 2; ++_i) \
;         __builtin_amdgcn_global_load_lds((const unsigned*)((const char*)(gbase) + (voff)[_i]), (LAS unsigned*)(lds + (bufoff) + ldsw + _i * 8192), 16, 0, 0); } while (0)
; #define PG8_LDA(dst, b, h) do { _Pragma("unroll") for (int m = 0; m < 4; ++m) _Pragma("unroll") for (int k = 0; k < 2; ++k) dst[m][k] = *(const LAS bf16x8*)(lds + PG8_SA(b, h) + aoff + m * 2048 + k * 1024); } while (0)
; #define PG8_LDB(dst, b, h) do { _Pragma("unroll") for (int n = 0; n < 2; ++n) _Pragma("unroll") for (int k = 0; k < 2; ++k) dst[n][k] = *(const LAS bf16x8*)(lds + PG8_SB(b, h) + boff + n * 2048 + k * 1024); } while (0)
; #define PG8_MMA(ai, bj, At, Bt) do { __builtin_amdgcn_s_setprio(1); _Pragma("unroll") for (int m = 0; m < 4; ++m) _Pragma("unroll") for (int n = 0; n < 2; ++n) _Pragma("unroll") for (int k = 0; k < 2; ++k) \
;         acc[ai][bj][m][n] = __builtin_amdgcn_mfma_f32_16x16x32_bf16(Bt[n][k], At[m][k], acc[ai][bj][m][n], 0, 0, 0); __builtin_amdgcn_s_setprio(0); } while (0)
; #define PG8_WAIT_V(n) asm volatile("s_waitcnt vmcnt(" #n ")" ::: "memory")
; #define PG8_WAIT_L(n) asm volatile("s_waitcnt lgkmcnt(" #n ")" ::: "memory")
; #define PG8_BAR __builtin_amdgcn_s_barrier()
; #define PG8_SCHED __builtin_amdgcn_sched_barrier(0)
; template <class Epi>
; DI void gemm_phase(int wv, LAS unsigned char* lds, LAS unsigned char* scr, const Sched& S, const Epi& E) {
;     ...
;             const bool last = (t == nt - 2);
;             const char* a1 = cA + (size_t)(t + 1) * kstep;
;             const char* a2 = last ? nA : cA + (size_t)(t + 2) * kstep; const char* b2 = last ? nB : cB + (size_t)(t + 2) * kstep;
;             const char* a3 = a2 + kstep; const char* b3 = b2 + kstep;
;             PG8_LDB(B0, 0, 0); PG8_LDB(B1, 0, 1); PG8_SCHED; PG8_LDA(At, 0, 0); PG8_STAGE(PG8_SA(1, 1), a1 + hstepA, voffA);
;             PG8_WAIT_V(8); PG8_WAIT_L(0); PG8_BAR; PG8_MMA(0, 0, At, B0); PG8_MMA(0, 1, At, B1); PG8_BAR; PG8_SCHED;
;             PG8_LDA(At, 0, 1); PG8_STAGE(PG8_SB(0, 0), b2, voffB); PG8_STAGE(PG8_SB(0, 1), b2 + hstepB, voffB); PG8_STAGE(PG8_SA(0, 0), a2, voffA);
.LBB0_936:
	s_add_u32 s30, s28, 0x100
	s_addc_u32 s31, s29, 0
	s_add_i32 s69, 0, 0x10000
	s_cmp_eq_u32 s68, 40
	s_cselect_b32 s37, s9, s31
	s_cselect_b32 s36, s8, s30
	s_cselect_b32 s35, s23, s27
	s_cselect_b32 s34, s22, s25
	s_add_i32 s70, 0, 0x14000
	v_add_u32_e32 v156, s69, v142
	v_add_u32_e32 v172, s70, v142
	ds_read_b128 v[144:147], v156
	ds_read_b128 v[148:151], v156 offset:1024
	ds_read_b128 v[152:155], v156 offset:2048
	ds_read_b128 v[156:159], v156 offset:3072
	ds_read_b128 v[160:163], v172
	ds_read_b128 v[164:167], v172 offset:1024
	ds_read_b128 v[168:171], v172 offset:2048
	ds_read_b128 v[172:175], v172 offset:3072
	v_lshl_add_u64 v[210:211], s[28:29], 0, v[140:141]
	s_add_i32 m0, s57, 0xc000
	ds_read_b128 v[176:179], v143
	ds_read_b128 v[180:183], v143 offset:1024
	ds_read_b128 v[184:187], v143 offset:2048
	ds_read_b128 v[188:191], v143 offset:3072
	ds_read_b128 v[194:197], v143 offset:4096
	ds_read_b128 v[198:201], v143 offset:5120
	ds_read_b128 v[202:205], v143 offset:6144
	ds_read_b128 v[206:209], v143 offset:7168
	global_load_lds_dwordx4 v[210:211], off
	v_lshl_add_u64 v[210:211], s[28:29], 0, v[138:139]
	s_add_i32 m0, s57, 0xe000
	s_nop 0
	global_load_lds_dwordx4 v[210:211], off
	s_waitcnt vmcnt(8)
	s_waitcnt lgkmcnt(0)
	s_barrier
	s_waitcnt lgkmcnt(0)
	v_mfma_f32_16x16x32_bf16 v[124:127], v[144:147], v[176:179], v[124:127]
	v_mfma_f32_16x16x32_bf16 v[120:123], v[152:155], v[176:179], v[120:123]
	v_mfma_f32_16x16x32_bf16 v[116:119], v[144:147], v[184:187], v[116:119]
	v_mfma_f32_16x16x32_bf16 v[112:115], v[152:155], v[184:187], v[112:115]
	v_mfma_f32_16x16x32_bf16 v[100:103], v[144:147], v[194:197], v[100:103]
	v_mfma_f32_16x16x32_bf16 v[96:99], v[152:155], v[194:197], v[96:99]
	v_mfma_f32_16x16x32_bf16 v[84:87], v[144:147], v[202:205], v[84:87]
	v_mfma_f32_16x16x32_bf16 v[80:83], v[152:155], v[202:205], v[80:83]
	v_mfma_f32_16x16x32_bf16 v[124:127], v[148:151], v[180:183], v[124:127]
	v_mfma_f32_16x16x32_bf16 v[120:123], v[156:159], v[180:183], v[120:123]
	v_mfma_f32_16x16x32_bf16 v[116:119], v[148:151], v[188:191], v[116:119]
	v_mfma_f32_16x16x32_bf16 v[112:115], v[156:159], v[188:191], v[112:115]
	v_mfma_f32_16x16x32_bf16 v[100:103], v[148:151], v[198:201], v[100:103]
	v_mfma_f32_16x16x32_bf16 v[96:99], v[156:159], v[198:201], v[96:99]
	v_mfma_f32_16x16x32_bf16 v[84:87], v[148:151], v[206:209], v[84:87]
	v_mfma_f32_16x16x32_bf16 v[80:83], v[156:159], v[206:209], v[80:83]
	v_mfma_f32_16x16x32_bf16 v[108:111], v[160:163], v[176:179], v[108:111]
	v_mfma_f32_16x16x32_bf16 v[104:107], v[168:171], v[176:179], v[104:107]
	v_mfma_f32_16x16x32_bf16 v[92:95], v[160:163], v[184:187], v[92:95]
	v_mfma_f32_16x16x32_bf16 v[88:91], v[168:171], v[184:187], v[88:91]
	v_mfma_f32_16x16x32_bf16 v[76:79], v[160:163], v[194:197], v[76:79]
	v_mfma_f32_16x16x32_bf16 v[72:75], v[168:171], v[194:197], v[72:75]
	v_mfma_f32_16x16x32_bf16 v[68:71], v[160:163], v[202:205], v[68:71]
	v_mfma_f32_16x16x32_bf16 v[64:67], v[168:171], v[202:205], v[64:67]
	v_mfma_f32_16x16x32_bf16 v[108:111], v[164:167], v[180:183], v[108:111]
	v_mfma_f32_16x16x32_bf16 v[104:107], v[172:175], v[180:183], v[104:107]
	v_mfma_f32_16x16x32_bf16 v[92:95], v[164:167], v[188:191], v[92:95]
	v_mfma_f32_16x16x32_bf16 v[88:91], v[172:175], v[188:191], v[88:91]
	v_mfma_f32_16x16x32_bf16 v[76:79], v[164:167], v[198:201], v[76:79]
	v_mfma_f32_16x16x32_bf16 v[72:75], v[172:175], v[198:201], v[72:75]
	v_mfma_f32_16x16x32_bf16 v[68:71], v[164:167], v[206:209], v[68:71]
	v_mfma_f32_16x16x32_bf16 v[64:67], v[172:175], v[206:209], v[64:67]
	s_barrier
	s_add_i32 s28, s69, s56
	v_lshl_add_u64 v[210:211], s[34:35], 0, v[132:133]
	s_mov_b32 m0, s28
	ds_read_b128 v[176:179], v143 offset:16384
	ds_read_b128 v[180:183], v143 offset:17408
	ds_read_b128 v[184:187], v143 offset:18432
	ds_read_b128 v[188:191], v143 offset:19456
	ds_read_b128 v[194:197], v143 offset:20480
	ds_read_b128 v[198:201], v143 offset:21504
	ds_read_b128 v[202:205], v143 offset:22528
	ds_read_b128 v[206:209], v143 offset:23552
	global_load_lds_dwordx4 v[210:211], off
	s_add_i32 m0, s28, 0x2000
	s_add_u32 s28, s34, 0xb0000
	v_lshl_add_u64 v[212:213], s[34:35], 0, v[128:129]
	s_addc_u32 s29, s35, 0
	s_add_i32 s69, s70, s56
	global_load_lds_dwordx4 v[212:213], off
	v_lshl_add_u64 v[214:215], s[28:29], 0, v[132:133]
	s_mov_b32 m0, s69
	v_lshl_add_u64 v[216:217], s[36:37], 0, v[130:131]
	global_load_lds_dwordx4 v[214:215], off
	v_lshl_add_u64 v[214:215], s[28:29], 0, v[128:129]
	s_add_i32 m0, s69, 0x2000
	s_nop 0
	global_load_lds_dwordx4 v[214:215], off
	v_lshl_add_u64 v[214:215], s[36:37], 0, v[134:135]
	s_mov_b32 m0, s57
	s_nop 0
	global_load_lds_dwordx4 v[214:215], off
	s_mov_b32 m0, s58
	s_nop 0
	global_load_lds_dwordx4 v[216:217], off
	s_waitcnt vmcnt(8)
	s_waitcnt lgkmcnt(0)
	s_barrier
; #define PG8_STAGE(bufoff, gbase, voff) do { _Pragma("unroll") for (int _i = 0; _i < 2; ++_i) \
;         __builtin_amdgcn_global_load_lds((const unsigned*)((const char*)(gbase) + (voff)[_i]), (LAS unsigned*)(lds + (bufoff) + ldsw + _i * 8192), 16, 0, 0); } while (0)
; #define PG8_LDA(dst, b, h) do { _Pragma("unroll") for (int m = 0; m < 4; ++m) _Pragma("unroll") for (int k = 0; k < 2; ++k) dst[m][k] = *(const LAS bf16x8*)(lds + PG8_SA(b, h) + aoff + m * 2048 + k * 1024); } while (0)
; #define PG8_LDB(dst, b, h) do { _Pragma("unroll") for (int n = 0; n < 2; ++n) _Pragma("unroll") for (int k = 0; k < 2; ++k) dst[n][k] = *(const LAS bf16x8*)(lds + PG8_SB(b, h) + boff + n * 2048 + k * 1024); } while (0)
; #define PG8_MMA(ai, bj, At, Bt) do { __builtin_amdgcn_s_setprio(1); _Pragma("unroll") for (int m = 0; m < 4; ++m) _Pragma("unroll") for (int n = 0; n < 2; ++n) _Pragma("unroll") for (int k = 0; k < 2; ++k) \
;         acc[ai][bj][m][n] = __builtin_amdgcn_mfma_f32_16x16x32_bf16(Bt[n][k], At[m][k], acc[ai][bj][m][n], 0, 0, 0); __builtin_amdgcn_s_setprio(0); } while (0)
; #define PG8_WAIT_V(n) asm volatile("s_waitcnt vmcnt(" #n ")" ::: "memory")
; #define PG8_WAIT_L(n) asm volatile("s_waitcnt lgkmcnt(" #n ")" ::: "memory")
; #define PG8_BAR __builtin_amdgcn_s_barrier()
; #define PG8_SCHED __builtin_amdgcn_sched_barrier(0)
; template <class Epi>
; DI void gemm_phase(int wv, LAS unsigned char* lds, LAS unsigned char* scr, const Sched& S, const Epi& E) {
;     ...
;             PG8_WAIT_V(8); PG8_WAIT_L(0); PG8_BAR; PG8_MMA(1, 0, At, B0); PG8_MMA(1, 1, At, B1); PG8_BAR; PG8_SCHED;
;             PG8_LDB(B0, 1, 0); PG8_LDB(B1, 1, 1); PG8_SCHED; PG8_LDA(At, 1, 0); PG8_STAGE(PG8_SA(0, 1), a2 + hstepA, voffA);
;             PG8_WAIT_V(8); PG8_WAIT_L(0); PG8_BAR; PG8_MMA(0, 0, At, B0); PG8_MMA(0, 1, At, B1); PG8_BAR; PG8_SCHED;
	s_waitcnt lgkmcnt(0)
	v_mfma_f32_16x16x32_bf16 v[60:63], v[144:147], v[176:179], v[60:63]
	v_mfma_f32_16x16x32_bf16 v[56:59], v[152:155], v[176:179], v[56:59]
	v_mfma_f32_16x16x32_bf16 v[52:55], v[144:147], v[184:187], v[52:55]
	v_mfma_f32_16x16x32_bf16 v[48:51], v[152:155], v[184:187], v[48:51]
	v_mfma_f32_16x16x32_bf16 v[36:39], v[144:147], v[194:197], v[36:39]
	v_mfma_f32_16x16x32_bf16 v[32:35], v[152:155], v[194:197], v[32:35]
	v_mfma_f32_16x16x32_bf16 v[20:23], v[144:147], v[202:205], v[20:23]
	v_mfma_f32_16x16x32_bf16 v[16:19], v[152:155], v[202:205], v[16:19]
	v_mfma_f32_16x16x32_bf16 v[60:63], v[148:151], v[180:183], v[60:63]
	v_mfma_f32_16x16x32_bf16 v[56:59], v[156:159], v[180:183], v[56:59]
	v_mfma_f32_16x16x32_bf16 v[52:55], v[148:151], v[188:191], v[52:55]
	v_mfma_f32_16x16x32_bf16 v[48:51], v[156:159], v[188:191], v[48:51]
	v_mfma_f32_16x16x32_bf16 v[36:39], v[148:151], v[198:201], v[36:39]
	v_mfma_f32_16x16x32_bf16 v[32:35], v[156:159], v[198:201], v[32:35]
	v_mfma_f32_16x16x32_bf16 v[20:23], v[148:151], v[206:209], v[20:23]
	v_mfma_f32_16x16x32_bf16 v[16:19], v[156:159], v[206:209], v[16:19]
	v_mfma_f32_16x16x32_bf16 v[44:47], v[160:163], v[176:179], v[44:47]
	v_mfma_f32_16x16x32_bf16 v[40:43], v[168:171], v[176:179], v[40:43]
	v_mfma_f32_16x16x32_bf16 v[28:31], v[160:163], v[184:187], v[28:31]
	v_mfma_f32_16x16x32_bf16 v[24:27], v[168:171], v[184:187], v[24:27]
	v_mfma_f32_16x16x32_bf16 v[12:15], v[160:163], v[194:197], v[12:15]
	v_mfma_f32_16x16x32_bf16 v[8:11], v[168:171], v[194:197], v[8:11]
	v_mfma_f32_16x16x32_bf16 v[4:7], v[160:163], v[202:205], v[4:7]
	v_mfma_f32_16x16x32_bf16 v[0:3], v[168:171], v[202:205], v[0:3]
	v_mfma_f32_16x16x32_bf16 v[44:47], v[164:167], v[180:183], v[44:47]
	v_mfma_f32_16x16x32_bf16 v[40:43], v[172:175], v[180:183], v[40:43]
	v_mfma_f32_16x16x32_bf16 v[28:31], v[164:167], v[188:191], v[28:31]
	v_mfma_f32_16x16x32_bf16 v[24:27], v[172:175], v[188:191], v[24:27]
	v_mfma_f32_16x16x32_bf16 v[12:15], v[164:167], v[198:201], v[12:15]
	v_mfma_f32_16x16x32_bf16 v[8:11], v[172:175], v[198:201], v[8:11]
	v_mfma_f32_16x16x32_bf16 v[4:7], v[164:167], v[206:209], v[4:7]
	v_mfma_f32_16x16x32_bf16 v[0:3], v[172:175], v[206:209], v[0:3]
	s_barrier
	s_add_i32 s69, 0, 0x18000
	s_add_i32 s70, 0, 0x1c000
	v_add_u32_e32 v156, s69, v142
	v_add_u32_e32 v172, s70, v142
	ds_read_b128 v[144:147], v156
	ds_read_b128 v[148:151], v156 offset:1024
	ds_read_b128 v[152:155], v156 offset:2048
	ds_read_b128 v[156:159], v156 offset:3072
	ds_read_b128 v[160:163], v172
	ds_read_b128 v[164:167], v172 offset:1024
	ds_read_b128 v[168:171], v172 offset:2048
	ds_read_b128 v[172:175], v172 offset:3072
	s_add_u32 s28, s36, 0xb0000
	s_addc_u32 s29, s37, 0
	s_mov_b32 m0, s59
	v_lshl_add_u64 v[218:219], s[28:29], 0, v[134:135]
	ds_read_b128 v[176:179], v143 offset:32768
	ds_read_b128 v[180:183], v143 offset:33792
	ds_read_b128 v[184:187], v143 offset:34816
	ds_read_b128 v[188:191], v143 offset:35840
	ds_read_b128 v[194:197], v143 offset:36864
	ds_read_b128 v[198:201], v143 offset:37888
	ds_read_b128 v[202:205], v143 offset:38912
	ds_read_b128 v[206:209], v143 offset:39936
	global_load_lds_dwordx4 v[218:219], off
	v_lshl_add_u64 v[218:219], s[28:29], 0, v[130:131]
	s_mov_b32 m0, s60
	s_nop 0
	global_load_lds_dwordx4 v[218:219], off
	s_waitcnt vmcnt(8)
	s_waitcnt lgkmcnt(0)
	s_barrier
	s_waitcnt lgkmcnt(0)
	v_mfma_f32_16x16x32_bf16 v[124:127], v[144:147], v[176:179], v[124:127]
	v_mfma_f32_16x16x32_bf16 v[120:123], v[152:155], v[176:179], v[120:123]
	v_mfma_f32_16x16x32_bf16 v[116:119], v[144:147], v[184:187], v[116:119]
	v_mfma_f32_16x16x32_bf16 v[112:115], v[152:155], v[184:187], v[112:115]
	v_mfma_f32_16x16x32_bf16 v[100:103], v[144:147], v[194:197], v[100:103]
	v_mfma_f32_16x16x32_bf16 v[96:99], v[152:155], v[194:197], v[96:99]
	v_mfma_f32_16x16x32_bf16 v[84:87], v[144:147], v[202:205], v[84:87]
	v_mfma_f32_16x16x32_bf16 v[80:83], v[152:155], v[202:205], v[80:83]
	v_mfma_f32_16x16x32_bf16 v[124:127], v[148:151], v[180:183], v[124:127]
	v_mfma_f32_16x16x32_bf16 v[120:123], v[156:159], v[180:183], v[120:123]
	v_mfma_f32_16x16x32_bf16 v[116:119], v[148:151], v[188:191], v[116:119]
	v_mfma_f32_16x16x32_bf16 v[112:115], v[156:159], v[188:191], v[112:115]
	v_mfma_f32_16x16x32_bf16 v[100:103], v[148:151], v[198:201], v[100:103]
	v_mfma_f32_16x16x32_bf16 v[96:99], v[156:159], v[198:201], v[96:99]
	v_mfma_f32_16x16x32_bf16 v[84:87], v[148:151], v[206:209], v[84:87]
	v_mfma_f32_16x16x32_bf16 v[80:83], v[156:159], v[206:209], v[80:83]
	v_mfma_f32_16x16x32_bf16 v[108:111], v[160:163], v[176:179], v[108:111]
	v_mfma_f32_16x16x32_bf16 v[104:107], v[168:171], v[176:179], v[104:107]
	v_mfma_f32_16x16x32_bf16 v[92:95], v[160:163], v[184:187], v[92:95]
	v_mfma_f32_16x16x32_bf16 v[88:91], v[168:171], v[184:187], v[88:91]
	v_mfma_f32_16x16x32_bf16 v[76:79], v[160:163], v[194:197], v[76:79]
	v_mfma_f32_16x16x32_bf16 v[72:75], v[168:171], v[194:197], v[72:75]
	v_mfma_f32_16x16x32_bf16 v[68:71], v[160:163], v[202:205], v[68:71]
	v_mfma_f32_16x16x32_bf16 v[64:67], v[168:171], v[202:205], v[64:67]
	v_mfma_f32_16x16x32_bf16 v[108:111], v[164:167], v[180:183], v[108:111]
	v_mfma_f32_16x16x32_bf16 v[104:107], v[172:175], v[180:183], v[104:107]
	v_mfma_f32_16x16x32_bf16 v[92:95], v[164:167], v[188:191], v[92:95]
	v_mfma_f32_16x16x32_bf16 v[88:91], v[172:175], v[188:191], v[88:91]
	v_mfma_f32_16x16x32_bf16 v[76:79], v[164:167], v[198:201], v[76:79]
	v_mfma_f32_16x16x32_bf16 v[72:75], v[172:175], v[198:201], v[72:75]
	v_mfma_f32_16x16x32_bf16 v[68:71], v[164:167], v[206:209], v[68:71]
	v_mfma_f32_16x16x32_bf16 v[64:67], v[172:175], v[206:209], v[64:67]
	s_barrier
; #define PG8_STAGE(bufoff, gbase, voff) do { _Pragma("unroll") for (int _i = 0; _i < 2; ++_i) \
;         __builtin_amdgcn_global_load_lds((const unsigned*)((const char*)(gbase) + (voff)[_i]), (LAS unsigned*)(lds + (bufoff) + ldsw + _i * 8192), 16, 0, 0); } while (0)
; #define PG8_LDA(dst, b, h) do { _Pragma("unroll") for (int m = 0; m < 4; ++m) _Pragma("unroll") for (int k = 0; k < 2; ++k) dst[m][k] = *(const LAS bf16x8*)(lds + PG8_SA(b, h) + aoff + m * 2048 + k * 1024); } while (0)
; #define PG8_MMA(ai, bj, At, Bt) do { __builtin_amdgcn_s_setprio(1); _Pragma("unroll") for (int m = 0; m < 4; ++m) _Pragma("unroll") for (int n = 0; n < 2; ++n) _Pragma("unroll") for (int k = 0; k < 2; ++k) \
;         acc[ai][bj][m][n] = __builtin_amdgcn_mfma_f32_16x16x32_bf16(Bt[n][k], At[m][k], acc[ai][bj][m][n], 0, 0, 0); __builtin_amdgcn_s_setprio(0); } while (0)
; #define PG8_WAIT_V(n) asm volatile("s_waitcnt vmcnt(" #n ")" ::: "memory")
; #define PG8_WAIT_L(n) asm volatile("s_waitcnt lgkmcnt(" #n ")" ::: "memory")
; #define PG8_BAR __builtin_amdgcn_s_barrier()
; #define PG8_SCHED __builtin_amdgcn_sched_barrier(0)
; template <class Epi>
; DI void gemm_phase(int wv, LAS unsigned char* lds, LAS unsigned char* scr, const Sched& S, const Epi& E) {
;     ...
;             PG8_LDA(At, 1, 1); PG8_STAGE(PG8_SB(1, 0), b3, voffB); PG8_STAGE(PG8_SB(1, 1), b3 + hstepB, voffB); PG8_STAGE(PG8_SA(1, 0), a3, voffA);
;             PG8_WAIT_V(8); PG8_WAIT_L(0); PG8_BAR; PG8_MMA(1, 0, At, B0); PG8_MMA(1, 1, At, B1); PG8_BAR; PG8_SCHED;
;         }
;         if (wr == 0) PG8_BAR;
	s_add_i32 s28, s69, s56
	v_lshl_add_u64 v[210:211], v[210:211], 0, s[2:3]
	s_mov_b32 m0, s28
	ds_read_b128 v[176:179], v143 offset:49152
	ds_read_b128 v[180:183], v143 offset:50176
	ds_read_b128 v[184:187], v143 offset:51200
	ds_read_b128 v[188:191], v143 offset:52224
	ds_read_b128 v[194:197], v143 offset:53248
	ds_read_b128 v[198:201], v143 offset:54272
	ds_read_b128 v[202:205], v143 offset:55296
	ds_read_b128 v[206:209], v143 offset:56320
	global_load_lds_dwordx4 v[210:211], off
	s_add_i32 m0, s28, 0x2000
	s_add_u32 s28, s34, 0xb0080
	v_lshl_add_u64 v[210:211], v[212:213], 0, s[2:3]
	s_addc_u32 s29, s35, 0
	s_add_i32 s34, s70, s56
	global_load_lds_dwordx4 v[210:211], off
	v_lshl_add_u64 v[210:211], s[28:29], 0, v[132:133]
	s_mov_b32 m0, s34
	s_nop 0
	global_load_lds_dwordx4 v[210:211], off
	v_lshl_add_u64 v[210:211], s[28:29], 0, v[128:129]
	s_add_i32 m0, s34, 0x2000
	s_nop 0
	global_load_lds_dwordx4 v[210:211], off
	v_lshl_add_u64 v[210:211], v[214:215], 0, s[2:3]
	s_mov_b32 m0, s63
	s_nop 0
	global_load_lds_dwordx4 v[210:211], off
	v_lshl_add_u64 v[210:211], v[216:217], 0, s[2:3]
	s_mov_b32 m0, s64
	s_nop 0
	global_load_lds_dwordx4 v[210:211], off
	s_waitcnt vmcnt(8)
	s_waitcnt lgkmcnt(0)
	s_barrier
	s_waitcnt lgkmcnt(0)
	v_mfma_f32_16x16x32_bf16 v[60:63], v[144:147], v[176:179], v[60:63]
	v_mfma_f32_16x16x32_bf16 v[56:59], v[152:155], v[176:179], v[56:59]
	v_mfma_f32_16x16x32_bf16 v[52:55], v[144:147], v[184:187], v[52:55]
	v_mfma_f32_16x16x32_bf16 v[48:51], v[152:155], v[184:187], v[48:51]
	v_mfma_f32_16x16x32_bf16 v[36:39], v[144:147], v[194:197], v[36:39]
	v_mfma_f32_16x16x32_bf16 v[32:35], v[152:155], v[194:197], v[32:35]
	v_mfma_f32_16x16x32_bf16 v[20:23], v[144:147], v[202:205], v[20:23]
	v_mfma_f32_16x16x32_bf16 v[16:19], v[152:155], v[202:205], v[16:19]
	v_mfma_f32_16x16x32_bf16 v[60:63], v[148:151], v[180:183], v[60:63]
	v_mfma_f32_16x16x32_bf16 v[56:59], v[156:159], v[180:183], v[56:59]
	v_mfma_f32_16x16x32_bf16 v[52:55], v[148:151], v[188:191], v[52:55]
	v_mfma_f32_16x16x32_bf16 v[48:51], v[156:159], v[188:191], v[48:51]
	v_mfma_f32_16x16x32_bf16 v[36:39], v[148:151], v[198:201], v[36:39]
	v_mfma_f32_16x16x32_bf16 v[32:35], v[156:159], v[198:201], v[32:35]
	v_mfma_f32_16x16x32_bf16 v[20:23], v[148:151], v[206:209], v[20:23]
	v_mfma_f32_16x16x32_bf16 v[16:19], v[156:159], v[206:209], v[16:19]
	v_mfma_f32_16x16x32_bf16 v[44:47], v[160:163], v[176:179], v[44:47]
	v_mfma_f32_16x16x32_bf16 v[40:43], v[168:171], v[176:179], v[40:43]
	v_mfma_f32_16x16x32_bf16 v[28:31], v[160:163], v[184:187], v[28:31]
	v_mfma_f32_16x16x32_bf16 v[24:27], v[168:171], v[184:187], v[24:27]
	v_mfma_f32_16x16x32_bf16 v[12:15], v[160:163], v[194:197], v[12:15]
	v_mfma_f32_16x16x32_bf16 v[8:11], v[168:171], v[194:197], v[8:11]
	v_mfma_f32_16x16x32_bf16 v[4:7], v[160:163], v[202:205], v[4:7]
	v_mfma_f32_16x16x32_bf16 v[0:3], v[168:171], v[202:205], v[0:3]
	v_mfma_f32_16x16x32_bf16 v[44:47], v[164:167], v[180:183], v[44:47]
	v_mfma_f32_16x16x32_bf16 v[40:43], v[172:175], v[180:183], v[40:43]
	v_mfma_f32_16x16x32_bf16 v[28:31], v[164:167], v[188:191], v[28:31]
	v_mfma_f32_16x16x32_bf16 v[24:27], v[172:175], v[188:191], v[24:27]
	v_mfma_f32_16x16x32_bf16 v[12:15], v[164:167], v[198:201], v[12:15]
	v_mfma_f32_16x16x32_bf16 v[8:11], v[172:175], v[198:201], v[8:11]
	v_mfma_f32_16x16x32_bf16 v[4:7], v[164:167], v[206:209], v[4:7]
	v_mfma_f32_16x16x32_bf16 v[0:3], v[172:175], v[206:209], v[0:3]
	s_barrier
	s_add_i32 s68, s68, 2
	s_add_u32 s25, s25, 0x100
	s_addc_u32 s27, s27, 0
	s_cmp_gt_u32 s68, 41
	s_mov_b64 s[28:29], s[30:31]
	s_cbranch_scc0 .LBB0_936
	s_and_b64 vcc, exec, s[20:21]
	s_cbranch_vccz .LBB0_939
	s_barrier
